# EpiH epilogue rewritten without hazard nops, fox scan loads batched, EpiRes residual loads hoisted, diff-attn K fragment reads unserialized, SP2 ds_read/DMA interleave
# speedup vs baseline: 1.0054x; 1.0054x over previous
; #define PG8_STAGE(bufoff, gbase, voff) do { _Pragma("unroll") for (int _i = 0; _i < 2; ++_i) \
;         __builtin_amdgcn_global_load_lds((const unsigned*)((const char*)(gbase) + (voff)[_i]), (PG8_LAS unsigned*)(lds + (bufoff) + ldsw + _i * 8192), 16, 0, 0); } while (0)
; #define PG8_LDA(dst, b, h) do { _Pragma("unroll") for (int m = 0; m < 4; ++m) _Pragma("unroll") for (int k = 0; k < 2; ++k) dst[m][k] = *(const PG8_LAS bf16x8*)(lds + PG8_SA(b, h) + aoff + m * 2048 + k * 1024); } while (0)
; #define PG8_LDB(dst, b, h) do { _Pragma("unroll") for (int n = 0; n < 2; ++n) _Pragma("unroll") for (int k = 0; k < 2; ++k) dst[n][k] = *(const PG8_LAS bf16x8*)(lds + PG8_SB(b, h) + boff + n * 2048 + k * 1024); } while (0)
; #define PG8_MMA(ai, bj, At, Bt) do { __builtin_amdgcn_s_setprio(1); _Pragma("unroll") for (int m = 0; m < 4; ++m) _Pragma("unroll") for (int n = 0; n < 2; ++n) _Pragma("unroll") for (int k = 0; k < 2; ++k) \
;         acc[ai][bj][m][n] = __builtin_amdgcn_mfma_f32_16x16x32_bf16(Bt[n][k], At[m][k], acc[ai][bj][m][n], 0, 0, 0); __builtin_amdgcn_s_setprio(0); } while (0)
; #define PG8_WAIT_V(n) asm volatile("s_waitcnt vmcnt(" #n ")" ::: "memory")
; #define PG8_BAR __builtin_amdgcn_s_barrier()
; template <class Epi, class Sched, bool ALIGN_EPI = false, bool SP2 = false>
; __device__ __forceinline__ void gemm_phase(PG8_LAS unsigned char* lds, const Gemm g, const Sched& S, const Epi& E) {
;     ...
;         for (int t = 0; t < nt; t += 2) {
;             const bool last = (t == nt - 2);
;             const char* a1 = cA + (size_t)(t + 1) * kstep;
;             const char* a2 = last ? nA : cA + (size_t)(t + 2) * kstep; const char* b2 = last ? nB : cB + (size_t)(t + 2) * kstep;
;             const char* a3 = a2 + kstep; const char* b3 = b2 + kstep;
;             if (last && has_next) S.a_ready(nxt);
;             if constexpr (SP2) {
;             PG8_LDB(B0, 0, 0); PG8_LDB(B1, 0, 1); PG8_SCHED; PG8_LDA(At, 0, 0); PG8_STAGE(PG8_SA(1, 1), a1 + hstep, voffA);
;             PG8_WAIT_V(8); PG8_WAIT_L(0); PG8_BAR; PG8_MMA(0, 0, At, B0); PG8_MMA(0, 1, At, B1); PG8_BAR; PG8_SCHED;
;             PG8_LDA(At, 0, 1); PG8_STAGE(PG8_SB(0, 0), b2, voffB); PG8_STAGE(PG8_SB(0, 1), b2 + hstep, voffB); PG8_STAGE(PG8_SA(0, 0), a2, voffA);
;             PG8_WAIT_V(8); PG8_WAIT_L(0); PG8_BAR; PG8_MMA(1, 0, At, B0); PG8_MMA(1, 1, At, B1); PG8_BAR; PG8_SCHED;
.LBB0_317:
	s_add_u32 s20, s8, 0xfffc0080
	s_addc_u32 s21, s9, -1
	s_add_i32 s37, 0, 0x10000
	s_cmp_eq_u32 s55, 12
	s_cselect_b32 s47, s41, s21
	s_cselect_b32 s46, s51, s20
	v_add_u32_e32 v144, s37, v149
	s_cselect_b32 s21, s27, s54
	s_cselect_b32 s20, s52, s53
	s_add_i32 s58, 0, 0x14000
	ds_read_b128 v[140:143], v144
	ds_read_b128 v[158:161], v144 offset:1024
	ds_read_b128 v[162:165], v144 offset:2048
	ds_read_b128 v[166:169], v144 offset:3072
	v_add_u32_e32 v144, s58, v149
	ds_read_b128 v[170:173], v144
	ds_read_b128 v[174:177], v144 offset:1024
	ds_read_b128 v[178:181], v144 offset:2048
	ds_read_b128 v[182:185], v144 offset:3072
	v_lshl_add_u64 v[146:147], s[8:9], 0, v[136:137]
	s_add_i32 m0, s18, 0xc000
	ds_read_b128 v[186:189], v157
	ds_read_b128 v[190:193], v157 offset:1024
	ds_read_b128 v[204:207], v157 offset:2048
	ds_read_b128 v[208:211], v157 offset:3072
	ds_read_b128 v[212:215], v157 offset:4096
	ds_read_b128 v[216:219], v157 offset:5120
	ds_read_b128 v[220:223], v157 offset:6144
	ds_read_b128 v[224:227], v157 offset:7168
	global_load_lds_dwordx4 v[146:147], off
	v_lshl_add_u64 v[146:147], s[8:9], 0, v[138:139]
	s_add_i32 m0, s18, 0xe000
	s_nop 0
	global_load_lds_dwordx4 v[146:147], off
	s_waitcnt vmcnt(8)
	s_waitcnt lgkmcnt(0)
	s_barrier
	s_setprio 1
	s_waitcnt lgkmcnt(0)
	v_mfma_f32_16x16x32_bf16 v[126:129], v[140:143], v[186:189], v[126:129]
	v_mfma_f32_16x16x32_bf16 v[122:125], v[162:165], v[186:189], v[122:125]
	v_mfma_f32_16x16x32_bf16 v[110:113], v[140:143], v[204:207], v[110:113]
	v_mfma_f32_16x16x32_bf16 v[106:109], v[162:165], v[204:207], v[106:109]
	v_mfma_f32_16x16x32_bf16 v[94:97], v[140:143], v[212:215], v[94:97]
	v_mfma_f32_16x16x32_bf16 v[90:93], v[162:165], v[212:215], v[90:93]
	v_mfma_f32_16x16x32_bf16 v[78:81], v[140:143], v[220:223], v[78:81]
	v_mfma_f32_16x16x32_bf16 v[74:77], v[162:165], v[220:223], v[74:77]
	v_mfma_f32_16x16x32_bf16 v[126:129], v[158:161], v[190:193], v[126:129]
	v_mfma_f32_16x16x32_bf16 v[122:125], v[166:169], v[190:193], v[122:125]
	v_mfma_f32_16x16x32_bf16 v[110:113], v[158:161], v[208:211], v[110:113]
	v_mfma_f32_16x16x32_bf16 v[106:109], v[166:169], v[208:211], v[106:109]
	v_mfma_f32_16x16x32_bf16 v[94:97], v[158:161], v[216:219], v[94:97]
	v_mfma_f32_16x16x32_bf16 v[90:93], v[166:169], v[216:219], v[90:93]
	v_mfma_f32_16x16x32_bf16 v[78:81], v[158:161], v[224:227], v[78:81]
	v_mfma_f32_16x16x32_bf16 v[74:77], v[166:169], v[224:227], v[74:77]
	s_setprio 0
	s_setprio 1
	v_mfma_f32_16x16x32_bf16 v[118:121], v[170:173], v[186:189], v[118:121]
	v_mfma_f32_16x16x32_bf16 v[114:117], v[178:181], v[186:189], v[114:117]
	v_mfma_f32_16x16x32_bf16 v[102:105], v[170:173], v[204:207], v[102:105]
	v_mfma_f32_16x16x32_bf16 v[98:101], v[178:181], v[204:207], v[98:101]
	v_mfma_f32_16x16x32_bf16 v[86:89], v[170:173], v[212:215], v[86:89]
	v_mfma_f32_16x16x32_bf16 v[82:85], v[178:181], v[212:215], v[82:85]
	v_mfma_f32_16x16x32_bf16 v[70:73], v[170:173], v[220:223], v[70:73]
	v_mfma_f32_16x16x32_bf16 v[66:69], v[178:181], v[220:223], v[66:69]
	v_mfma_f32_16x16x32_bf16 v[118:121], v[174:177], v[190:193], v[118:121]
	v_mfma_f32_16x16x32_bf16 v[114:117], v[182:185], v[190:193], v[114:117]
	v_mfma_f32_16x16x32_bf16 v[102:105], v[174:177], v[208:211], v[102:105]
	v_mfma_f32_16x16x32_bf16 v[98:101], v[182:185], v[208:211], v[98:101]
	v_mfma_f32_16x16x32_bf16 v[86:89], v[174:177], v[216:219], v[86:89]
	v_mfma_f32_16x16x32_bf16 v[82:85], v[182:185], v[216:219], v[82:85]
	v_mfma_f32_16x16x32_bf16 v[70:73], v[174:177], v[224:227], v[70:73]
	v_mfma_f32_16x16x32_bf16 v[66:69], v[182:185], v[224:227], v[66:69]
	s_setprio 0
	s_barrier
	s_add_i32 s37, s37, s16
	v_lshl_add_u64 v[146:147], s[20:21], 0, v[0:1]
	s_mov_b32 m0, s37
	ds_read_b128 v[186:189], v157 offset:16384
	global_load_lds_dwordx4 v[146:147], off
	ds_read_b128 v[190:193], v157 offset:17408
	ds_read_b128 v[204:207], v157 offset:18432
	s_add_i32 m0, s37, 0x2000
	s_add_u32 s56, s20, 0x40000
	v_lshl_add_u64 v[150:151], s[20:21], 0, v[130:131]
	s_addc_u32 s57, s21, 0
	s_add_i32 s37, s58, s16
	global_load_lds_dwordx4 v[150:151], off
	ds_read_b128 v[208:211], v157 offset:19456
	ds_read_b128 v[212:215], v157 offset:20480
	v_lshl_add_u64 v[154:155], s[56:57], 0, v[0:1]
	s_mov_b32 m0, s37
	v_lshl_add_u64 v[228:229], s[46:47], 0, v[132:133]
	global_load_lds_dwordx4 v[154:155], off
	ds_read_b128 v[216:219], v157 offset:21504
	ds_read_b128 v[220:223], v157 offset:22528
	v_lshl_add_u64 v[154:155], s[56:57], 0, v[130:131]
	s_add_i32 m0, s37, 0x2000
	s_nop 0
	global_load_lds_dwordx4 v[154:155], off
	ds_read_b128 v[224:227], v157 offset:23552
	v_lshl_add_u64 v[154:155], s[46:47], 0, v[134:135]
	s_mov_b32 m0, s18
	s_nop 0
	global_load_lds_dwordx4 v[154:155], off
	s_mov_b32 m0, s19
	s_nop 0
	global_load_lds_dwordx4 v[228:229], off
	s_waitcnt vmcnt(8)
	s_waitcnt lgkmcnt(0)
	s_barrier
; #define PG8_STAGE(bufoff, gbase, voff) do { _Pragma("unroll") for (int _i = 0; _i < 2; ++_i) \
;         __builtin_amdgcn_global_load_lds((const unsigned*)((const char*)(gbase) + (voff)[_i]), (PG8_LAS unsigned*)(lds + (bufoff) + ldsw + _i * 8192), 16, 0, 0); } while (0)
; #define PG8_LDA(dst, b, h) do { _Pragma("unroll") for (int m = 0; m < 4; ++m) _Pragma("unroll") for (int k = 0; k < 2; ++k) dst[m][k] = *(const PG8_LAS bf16x8*)(lds + PG8_SA(b, h) + aoff + m * 2048 + k * 1024); } while (0)
; #define PG8_LDB(dst, b, h) do { _Pragma("unroll") for (int n = 0; n < 2; ++n) _Pragma("unroll") for (int k = 0; k < 2; ++k) dst[n][k] = *(const PG8_LAS bf16x8*)(lds + PG8_SB(b, h) + boff + n * 2048 + k * 1024); } while (0)
; #define PG8_MMA(ai, bj, At, Bt) do { __builtin_amdgcn_s_setprio(1); _Pragma("unroll") for (int m = 0; m < 4; ++m) _Pragma("unroll") for (int n = 0; n < 2; ++n) _Pragma("unroll") for (int k = 0; k < 2; ++k) \
;         acc[ai][bj][m][n] = __builtin_amdgcn_mfma_f32_16x16x32_bf16(Bt[n][k], At[m][k], acc[ai][bj][m][n], 0, 0, 0); __builtin_amdgcn_s_setprio(0); } while (0)
; #define PG8_WAIT_V(n) asm volatile("s_waitcnt vmcnt(" #n ")" ::: "memory")
; #define PG8_WAIT_L(n) asm volatile("s_waitcnt lgkmcnt(" #n ")" ::: "memory")
; #define PG8_BAR __builtin_amdgcn_s_barrier()
; #define PG8_SCHED __builtin_amdgcn_sched_barrier(0)
; template <class Epi, class Sched, bool ALIGN_EPI = false, bool SP2 = false>
; __device__ __forceinline__ void gemm_phase(PG8_LAS unsigned char* lds, const Gemm g, const Sched& S, const Epi& E) {
;     ...
;             PG8_WAIT_V(8); PG8_WAIT_L(0); PG8_BAR; PG8_MMA(1, 0, At, B0); PG8_MMA(1, 1, At, B1); PG8_BAR; PG8_SCHED;
;             PG8_LDB(B0, 1, 0); PG8_LDB(B1, 1, 1); PG8_SCHED; PG8_LDA(At, 1, 0); PG8_STAGE(PG8_SA(0, 1), a2 + hstep, voffA);
;             PG8_WAIT_V(8); PG8_WAIT_L(0); PG8_BAR; PG8_MMA(0, 0, At, B0); PG8_MMA(0, 1, At, B1); PG8_BAR; PG8_SCHED;
;             PG8_LDA(At, 1, 1); PG8_STAGE(PG8_SB(1, 0), b3, voffB); PG8_STAGE(PG8_SB(1, 1), b3 + hstep, voffB); PG8_STAGE(PG8_SA(1, 0), a3, voffA);
	s_setprio 1
	s_waitcnt lgkmcnt(0)
	v_mfma_f32_16x16x32_bf16 v[62:65], v[140:143], v[186:189], v[62:65]
	v_mfma_f32_16x16x32_bf16 v[58:61], v[162:165], v[186:189], v[58:61]
	v_mfma_f32_16x16x32_bf16 v[46:49], v[140:143], v[204:207], v[46:49]
	v_mfma_f32_16x16x32_bf16 v[42:45], v[162:165], v[204:207], v[42:45]
	v_mfma_f32_16x16x32_bf16 v[30:33], v[140:143], v[212:215], v[30:33]
	v_mfma_f32_16x16x32_bf16 v[26:29], v[162:165], v[212:215], v[26:29]
	v_mfma_f32_16x16x32_bf16 v[14:17], v[140:143], v[220:223], v[14:17]
	v_mfma_f32_16x16x32_bf16 v[10:13], v[162:165], v[220:223], v[10:13]
	v_mfma_f32_16x16x32_bf16 v[62:65], v[158:161], v[190:193], v[62:65]
	v_mfma_f32_16x16x32_bf16 v[58:61], v[166:169], v[190:193], v[58:61]
	v_mfma_f32_16x16x32_bf16 v[46:49], v[158:161], v[208:211], v[46:49]
	v_mfma_f32_16x16x32_bf16 v[42:45], v[166:169], v[208:211], v[42:45]
	v_mfma_f32_16x16x32_bf16 v[30:33], v[158:161], v[216:219], v[30:33]
	v_mfma_f32_16x16x32_bf16 v[26:29], v[166:169], v[216:219], v[26:29]
	v_mfma_f32_16x16x32_bf16 v[14:17], v[158:161], v[224:227], v[14:17]
	v_mfma_f32_16x16x32_bf16 v[10:13], v[166:169], v[224:227], v[10:13]
	s_setprio 0
	s_setprio 1
	v_mfma_f32_16x16x32_bf16 v[54:57], v[170:173], v[186:189], v[54:57]
	v_mfma_f32_16x16x32_bf16 v[50:53], v[178:181], v[186:189], v[50:53]
	v_mfma_f32_16x16x32_bf16 v[38:41], v[170:173], v[204:207], v[38:41]
	v_mfma_f32_16x16x32_bf16 v[34:37], v[178:181], v[204:207], v[34:37]
	v_mfma_f32_16x16x32_bf16 v[22:25], v[170:173], v[212:215], v[22:25]
	v_mfma_f32_16x16x32_bf16 v[18:21], v[178:181], v[212:215], v[18:21]
	v_mfma_f32_16x16x32_bf16 v[6:9], v[170:173], v[220:223], v[6:9]
	v_mfma_f32_16x16x32_bf16 v[2:5], v[178:181], v[220:223], v[2:5]
	v_mfma_f32_16x16x32_bf16 v[54:57], v[174:177], v[190:193], v[54:57]
	v_mfma_f32_16x16x32_bf16 v[50:53], v[182:185], v[190:193], v[50:53]
	v_mfma_f32_16x16x32_bf16 v[38:41], v[174:177], v[208:211], v[38:41]
	v_mfma_f32_16x16x32_bf16 v[34:37], v[182:185], v[208:211], v[34:37]
	v_mfma_f32_16x16x32_bf16 v[22:25], v[174:177], v[216:219], v[22:25]
	v_mfma_f32_16x16x32_bf16 v[18:21], v[182:185], v[216:219], v[18:21]
	v_mfma_f32_16x16x32_bf16 v[6:9], v[174:177], v[224:227], v[6:9]
	v_mfma_f32_16x16x32_bf16 v[2:5], v[182:185], v[224:227], v[2:5]
	s_setprio 0
	s_barrier
	s_add_i32 s37, 0, 0x18000
	v_add_u32_e32 v144, s37, v149
	s_add_i32 s56, 0, 0x1c000
	ds_read_b128 v[140:143], v144
	ds_read_b128 v[158:161], v144 offset:1024
	ds_read_b128 v[162:165], v144 offset:2048
	ds_read_b128 v[166:169], v144 offset:3072
	v_add_u32_e32 v144, s56, v149
	ds_read_b128 v[170:173], v144
	ds_read_b128 v[174:177], v144 offset:1024
	ds_read_b128 v[178:181], v144 offset:2048
	ds_read_b128 v[182:185], v144 offset:3072
	s_add_u32 s46, s46, 0x40000
	s_addc_u32 s47, s47, 0
	s_mov_b32 m0, s33
	v_lshl_add_u64 v[230:231], s[46:47], 0, v[134:135]
	ds_read_b128 v[186:189], v157 offset:32768
	ds_read_b128 v[190:193], v157 offset:33792
	ds_read_b128 v[204:207], v157 offset:34816
	ds_read_b128 v[208:211], v157 offset:35840
	ds_read_b128 v[212:215], v157 offset:36864
	ds_read_b128 v[216:219], v157 offset:37888
	ds_read_b128 v[220:223], v157 offset:38912
	ds_read_b128 v[224:227], v157 offset:39936
	global_load_lds_dwordx4 v[230:231], off
	v_lshl_add_u64 v[230:231], s[46:47], 0, v[132:133]
	s_mov_b32 m0, s34
	s_nop 0
	global_load_lds_dwordx4 v[230:231], off
	s_waitcnt vmcnt(8)
	s_waitcnt lgkmcnt(0)
	s_barrier
	s_setprio 1
	s_waitcnt lgkmcnt(0)
	v_mfma_f32_16x16x32_bf16 v[126:129], v[140:143], v[186:189], v[126:129]
	v_mfma_f32_16x16x32_bf16 v[122:125], v[162:165], v[186:189], v[122:125]
	v_mfma_f32_16x16x32_bf16 v[110:113], v[140:143], v[204:207], v[110:113]
	v_mfma_f32_16x16x32_bf16 v[106:109], v[162:165], v[204:207], v[106:109]
	v_mfma_f32_16x16x32_bf16 v[94:97], v[140:143], v[212:215], v[94:97]
	v_mfma_f32_16x16x32_bf16 v[90:93], v[162:165], v[212:215], v[90:93]
	v_mfma_f32_16x16x32_bf16 v[78:81], v[140:143], v[220:223], v[78:81]
	v_mfma_f32_16x16x32_bf16 v[74:77], v[162:165], v[220:223], v[74:77]
	v_mfma_f32_16x16x32_bf16 v[126:129], v[158:161], v[190:193], v[126:129]
	v_mfma_f32_16x16x32_bf16 v[122:125], v[166:169], v[190:193], v[122:125]
	v_mfma_f32_16x16x32_bf16 v[110:113], v[158:161], v[208:211], v[110:113]
	v_mfma_f32_16x16x32_bf16 v[106:109], v[166:169], v[208:211], v[106:109]
	v_mfma_f32_16x16x32_bf16 v[94:97], v[158:161], v[216:219], v[94:97]
	v_mfma_f32_16x16x32_bf16 v[90:93], v[166:169], v[216:219], v[90:93]
	v_mfma_f32_16x16x32_bf16 v[78:81], v[158:161], v[224:227], v[78:81]
	v_mfma_f32_16x16x32_bf16 v[74:77], v[166:169], v[224:227], v[74:77]
	s_setprio 0
	s_setprio 1
	v_mfma_f32_16x16x32_bf16 v[118:121], v[170:173], v[186:189], v[118:121]
	v_mfma_f32_16x16x32_bf16 v[114:117], v[178:181], v[186:189], v[114:117]
	v_mfma_f32_16x16x32_bf16 v[102:105], v[170:173], v[204:207], v[102:105]
	v_mfma_f32_16x16x32_bf16 v[98:101], v[178:181], v[204:207], v[98:101]
	v_mfma_f32_16x16x32_bf16 v[86:89], v[170:173], v[212:215], v[86:89]
	v_mfma_f32_16x16x32_bf16 v[82:85], v[178:181], v[212:215], v[82:85]
	v_mfma_f32_16x16x32_bf16 v[70:73], v[170:173], v[220:223], v[70:73]
	v_mfma_f32_16x16x32_bf16 v[66:69], v[178:181], v[220:223], v[66:69]
	v_mfma_f32_16x16x32_bf16 v[118:121], v[174:177], v[190:193], v[118:121]
	v_mfma_f32_16x16x32_bf16 v[114:117], v[182:185], v[190:193], v[114:117]
	v_mfma_f32_16x16x32_bf16 v[102:105], v[174:177], v[208:211], v[102:105]
	v_mfma_f32_16x16x32_bf16 v[98:101], v[182:185], v[208:211], v[98:101]
	v_mfma_f32_16x16x32_bf16 v[86:89], v[174:177], v[216:219], v[86:89]
	v_mfma_f32_16x16x32_bf16 v[82:85], v[182:185], v[216:219], v[82:85]
	v_mfma_f32_16x16x32_bf16 v[70:73], v[174:177], v[224:227], v[70:73]
	v_mfma_f32_16x16x32_bf16 v[66:69], v[182:185], v[224:227], v[66:69]
	s_setprio 0
	s_barrier
; #define PG8_STAGE(bufoff, gbase, voff) do { _Pragma("unroll") for (int _i = 0; _i < 2; ++_i) \
;         __builtin_amdgcn_global_load_lds((const unsigned*)((const char*)(gbase) + (voff)[_i]), (PG8_LAS unsigned*)(lds + (bufoff) + ldsw + _i * 8192), 16, 0, 0); } while (0)
; #define PG8_LDA(dst, b, h) do { _Pragma("unroll") for (int m = 0; m < 4; ++m) _Pragma("unroll") for (int k = 0; k < 2; ++k) dst[m][k] = *(const PG8_LAS bf16x8*)(lds + PG8_SA(b, h) + aoff + m * 2048 + k * 1024); } while (0)
; #define PG8_MMA(ai, bj, At, Bt) do { __builtin_amdgcn_s_setprio(1); _Pragma("unroll") for (int m = 0; m < 4; ++m) _Pragma("unroll") for (int n = 0; n < 2; ++n) _Pragma("unroll") for (int k = 0; k < 2; ++k) \
;         acc[ai][bj][m][n] = __builtin_amdgcn_mfma_f32_16x16x32_bf16(Bt[n][k], At[m][k], acc[ai][bj][m][n], 0, 0, 0); __builtin_amdgcn_s_setprio(0); } while (0)
; #define PG8_WAIT_V(n) asm volatile("s_waitcnt vmcnt(" #n ")" ::: "memory")
; #define PG8_WAIT_L(n) asm volatile("s_waitcnt lgkmcnt(" #n ")" ::: "memory")
; #define PG8_BAR __builtin_amdgcn_s_barrier()
; #define PG8_SCHED __builtin_amdgcn_sched_barrier(0)
; __device__ __forceinline__ void rstd8(const float* part, int row0, float (&rs)[2][4]) {
;     f32x4 v[2][4];
; #pragma unroll
;     for (int ai = 0; ai < 2; ++ai)
; #pragma unroll
;         for (int m = 0; m < 4; ++m) v[ai][m] = *(const f32x4*)(part + (size_t)(row0 + ai * HALF + m * 16) * 4);
; template <class Epi, class Sched, bool ALIGN_EPI = false, bool SP2 = false>
; __device__ __forceinline__ void gemm_phase(PG8_LAS unsigned char* lds, const Gemm g, const Sched& S, const Epi& E) {
;     ...
;             PG8_LDA(At, 1, 1); PG8_STAGE(PG8_SB(1, 0), b3, voffB); PG8_STAGE(PG8_SB(1, 1), b3 + hstep, voffB); PG8_STAGE(PG8_SA(1, 0), a3, voffA);
;             PG8_WAIT_V(8); PG8_WAIT_L(0); PG8_BAR; PG8_MMA(1, 0, At, B0); PG8_MMA(1, 1, At, B1); PG8_BAR; PG8_SCHED;
	s_add_i32 s37, s37, s16
	v_lshl_add_u64 v[146:147], v[146:147], 0, s[28:29]
	s_mov_b32 m0, s37
	ds_read_b128 v[186:189], v157 offset:49152
	global_load_lds_dwordx4 v[146:147], off
	ds_read_b128 v[190:193], v157 offset:50176
	ds_read_b128 v[204:207], v157 offset:51200
	s_add_i32 m0, s37, 0x2000
	s_add_u32 s20, s20, 0x40080
	v_lshl_add_u64 v[146:147], v[150:151], 0, s[28:29]
	s_addc_u32 s21, s21, 0
	s_add_i32 s37, s56, s16
	global_load_lds_dwordx4 v[146:147], off
	ds_read_b128 v[208:211], v157 offset:52224
	ds_read_b128 v[212:215], v157 offset:53248
	v_lshl_add_u64 v[146:147], s[20:21], 0, v[0:1]
	s_mov_b32 m0, s37
	s_nop 0
	global_load_lds_dwordx4 v[146:147], off
	ds_read_b128 v[216:219], v157 offset:54272
	ds_read_b128 v[220:223], v157 offset:55296
	v_lshl_add_u64 v[146:147], s[20:21], 0, v[130:131]
	s_add_i32 m0, s37, 0x2000
	s_nop 0
	global_load_lds_dwordx4 v[146:147], off
	ds_read_b128 v[224:227], v157 offset:56320
	v_lshl_add_u64 v[146:147], v[154:155], 0, s[28:29]
	s_mov_b32 m0, s35
	s_nop 0
	global_load_lds_dwordx4 v[146:147], off
	v_lshl_add_u64 v[146:147], v[228:229], 0, s[28:29]
	s_mov_b32 m0, s36
	s_nop 0
	global_load_lds_dwordx4 v[146:147], off
	s_waitcnt vmcnt(8)
	s_waitcnt lgkmcnt(0)
	s_barrier
	s_setprio 1
	s_waitcnt lgkmcnt(0)
	v_mfma_f32_16x16x32_bf16 v[62:65], v[140:143], v[186:189], v[62:65]
	v_mfma_f32_16x16x32_bf16 v[58:61], v[162:165], v[186:189], v[58:61]
	v_mfma_f32_16x16x32_bf16 v[46:49], v[140:143], v[204:207], v[46:49]
	v_mfma_f32_16x16x32_bf16 v[42:45], v[162:165], v[204:207], v[42:45]
	v_mfma_f32_16x16x32_bf16 v[30:33], v[140:143], v[212:215], v[30:33]
	v_mfma_f32_16x16x32_bf16 v[26:29], v[162:165], v[212:215], v[26:29]
	v_mfma_f32_16x16x32_bf16 v[14:17], v[140:143], v[220:223], v[14:17]
	v_mfma_f32_16x16x32_bf16 v[10:13], v[162:165], v[220:223], v[10:13]
	v_mfma_f32_16x16x32_bf16 v[62:65], v[158:161], v[190:193], v[62:65]
	v_mfma_f32_16x16x32_bf16 v[58:61], v[166:169], v[190:193], v[58:61]
	v_mfma_f32_16x16x32_bf16 v[46:49], v[158:161], v[208:211], v[46:49]
	v_mfma_f32_16x16x32_bf16 v[42:45], v[166:169], v[208:211], v[42:45]
	v_mfma_f32_16x16x32_bf16 v[30:33], v[158:161], v[216:219], v[30:33]
	v_mfma_f32_16x16x32_bf16 v[26:29], v[166:169], v[216:219], v[26:29]
	v_mfma_f32_16x16x32_bf16 v[14:17], v[158:161], v[224:227], v[14:17]
	v_mfma_f32_16x16x32_bf16 v[10:13], v[166:169], v[224:227], v[10:13]
	s_setprio 0
	s_setprio 1
	v_mfma_f32_16x16x32_bf16 v[54:57], v[170:173], v[186:189], v[54:57]
	v_mfma_f32_16x16x32_bf16 v[50:53], v[178:181], v[186:189], v[50:53]
	v_mfma_f32_16x16x32_bf16 v[38:41], v[170:173], v[204:207], v[38:41]
	v_mfma_f32_16x16x32_bf16 v[34:37], v[178:181], v[204:207], v[34:37]
	v_mfma_f32_16x16x32_bf16 v[22:25], v[170:173], v[212:215], v[22:25]
	v_mfma_f32_16x16x32_bf16 v[18:21], v[178:181], v[212:215], v[18:21]
	v_mfma_f32_16x16x32_bf16 v[6:9], v[170:173], v[220:223], v[6:9]
	v_mfma_f32_16x16x32_bf16 v[2:5], v[178:181], v[220:223], v[2:5]
	v_mfma_f32_16x16x32_bf16 v[54:57], v[174:177], v[190:193], v[54:57]
	v_mfma_f32_16x16x32_bf16 v[50:53], v[182:185], v[190:193], v[50:53]
	v_mfma_f32_16x16x32_bf16 v[38:41], v[174:177], v[208:211], v[38:41]
	v_mfma_f32_16x16x32_bf16 v[34:37], v[182:185], v[208:211], v[34:37]
	v_mfma_f32_16x16x32_bf16 v[22:25], v[174:177], v[216:219], v[22:25]
	v_mfma_f32_16x16x32_bf16 v[18:21], v[182:185], v[216:219], v[18:21]
	v_mfma_f32_16x16x32_bf16 v[6:9], v[174:177], v[224:227], v[6:9]
	v_mfma_f32_16x16x32_bf16 v[2:5], v[182:185], v[224:227], v[2:5]
	s_setprio 0
	s_barrier
	s_add_i32 s55, s55, 2
	s_add_u32 s8, s8, 0x100
	s_addc_u32 s9, s9, 0
	s_add_u32 s53, s53, 0x100
	s_addc_u32 s54, s54, 0
	s_cmp_gt_u32 s55, 13
	s_cbranch_scc0 .LBB0_317
	s_and_b64 vcc, exec, s[6:7]
	s_cbranch_vccz .LBB0_320
	s_barrier
.LBB0_320:
	v_lshl_add_u32 v166, s50, 8, v145
	v_ashrrev_i32_e32 v167, 31, v166
	v_lshl_add_u64 v[140:141], v[166:167], 4, s[14:15]
	v_or_b32_e32 v162, 16, v166
	global_load_dwordx4 v[170:173], v[140:141], off
	v_ashrrev_i32_e32 v163, 31, v162
	v_lshl_add_u64 v[140:141], v[162:163], 4, s[14:15]
	v_or_b32_e32 v158, 32, v166
	global_load_dwordx4 v[174:177], v[140:141], off
	v_ashrrev_i32_e32 v159, 31, v158
	v_lshl_add_u64 v[140:141], v[158:159], 4, s[14:15]
	v_or_b32_e32 v154, 48, v166
	global_load_dwordx4 v[178:181], v[140:141], off
	v_ashrrev_i32_e32 v155, 31, v154
	v_lshl_add_u64 v[140:141], v[154:155], 4, s[14:15]
	v_add_u32_e32 v150, 0x80, v166
	global_load_dwordx4 v[182:185], v[140:141], off
	v_ashrrev_i32_e32 v151, 31, v150
	v_lshl_add_u64 v[140:141], v[150:151], 4, s[14:15]
	v_add_u32_e32 v146, 0x90, v166
	global_load_dwordx4 v[186:189], v[140:141], off
	v_ashrrev_i32_e32 v147, 31, v146
	v_add_u32_e32 v142, 0xa0, v166
	v_lshl_add_u64 v[140:141], v[146:147], 4, s[14:15]
	v_ashrrev_i32_e32 v143, 31, v142
	global_load_dwordx4 v[190:193], v[140:141], off
	v_lshl_add_u64 v[140:141], v[142:143], 4, s[14:15]
	global_load_dwordx4 v[204:207], v[140:141], off
	v_add_u32_e32 v140, 0xb0, v166
	v_ashrrev_i32_e32 v141, 31, v140
	v_lshl_add_u64 v[160:161], v[140:141], 4, s[14:15]
	global_load_dwordx4 v[208:211], v[160:161], off
	v_lshl_or_b32 v168, s49, 7, v153
	v_ashrrev_i32_e32 v169, 31, v168
	s_movk_i32 s20, 0x1600
	s_andn2_b64 vcc, exec, s[38:39]
	s_waitcnt vmcnt(0)
; __device__ __forceinline__ unsigned pk(float lo, float hi) { f32x2v v = {lo, hi}; bf16x2v b = __builtin_convertvector(v, bf16x2v); return __builtin_bit_cast(unsigned, b); }
; __device__ __forceinline__ void rstd8(const float* part, int row0, float (&rs)[2][4]) {
;     ...
;         for (int m = 0; m < 4; ++m) rs[ai][m] = __builtin_amdgcn_rsqf(((v[ai][m][0] + v[ai][m][1]) + (v[ai][m][2] + v[ai][m][3])) * (1.0f / 1024.0f) + 1e-6f);
;     asm volatile("" ::: "memory");
; }
; __device__ __forceinline__ float silu_f(float x) { return x * __builtin_amdgcn_rcpf(1.0f + __builtin_amdgcn_exp2f(-1.4426950408889634f * x)); }
;     __device__ __forceinline__ void operator()(const f32x4 (&acc)[2][2][4][2], const Unit& u, int wr, int wc, int fr, int fq) const {
;         const int row0 = u.pm * BM + wr * 64 + fr, col0 = u.pn * 128 + wc * 32 + 8 * fq;
;         float rsv[2][4]; rstd8(part, row0, rsv);
; #pragma unroll
;         for (int ai = 0; ai < 2; ++ai)
; #pragma unroll
;             for (int m = 0; m < 4; ++m) { const int row = row0 + ai * HALF + m * 16; const float rs = rsv[ai][m];
;                 const f32x4 g0 = acc[ai][0][m][0] * rs, g1 = acc[ai][0][m][1] * rs, u0 = acc[ai][1][m][0] * rs, u1 = acc[ai][1][m][1] * rs;
;                 u32x4 w; w.x = pk(silu_f(g0[0]) * u0[0], silu_f(g0[1]) * u0[1]); w.y = pk(silu_f(g0[2]) * u0[2], silu_f(g0[3]) * u0[3]);
;                 w.z = pk(silu_f(g1[0]) * u1[0], silu_f(g1[1]) * u1[1]); w.w = pk(silu_f(g1[2]) * u1[2], silu_f(g1[3]) * u1[3]);
;                 *(u32x4*)(H + (size_t)row * DFF + col0) = w; }
	v_add_f32_e32 v170, v170, v171
	v_add_f32_e32 v174, v174, v175
	v_add_f32_e32 v178, v178, v179
	v_add_f32_e32 v182, v182, v183
	v_add_f32_e32 v186, v186, v187
	v_add_f32_e32 v190, v190, v191
	v_add_f32_e32 v204, v204, v205
	v_add_f32_e32 v208, v208, v209
	v_add_f32_e32 v172, v172, v173
	v_add_f32_e32 v176, v176, v177
	v_add_f32_e32 v180, v180, v181
	v_add_f32_e32 v184, v184, v185
	v_add_f32_e32 v188, v188, v189
	v_add_f32_e32 v192, v192, v193
	v_add_f32_e32 v206, v206, v207
	v_add_f32_e32 v210, v210, v211
	v_add_f32_e32 v170, v170, v172
	v_add_f32_e32 v174, v174, v176
	v_add_f32_e32 v178, v178, v180
	v_add_f32_e32 v182, v182, v184
	v_add_f32_e32 v186, v186, v188
	v_add_f32_e32 v190, v190, v192
	v_add_f32_e32 v204, v204, v206
	v_add_f32_e32 v208, v208, v210
	v_fmamk_f32 v170, v170, 0x3a800000, v241
	v_fmamk_f32 v174, v174, 0x3a800000, v241
	v_fmamk_f32 v178, v178, 0x3a800000, v241
	v_fmamk_f32 v182, v182, 0x3a800000, v241
	v_fmamk_f32 v186, v186, 0x3a800000, v241
	v_fmamk_f32 v190, v190, 0x3a800000, v241
	v_fmamk_f32 v204, v204, 0x3a800000, v241
	v_fmamk_f32 v208, v208, 0x3a800000, v241
	v_rsq_f32_e32 v170, v170
	v_rsq_f32_e32 v174, v174
	v_rsq_f32_e32 v178, v178
	v_rsq_f32_e32 v182, v182
	v_rsq_f32_e32 v186, v186
	v_rsq_f32_e32 v190, v190
	v_rsq_f32_e32 v204, v204
	v_rsq_f32_e32 v208, v208
	v_mov_b64_e32 v[212:213], s[12:13]
	v_lshlrev_b64 v[214:215], 1, v[168:169]
	v_pk_mul_f32 v[126:127], v[126:127], v[170:171] op_sel_hi:[1,0]
	v_pk_mul_f32 v[128:129], v[128:129], v[170:171] op_sel_hi:[1,0]
	v_pk_mul_f32 v[122:123], v[122:123], v[170:171] op_sel_hi:[1,0]
	v_pk_mul_f32 v[124:125], v[124:125], v[170:171] op_sel_hi:[1,0]
	v_pk_mul_f32 v[118:119], v[118:119], v[170:171] op_sel_hi:[1,0]
	v_pk_mul_f32 v[120:121], v[120:121], v[170:171] op_sel_hi:[1,0]
	v_pk_mul_f32 v[114:115], v[114:115], v[170:171] op_sel_hi:[1,0]
	v_pk_mul_f32 v[116:117], v[116:117], v[170:171] op_sel_hi:[1,0]
	v_mul_f32_e32 v172, 0xbfb8aa3b, v126
	v_mul_f32_e32 v173, 0xbfb8aa3b, v127
	v_mul_f32_e32 v216, 0xbfb8aa3b, v128
	v_mul_f32_e32 v217, 0xbfb8aa3b, v129
	v_mul_f32_e32 v218, 0xbfb8aa3b, v122
	v_mul_f32_e32 v219, 0xbfb8aa3b, v123
	v_mul_f32_e32 v220, 0xbfb8aa3b, v124
	v_mul_f32_e32 v221, 0xbfb8aa3b, v125
	v_exp_f32_e32 v172, v172
	v_exp_f32_e32 v173, v173
	v_exp_f32_e32 v216, v216
	v_exp_f32_e32 v217, v217
	v_exp_f32_e32 v218, v218
	v_exp_f32_e32 v219, v219
	v_exp_f32_e32 v220, v220
	v_exp_f32_e32 v221, v221
	v_add_f32_e32 v172, 1.0, v172
	v_add_f32_e32 v173, 1.0, v173
	v_add_f32_e32 v216, 1.0, v216
	v_add_f32_e32 v217, 1.0, v217
	v_add_f32_e32 v218, 1.0, v218
	v_add_f32_e32 v219, 1.0, v219
	v_add_f32_e32 v220, 1.0, v220
	v_add_f32_e32 v221, 1.0, v221
	v_rcp_f32_e32 v172, v172
	v_rcp_f32_e32 v173, v173
	v_rcp_f32_e32 v216, v216
	v_rcp_f32_e32 v217, v217
	v_rcp_f32_e32 v218, v218
	v_rcp_f32_e32 v219, v219
	v_rcp_f32_e32 v220, v220
	v_rcp_f32_e32 v221, v221
	v_mad_i64_i32 v[228:229], s[8:9], v166, s20, v[212:213]
	v_pk_mul_f32 v[172:173], v[126:127], v[172:173]
	v_pk_mul_f32 v[216:217], v[128:129], v[216:217]
	v_pk_mul_f32 v[218:219], v[122:123], v[218:219]
	v_pk_mul_f32 v[220:221], v[124:125], v[220:221]
	v_lshl_add_u64 v[228:229], v[228:229], 0, v[214:215]
	v_pk_mul_f32 v[118:119], v[118:119], v[172:173]
	v_pk_mul_f32 v[120:121], v[120:121], v[216:217]
	v_pk_mul_f32 v[114:115], v[114:115], v[218:219]
	v_pk_mul_f32 v[116:117], v[116:117], v[220:221]
	s_nop 0
	v_cvt_pk_bf16_f32 v126, v118, v119
	v_cvt_pk_bf16_f32 v127, v120, v121
	v_cvt_pk_bf16_f32 v128, v114, v115
	v_cvt_pk_bf16_f32 v129, v116, v117
	global_store_dwordx4 v[228:229], v[126:129], off
	v_pk_mul_f32 v[110:111], v[110:111], v[174:175] op_sel_hi:[1,0]
	v_pk_mul_f32 v[112:113], v[112:113], v[174:175] op_sel_hi:[1,0]
	v_pk_mul_f32 v[106:107], v[106:107], v[174:175] op_sel_hi:[1,0]
	v_pk_mul_f32 v[108:109], v[108:109], v[174:175] op_sel_hi:[1,0]
	v_pk_mul_f32 v[102:103], v[102:103], v[174:175] op_sel_hi:[1,0]
	v_pk_mul_f32 v[104:105], v[104:105], v[174:175] op_sel_hi:[1,0]
	v_pk_mul_f32 v[98:99], v[98:99], v[174:175] op_sel_hi:[1,0]
	v_pk_mul_f32 v[100:101], v[100:101], v[174:175] op_sel_hi:[1,0]
	v_mul_f32_e32 v176, 0xbfb8aa3b, v110
	v_mul_f32_e32 v177, 0xbfb8aa3b, v111
	v_mul_f32_e32 v216, 0xbfb8aa3b, v112
	v_mul_f32_e32 v217, 0xbfb8aa3b, v113
	v_mul_f32_e32 v218, 0xbfb8aa3b, v106
	v_mul_f32_e32 v219, 0xbfb8aa3b, v107
	v_mul_f32_e32 v220, 0xbfb8aa3b, v108
	v_mul_f32_e32 v221, 0xbfb8aa3b, v109
	v_exp_f32_e32 v176, v176
	v_exp_f32_e32 v177, v177
	v_exp_f32_e32 v216, v216
	v_exp_f32_e32 v217, v217
	v_exp_f32_e32 v218, v218
	v_exp_f32_e32 v219, v219
	v_exp_f32_e32 v220, v220
	v_exp_f32_e32 v221, v221
	v_add_f32_e32 v176, 1.0, v176
	v_add_f32_e32 v177, 1.0, v177
	v_add_f32_e32 v216, 1.0, v216
	v_add_f32_e32 v217, 1.0, v217
	v_add_f32_e32 v218, 1.0, v218
	v_add_f32_e32 v219, 1.0, v219
	v_add_f32_e32 v220, 1.0, v220
	v_add_f32_e32 v221, 1.0, v221
	v_rcp_f32_e32 v176, v176
	v_rcp_f32_e32 v177, v177
	v_rcp_f32_e32 v216, v216
	v_rcp_f32_e32 v217, v217
	v_rcp_f32_e32 v218, v218
	v_rcp_f32_e32 v219, v219
	v_rcp_f32_e32 v220, v220
	v_rcp_f32_e32 v221, v221
	v_mad_i64_i32 v[228:229], s[8:9], v162, s20, v[212:213]
	v_pk_mul_f32 v[176:177], v[110:111], v[176:177]
	v_pk_mul_f32 v[216:217], v[112:113], v[216:217]
	v_pk_mul_f32 v[218:219], v[106:107], v[218:219]
	v_pk_mul_f32 v[220:221], v[108:109], v[220:221]
	v_lshl_add_u64 v[228:229], v[228:229], 0, v[214:215]
	v_pk_mul_f32 v[102:103], v[102:103], v[176:177]
	v_pk_mul_f32 v[104:105], v[104:105], v[216:217]
	v_pk_mul_f32 v[98:99], v[98:99], v[218:219]
	v_pk_mul_f32 v[100:101], v[100:101], v[220:221]
	s_nop 0
	v_cvt_pk_bf16_f32 v110, v102, v103
	v_cvt_pk_bf16_f32 v111, v104, v105
; __device__ __forceinline__ unsigned pk(float lo, float hi) { f32x2v v = {lo, hi}; bf16x2v b = __builtin_convertvector(v, bf16x2v); return __builtin_bit_cast(unsigned, b); }
; __device__ __forceinline__ float silu_f(float x) { return x * __builtin_amdgcn_rcpf(1.0f + __builtin_amdgcn_exp2f(-1.4426950408889634f * x)); }
;     __device__ __forceinline__ void operator()(const f32x4 (&acc)[2][2][4][2], const Unit& u, int wr, int wc, int fr, int fq) const {
;     ...
;         for (int ai = 0; ai < 2; ++ai)
; #pragma unroll
;             for (int m = 0; m < 4; ++m) { const int row = row0 + ai * HALF + m * 16; const float rs = rsv[ai][m];
;                 const f32x4 g0 = acc[ai][0][m][0] * rs, g1 = acc[ai][0][m][1] * rs, u0 = acc[ai][1][m][0] * rs, u1 = acc[ai][1][m][1] * rs;
;                 u32x4 w; w.x = pk(silu_f(g0[0]) * u0[0], silu_f(g0[1]) * u0[1]); w.y = pk(silu_f(g0[2]) * u0[2], silu_f(g0[3]) * u0[3]);
;                 w.z = pk(silu_f(g1[0]) * u1[0], silu_f(g1[1]) * u1[1]); w.w = pk(silu_f(g1[2]) * u1[2], silu_f(g1[3]) * u1[3]);
;                 *(u32x4*)(H + (size_t)row * DFF + col0) = w; }
	v_cvt_pk_bf16_f32 v112, v98, v99
	v_cvt_pk_bf16_f32 v113, v100, v101
	global_store_dwordx4 v[228:229], v[110:113], off
	v_pk_mul_f32 v[94:95], v[94:95], v[178:179] op_sel_hi:[1,0]
	v_pk_mul_f32 v[96:97], v[96:97], v[178:179] op_sel_hi:[1,0]
	v_pk_mul_f32 v[90:91], v[90:91], v[178:179] op_sel_hi:[1,0]
	v_pk_mul_f32 v[92:93], v[92:93], v[178:179] op_sel_hi:[1,0]
	v_pk_mul_f32 v[86:87], v[86:87], v[178:179] op_sel_hi:[1,0]
	v_pk_mul_f32 v[88:89], v[88:89], v[178:179] op_sel_hi:[1,0]
	v_pk_mul_f32 v[82:83], v[82:83], v[178:179] op_sel_hi:[1,0]
	v_pk_mul_f32 v[84:85], v[84:85], v[178:179] op_sel_hi:[1,0]
	v_mul_f32_e32 v180, 0xbfb8aa3b, v94
	v_mul_f32_e32 v181, 0xbfb8aa3b, v95
	v_mul_f32_e32 v216, 0xbfb8aa3b, v96
	v_mul_f32_e32 v217, 0xbfb8aa3b, v97
	v_mul_f32_e32 v218, 0xbfb8aa3b, v90
	v_mul_f32_e32 v219, 0xbfb8aa3b, v91
	v_mul_f32_e32 v220, 0xbfb8aa3b, v92
	v_mul_f32_e32 v221, 0xbfb8aa3b, v93
	v_exp_f32_e32 v180, v180
	v_exp_f32_e32 v181, v181
	v_exp_f32_e32 v216, v216
	v_exp_f32_e32 v217, v217
	v_exp_f32_e32 v218, v218
	v_exp_f32_e32 v219, v219
	v_exp_f32_e32 v220, v220
	v_exp_f32_e32 v221, v221
	v_add_f32_e32 v180, 1.0, v180
	v_add_f32_e32 v181, 1.0, v181
	v_add_f32_e32 v216, 1.0, v216
	v_add_f32_e32 v217, 1.0, v217
	v_add_f32_e32 v218, 1.0, v218
	v_add_f32_e32 v219, 1.0, v219
	v_add_f32_e32 v220, 1.0, v220
	v_add_f32_e32 v221, 1.0, v221
	v_rcp_f32_e32 v180, v180
	v_rcp_f32_e32 v181, v181
	v_rcp_f32_e32 v216, v216
	v_rcp_f32_e32 v217, v217
	v_rcp_f32_e32 v218, v218
	v_rcp_f32_e32 v219, v219
	v_rcp_f32_e32 v220, v220
	v_rcp_f32_e32 v221, v221
	v_mad_i64_i32 v[228:229], s[8:9], v158, s20, v[212:213]
	v_pk_mul_f32 v[180:181], v[94:95], v[180:181]
	v_pk_mul_f32 v[216:217], v[96:97], v[216:217]
	v_pk_mul_f32 v[218:219], v[90:91], v[218:219]
	v_pk_mul_f32 v[220:221], v[92:93], v[220:221]
	v_lshl_add_u64 v[228:229], v[228:229], 0, v[214:215]
	v_pk_mul_f32 v[86:87], v[86:87], v[180:181]
	v_pk_mul_f32 v[88:89], v[88:89], v[216:217]
	v_pk_mul_f32 v[82:83], v[82:83], v[218:219]
	v_pk_mul_f32 v[84:85], v[84:85], v[220:221]
	s_nop 0
	v_cvt_pk_bf16_f32 v94, v86, v87
	v_cvt_pk_bf16_f32 v95, v88, v89
	v_cvt_pk_bf16_f32 v96, v82, v83
	v_cvt_pk_bf16_f32 v97, v84, v85
	global_store_dwordx4 v[228:229], v[94:97], off
	v_pk_mul_f32 v[78:79], v[78:79], v[182:183] op_sel_hi:[1,0]
	v_pk_mul_f32 v[80:81], v[80:81], v[182:183] op_sel_hi:[1,0]
	v_pk_mul_f32 v[74:75], v[74:75], v[182:183] op_sel_hi:[1,0]
	v_pk_mul_f32 v[76:77], v[76:77], v[182:183] op_sel_hi:[1,0]
	v_pk_mul_f32 v[70:71], v[70:71], v[182:183] op_sel_hi:[1,0]
	v_pk_mul_f32 v[72:73], v[72:73], v[182:183] op_sel_hi:[1,0]
	v_pk_mul_f32 v[66:67], v[66:67], v[182:183] op_sel_hi:[1,0]
	v_pk_mul_f32 v[68:69], v[68:69], v[182:183] op_sel_hi:[1,0]
	v_mul_f32_e32 v184, 0xbfb8aa3b, v78
	v_mul_f32_e32 v185, 0xbfb8aa3b, v79
	v_mul_f32_e32 v216, 0xbfb8aa3b, v80
	v_mul_f32_e32 v217, 0xbfb8aa3b, v81
	v_mul_f32_e32 v218, 0xbfb8aa3b, v74
	v_mul_f32_e32 v219, 0xbfb8aa3b, v75
	v_mul_f32_e32 v220, 0xbfb8aa3b, v76
	v_mul_f32_e32 v221, 0xbfb8aa3b, v77
	v_exp_f32_e32 v184, v184
	v_exp_f32_e32 v185, v185
	v_exp_f32_e32 v216, v216
	v_exp_f32_e32 v217, v217
	v_exp_f32_e32 v218, v218
	v_exp_f32_e32 v219, v219
	v_exp_f32_e32 v220, v220
	v_exp_f32_e32 v221, v221
	v_add_f32_e32 v184, 1.0, v184
	v_add_f32_e32 v185, 1.0, v185
	v_add_f32_e32 v216, 1.0, v216
	v_add_f32_e32 v217, 1.0, v217
	v_add_f32_e32 v218, 1.0, v218
	v_add_f32_e32 v219, 1.0, v219
	v_add_f32_e32 v220, 1.0, v220
	v_add_f32_e32 v221, 1.0, v221
	v_rcp_f32_e32 v184, v184
	v_rcp_f32_e32 v185, v185
	v_rcp_f32_e32 v216, v216
	v_rcp_f32_e32 v217, v217
	v_rcp_f32_e32 v218, v218
	v_rcp_f32_e32 v219, v219
	v_rcp_f32_e32 v220, v220
	v_rcp_f32_e32 v221, v221
	v_mad_i64_i32 v[228:229], s[8:9], v154, s20, v[212:213]
	v_pk_mul_f32 v[184:185], v[78:79], v[184:185]
	v_pk_mul_f32 v[216:217], v[80:81], v[216:217]
	v_pk_mul_f32 v[218:219], v[74:75], v[218:219]
	v_pk_mul_f32 v[220:221], v[76:77], v[220:221]
	v_lshl_add_u64 v[228:229], v[228:229], 0, v[214:215]
	v_pk_mul_f32 v[70:71], v[70:71], v[184:185]
	v_pk_mul_f32 v[72:73], v[72:73], v[216:217]
	v_pk_mul_f32 v[66:67], v[66:67], v[218:219]
	v_pk_mul_f32 v[68:69], v[68:69], v[220:221]
	s_nop 0
	v_cvt_pk_bf16_f32 v78, v70, v71
	v_cvt_pk_bf16_f32 v79, v72, v73
	v_cvt_pk_bf16_f32 v80, v66, v67
	v_cvt_pk_bf16_f32 v81, v68, v69
	global_store_dwordx4 v[228:229], v[78:81], off
	v_pk_mul_f32 v[62:63], v[62:63], v[186:187] op_sel_hi:[1,0]
	v_pk_mul_f32 v[64:65], v[64:65], v[186:187] op_sel_hi:[1,0]
	v_pk_mul_f32 v[58:59], v[58:59], v[186:187] op_sel_hi:[1,0]
	v_pk_mul_f32 v[60:61], v[60:61], v[186:187] op_sel_hi:[1,0]
	v_pk_mul_f32 v[54:55], v[54:55], v[186:187] op_sel_hi:[1,0]
	v_pk_mul_f32 v[56:57], v[56:57], v[186:187] op_sel_hi:[1,0]
	v_pk_mul_f32 v[50:51], v[50:51], v[186:187] op_sel_hi:[1,0]
	v_pk_mul_f32 v[52:53], v[52:53], v[186:187] op_sel_hi:[1,0]
	v_mul_f32_e32 v188, 0xbfb8aa3b, v62
	v_mul_f32_e32 v189, 0xbfb8aa3b, v63
	v_mul_f32_e32 v216, 0xbfb8aa3b, v64
	v_mul_f32_e32 v217, 0xbfb8aa3b, v65
	v_mul_f32_e32 v218, 0xbfb8aa3b, v58
	v_mul_f32_e32 v219, 0xbfb8aa3b, v59
	v_mul_f32_e32 v220, 0xbfb8aa3b, v60
	v_mul_f32_e32 v221, 0xbfb8aa3b, v61
	v_exp_f32_e32 v188, v188
	v_exp_f32_e32 v189, v189
	v_exp_f32_e32 v216, v216
	v_exp_f32_e32 v217, v217
	v_exp_f32_e32 v218, v218
	v_exp_f32_e32 v219, v219
	v_exp_f32_e32 v220, v220
	v_exp_f32_e32 v221, v221
	v_add_f32_e32 v188, 1.0, v188
	v_add_f32_e32 v189, 1.0, v189
	v_add_f32_e32 v216, 1.0, v216
	v_add_f32_e32 v217, 1.0, v217
	v_add_f32_e32 v218, 1.0, v218
	v_add_f32_e32 v219, 1.0, v219
	v_add_f32_e32 v220, 1.0, v220
	v_add_f32_e32 v221, 1.0, v221
	v_rcp_f32_e32 v188, v188
	v_rcp_f32_e32 v189, v189
; __device__ __forceinline__ unsigned pk(float lo, float hi) { f32x2v v = {lo, hi}; bf16x2v b = __builtin_convertvector(v, bf16x2v); return __builtin_bit_cast(unsigned, b); }
; __device__ __forceinline__ float silu_f(float x) { return x * __builtin_amdgcn_rcpf(1.0f + __builtin_amdgcn_exp2f(-1.4426950408889634f * x)); }
;     __device__ __forceinline__ void operator()(const f32x4 (&acc)[2][2][4][2], const Unit& u, int wr, int wc, int fr, int fq) const {
;     ...
;         for (int ai = 0; ai < 2; ++ai)
; #pragma unroll
;             for (int m = 0; m < 4; ++m) { const int row = row0 + ai * HALF + m * 16; const float rs = rsv[ai][m];
;                 const f32x4 g0 = acc[ai][0][m][0] * rs, g1 = acc[ai][0][m][1] * rs, u0 = acc[ai][1][m][0] * rs, u1 = acc[ai][1][m][1] * rs;
;                 u32x4 w; w.x = pk(silu_f(g0[0]) * u0[0], silu_f(g0[1]) * u0[1]); w.y = pk(silu_f(g0[2]) * u0[2], silu_f(g0[3]) * u0[3]);
;                 w.z = pk(silu_f(g1[0]) * u1[0], silu_f(g1[1]) * u1[1]); w.w = pk(silu_f(g1[2]) * u1[2], silu_f(g1[3]) * u1[3]);
;                 *(u32x4*)(H + (size_t)row * DFF + col0) = w; }
	v_rcp_f32_e32 v216, v216
	v_rcp_f32_e32 v217, v217
	v_rcp_f32_e32 v218, v218
	v_rcp_f32_e32 v219, v219
	v_rcp_f32_e32 v220, v220
	v_rcp_f32_e32 v221, v221
	v_mad_i64_i32 v[228:229], s[8:9], v150, s20, v[212:213]
	v_pk_mul_f32 v[188:189], v[62:63], v[188:189]
	v_pk_mul_f32 v[216:217], v[64:65], v[216:217]
	v_pk_mul_f32 v[218:219], v[58:59], v[218:219]
	v_pk_mul_f32 v[220:221], v[60:61], v[220:221]
	v_lshl_add_u64 v[228:229], v[228:229], 0, v[214:215]
	v_pk_mul_f32 v[54:55], v[54:55], v[188:189]
	v_pk_mul_f32 v[56:57], v[56:57], v[216:217]
	v_pk_mul_f32 v[50:51], v[50:51], v[218:219]
	v_pk_mul_f32 v[52:53], v[52:53], v[220:221]
	s_nop 0
	v_cvt_pk_bf16_f32 v62, v54, v55
	v_cvt_pk_bf16_f32 v63, v56, v57
	v_cvt_pk_bf16_f32 v64, v50, v51
	v_cvt_pk_bf16_f32 v65, v52, v53
	global_store_dwordx4 v[228:229], v[62:65], off
	v_pk_mul_f32 v[46:47], v[46:47], v[190:191] op_sel_hi:[1,0]
	v_pk_mul_f32 v[48:49], v[48:49], v[190:191] op_sel_hi:[1,0]
	v_pk_mul_f32 v[42:43], v[42:43], v[190:191] op_sel_hi:[1,0]
	v_pk_mul_f32 v[44:45], v[44:45], v[190:191] op_sel_hi:[1,0]
	v_pk_mul_f32 v[38:39], v[38:39], v[190:191] op_sel_hi:[1,0]
	v_pk_mul_f32 v[40:41], v[40:41], v[190:191] op_sel_hi:[1,0]
	v_pk_mul_f32 v[34:35], v[34:35], v[190:191] op_sel_hi:[1,0]
	v_pk_mul_f32 v[36:37], v[36:37], v[190:191] op_sel_hi:[1,0]
	v_mul_f32_e32 v192, 0xbfb8aa3b, v46
	v_mul_f32_e32 v193, 0xbfb8aa3b, v47
	v_mul_f32_e32 v216, 0xbfb8aa3b, v48
	v_mul_f32_e32 v217, 0xbfb8aa3b, v49
	v_mul_f32_e32 v218, 0xbfb8aa3b, v42
	v_mul_f32_e32 v219, 0xbfb8aa3b, v43
	v_mul_f32_e32 v220, 0xbfb8aa3b, v44
	v_mul_f32_e32 v221, 0xbfb8aa3b, v45
	v_exp_f32_e32 v192, v192
	v_exp_f32_e32 v193, v193
	v_exp_f32_e32 v216, v216
	v_exp_f32_e32 v217, v217
	v_exp_f32_e32 v218, v218
	v_exp_f32_e32 v219, v219
	v_exp_f32_e32 v220, v220
	v_exp_f32_e32 v221, v221
	v_add_f32_e32 v192, 1.0, v192
	v_add_f32_e32 v193, 1.0, v193
	v_add_f32_e32 v216, 1.0, v216
	v_add_f32_e32 v217, 1.0, v217
	v_add_f32_e32 v218, 1.0, v218
	v_add_f32_e32 v219, 1.0, v219
	v_add_f32_e32 v220, 1.0, v220
	v_add_f32_e32 v221, 1.0, v221
	v_rcp_f32_e32 v192, v192
	v_rcp_f32_e32 v193, v193
	v_rcp_f32_e32 v216, v216
	v_rcp_f32_e32 v217, v217
	v_rcp_f32_e32 v218, v218
	v_rcp_f32_e32 v219, v219
	v_rcp_f32_e32 v220, v220
	v_rcp_f32_e32 v221, v221
	v_mad_i64_i32 v[228:229], s[8:9], v146, s20, v[212:213]
	v_pk_mul_f32 v[192:193], v[46:47], v[192:193]
	v_pk_mul_f32 v[216:217], v[48:49], v[216:217]
	v_pk_mul_f32 v[218:219], v[42:43], v[218:219]
	v_pk_mul_f32 v[220:221], v[44:45], v[220:221]
	v_lshl_add_u64 v[228:229], v[228:229], 0, v[214:215]
	v_pk_mul_f32 v[38:39], v[38:39], v[192:193]
	v_pk_mul_f32 v[40:41], v[40:41], v[216:217]
	v_pk_mul_f32 v[34:35], v[34:35], v[218:219]
	v_pk_mul_f32 v[36:37], v[36:37], v[220:221]
	s_nop 0
	v_cvt_pk_bf16_f32 v46, v38, v39
	v_cvt_pk_bf16_f32 v47, v40, v41
	v_cvt_pk_bf16_f32 v48, v34, v35
	v_cvt_pk_bf16_f32 v49, v36, v37
	global_store_dwordx4 v[228:229], v[46:49], off
	v_pk_mul_f32 v[30:31], v[30:31], v[204:205] op_sel_hi:[1,0]
	v_pk_mul_f32 v[32:33], v[32:33], v[204:205] op_sel_hi:[1,0]
	v_pk_mul_f32 v[26:27], v[26:27], v[204:205] op_sel_hi:[1,0]
	v_pk_mul_f32 v[28:29], v[28:29], v[204:205] op_sel_hi:[1,0]
	v_pk_mul_f32 v[22:23], v[22:23], v[204:205] op_sel_hi:[1,0]
	v_pk_mul_f32 v[24:25], v[24:25], v[204:205] op_sel_hi:[1,0]
	v_pk_mul_f32 v[18:19], v[18:19], v[204:205] op_sel_hi:[1,0]
	v_pk_mul_f32 v[20:21], v[20:21], v[204:205] op_sel_hi:[1,0]
	v_mul_f32_e32 v206, 0xbfb8aa3b, v30
	v_mul_f32_e32 v207, 0xbfb8aa3b, v31
	v_mul_f32_e32 v216, 0xbfb8aa3b, v32
	v_mul_f32_e32 v217, 0xbfb8aa3b, v33
	v_mul_f32_e32 v218, 0xbfb8aa3b, v26
	v_mul_f32_e32 v219, 0xbfb8aa3b, v27
; __device__ __forceinline__ unsigned pk(float lo, float hi) { f32x2v v = {lo, hi}; bf16x2v b = __builtin_convertvector(v, bf16x2v); return __builtin_bit_cast(unsigned, b); }
; __device__ __forceinline__ float silu_f(float x) { return x * __builtin_amdgcn_rcpf(1.0f + __builtin_amdgcn_exp2f(-1.4426950408889634f * x)); }
;     __device__ __forceinline__ void operator()(const f32x4 (&acc)[2][2][4][2], const Unit& u, int wr, int wc, int fr, int fq) const {
;     ...
;         for (int ai = 0; ai < 2; ++ai)
; #pragma unroll
;             for (int m = 0; m < 4; ++m) { const int row = row0 + ai * HALF + m * 16; const float rs = rsv[ai][m];
;                 const f32x4 g0 = acc[ai][0][m][0] * rs, g1 = acc[ai][0][m][1] * rs, u0 = acc[ai][1][m][0] * rs, u1 = acc[ai][1][m][1] * rs;
;                 u32x4 w; w.x = pk(silu_f(g0[0]) * u0[0], silu_f(g0[1]) * u0[1]); w.y = pk(silu_f(g0[2]) * u0[2], silu_f(g0[3]) * u0[3]);
;                 w.z = pk(silu_f(g1[0]) * u1[0], silu_f(g1[1]) * u1[1]); w.w = pk(silu_f(g1[2]) * u1[2], silu_f(g1[3]) * u1[3]);
;                 *(u32x4*)(H + (size_t)row * DFF + col0) = w; }
	v_mul_f32_e32 v220, 0xbfb8aa3b, v28
	v_mul_f32_e32 v221, 0xbfb8aa3b, v29
	v_exp_f32_e32 v206, v206
	v_exp_f32_e32 v207, v207
	v_exp_f32_e32 v216, v216
	v_exp_f32_e32 v217, v217
	v_exp_f32_e32 v218, v218
	v_exp_f32_e32 v219, v219
	v_exp_f32_e32 v220, v220
	v_exp_f32_e32 v221, v221
	v_add_f32_e32 v206, 1.0, v206
	v_add_f32_e32 v207, 1.0, v207
	v_add_f32_e32 v216, 1.0, v216
	v_add_f32_e32 v217, 1.0, v217
	v_add_f32_e32 v218, 1.0, v218
	v_add_f32_e32 v219, 1.0, v219
	v_add_f32_e32 v220, 1.0, v220
	v_add_f32_e32 v221, 1.0, v221
	v_rcp_f32_e32 v206, v206
	v_rcp_f32_e32 v207, v207
	v_rcp_f32_e32 v216, v216
	v_rcp_f32_e32 v217, v217
	v_rcp_f32_e32 v218, v218
	v_rcp_f32_e32 v219, v219
	v_rcp_f32_e32 v220, v220
	v_rcp_f32_e32 v221, v221
	v_mad_i64_i32 v[228:229], s[8:9], v142, s20, v[212:213]
	v_pk_mul_f32 v[206:207], v[30:31], v[206:207]
	v_pk_mul_f32 v[216:217], v[32:33], v[216:217]
	v_pk_mul_f32 v[218:219], v[26:27], v[218:219]
	v_pk_mul_f32 v[220:221], v[28:29], v[220:221]
	v_lshl_add_u64 v[228:229], v[228:229], 0, v[214:215]
	v_pk_mul_f32 v[22:23], v[22:23], v[206:207]
	v_pk_mul_f32 v[24:25], v[24:25], v[216:217]
	v_pk_mul_f32 v[18:19], v[18:19], v[218:219]
	v_pk_mul_f32 v[20:21], v[20:21], v[220:221]
	s_nop 0
	v_cvt_pk_bf16_f32 v30, v22, v23
	v_cvt_pk_bf16_f32 v31, v24, v25
	v_cvt_pk_bf16_f32 v32, v18, v19
	v_cvt_pk_bf16_f32 v33, v20, v21
	global_store_dwordx4 v[228:229], v[30:33], off
	v_pk_mul_f32 v[14:15], v[14:15], v[208:209] op_sel_hi:[1,0]
	v_pk_mul_f32 v[16:17], v[16:17], v[208:209] op_sel_hi:[1,0]
	v_pk_mul_f32 v[10:11], v[10:11], v[208:209] op_sel_hi:[1,0]
	v_pk_mul_f32 v[12:13], v[12:13], v[208:209] op_sel_hi:[1,0]
	v_pk_mul_f32 v[6:7], v[6:7], v[208:209] op_sel_hi:[1,0]
	v_pk_mul_f32 v[8:9], v[8:9], v[208:209] op_sel_hi:[1,0]
	v_pk_mul_f32 v[2:3], v[2:3], v[208:209] op_sel_hi:[1,0]
	v_pk_mul_f32 v[4:5], v[4:5], v[208:209] op_sel_hi:[1,0]
	v_mul_f32_e32 v210, 0xbfb8aa3b, v14
	v_mul_f32_e32 v211, 0xbfb8aa3b, v15
	v_mul_f32_e32 v216, 0xbfb8aa3b, v16
	v_mul_f32_e32 v217, 0xbfb8aa3b, v17
	v_mul_f32_e32 v218, 0xbfb8aa3b, v10
	v_mul_f32_e32 v219, 0xbfb8aa3b, v11
	v_mul_f32_e32 v220, 0xbfb8aa3b, v12
	v_mul_f32_e32 v221, 0xbfb8aa3b, v13
	v_exp_f32_e32 v210, v210
	v_exp_f32_e32 v211, v211
	v_exp_f32_e32 v216, v216
	v_exp_f32_e32 v217, v217
	v_exp_f32_e32 v218, v218
	v_exp_f32_e32 v219, v219
	v_exp_f32_e32 v220, v220
	v_exp_f32_e32 v221, v221
	v_add_f32_e32 v210, 1.0, v210
	v_add_f32_e32 v211, 1.0, v211
	v_add_f32_e32 v216, 1.0, v216
	v_add_f32_e32 v217, 1.0, v217
	v_add_f32_e32 v218, 1.0, v218
	v_add_f32_e32 v219, 1.0, v219
	v_add_f32_e32 v220, 1.0, v220
	v_add_f32_e32 v221, 1.0, v221
	v_rcp_f32_e32 v210, v210
	v_rcp_f32_e32 v211, v211
	v_rcp_f32_e32 v216, v216
	v_rcp_f32_e32 v217, v217
	v_rcp_f32_e32 v218, v218
	v_rcp_f32_e32 v219, v219
	v_rcp_f32_e32 v220, v220
	v_rcp_f32_e32 v221, v221
	v_mad_i64_i32 v[228:229], s[8:9], v140, s20, v[212:213]
	v_pk_mul_f32 v[210:211], v[14:15], v[210:211]
	v_pk_mul_f32 v[216:217], v[16:17], v[216:217]
	v_pk_mul_f32 v[218:219], v[10:11], v[218:219]
	v_pk_mul_f32 v[220:221], v[12:13], v[220:221]
	v_lshl_add_u64 v[228:229], v[228:229], 0, v[214:215]
	v_pk_mul_f32 v[6:7], v[6:7], v[210:211]
	v_pk_mul_f32 v[8:9], v[8:9], v[216:217]
	v_pk_mul_f32 v[2:3], v[2:3], v[218:219]
	v_pk_mul_f32 v[4:5], v[4:5], v[220:221]
	s_nop 0
	v_cvt_pk_bf16_f32 v14, v6, v7
	v_cvt_pk_bf16_f32 v15, v8, v9
	v_cvt_pk_bf16_f32 v16, v2, v3
	v_cvt_pk_bf16_f32 v17, v4, v5
	global_store_dwordx4 v[228:229], v[14:17], off
	s_mov_b64 s[8:9], -1
	s_cbranch_vccnz .LBB0_313
	s_andn2_b64 vcc, exec, s[4:5]
	s_cbranch_vccnz .LBB0_312
	s_barrier
	s_branch .LBB0_312

; #define PG8_STAGE(bufoff, gbase, voff) do { _Pragma("unroll") for (int _i = 0; _i < 2; ++_i) \
;         __builtin_amdgcn_global_load_lds((const unsigned*)((const char*)(gbase) + (voff)[_i]), (PG8_LAS unsigned*)(lds + (bufoff) + ldsw + _i * 8192), 16, 0, 0); } while (0)
; #define PG8_LDA(dst, b, h) do { _Pragma("unroll") for (int m = 0; m < 4; ++m) _Pragma("unroll") for (int k = 0; k < 2; ++k) dst[m][k] = *(const PG8_LAS bf16x8*)(lds + PG8_SA(b, h) + aoff + m * 2048 + k * 1024); } while (0)
; #define PG8_LDB(dst, b, h) do { _Pragma("unroll") for (int n = 0; n < 2; ++n) _Pragma("unroll") for (int k = 0; k < 2; ++k) dst[n][k] = *(const PG8_LAS bf16x8*)(lds + PG8_SB(b, h) + boff + n * 2048 + k * 1024); } while (0)
; #define PG8_MMA(ai, bj, At, Bt) do { __builtin_amdgcn_s_setprio(1); _Pragma("unroll") for (int m = 0; m < 4; ++m) _Pragma("unroll") for (int n = 0; n < 2; ++n) _Pragma("unroll") for (int k = 0; k < 2; ++k) \
;         acc[ai][bj][m][n] = __builtin_amdgcn_mfma_f32_16x16x32_bf16(Bt[n][k], At[m][k], acc[ai][bj][m][n], 0, 0, 0); __builtin_amdgcn_s_setprio(0); } while (0)
; #define PG8_WAIT_V(n) asm volatile("s_waitcnt vmcnt(" #n ")" ::: "memory")
; #define PG8_BAR __builtin_amdgcn_s_barrier()
; template <class Epi, class Sched, bool ALIGN_EPI = false, bool SP2 = false>
; __device__ __forceinline__ void gemm_phase(PG8_LAS unsigned char* lds, const Gemm g, const Sched& S, const Epi& E) {
;     ...
;         for (int t = 0; t < nt; t += 2) {
;             const bool last = (t == nt - 2);
;             const char* a1 = cA + (size_t)(t + 1) * kstep;
;             const char* a2 = last ? nA : cA + (size_t)(t + 2) * kstep; const char* b2 = last ? nB : cB + (size_t)(t + 2) * kstep;
;             const char* a3 = a2 + kstep; const char* b3 = b2 + kstep;
;             if (last && has_next) S.a_ready(nxt);
;             if constexpr (SP2) {
;             PG8_LDB(B0, 0, 0); PG8_LDB(B1, 0, 1); PG8_SCHED; PG8_LDA(At, 0, 0); PG8_STAGE(PG8_SA(1, 1), a1 + hstep, voffA);
;             PG8_WAIT_V(8); PG8_WAIT_L(0); PG8_BAR; PG8_MMA(0, 0, At, B0); PG8_MMA(0, 1, At, B1); PG8_BAR; PG8_SCHED;
;             PG8_LDA(At, 0, 1); PG8_STAGE(PG8_SB(0, 0), b2, voffB); PG8_STAGE(PG8_SB(0, 1), b2 + hstep, voffB); PG8_STAGE(PG8_SA(0, 0), a2, voffA);
;             PG8_WAIT_V(8); PG8_WAIT_L(0); PG8_BAR; PG8_MMA(1, 0, At, B0); PG8_MMA(1, 1, At, B1); PG8_BAR; PG8_SCHED;
.LBB0_390:
	s_add_u32 s20, s8, 0x100
	s_addc_u32 s21, s9, 0
	s_add_i32 s37, 0, 0x10000
	s_cmp_eq_u32 s57, 40
	s_cselect_b32 s51, s45, s21
	s_cselect_b32 s50, s44, s20
	s_cselect_b32 s49, s47, s56
	s_cselect_b32 s48, s46, s55
	s_add_i32 s58, 0, 0x14000
	v_add_u32_e32 v152, s37, v157
	v_add_u32_e32 v163, s58, v157
	ds_read_b128 v[130:133], v152
	ds_read_b128 v[134:137], v152 offset:1024
	ds_read_b128 v[148:151], v152 offset:2048
	ds_read_b128 v[152:155], v152 offset:3072
	ds_read_b128 v[164:167], v163
	ds_read_b128 v[168:171], v163 offset:1024
	ds_read_b128 v[172:175], v163 offset:2048
	ds_read_b128 v[176:179], v163 offset:3072
	v_lshl_add_u64 v[192:193], s[8:9], 0, v[144:145]
	s_add_i32 m0, s18, 0xc000
	ds_read_b128 v[180:183], v161
	ds_read_b128 v[184:187], v161 offset:1024
	ds_read_b128 v[188:191], v161 offset:2048
	ds_read_b128 v[204:207], v161 offset:3072
	ds_read_b128 v[208:211], v161 offset:4096
	ds_read_b128 v[212:215], v161 offset:5120
	ds_read_b128 v[216:219], v161 offset:6144
	ds_read_b128 v[220:223], v161 offset:7168
	global_load_lds_dwordx4 v[192:193], off
	v_lshl_add_u64 v[192:193], s[8:9], 0, v[146:147]
	s_add_i32 m0, s18, 0xe000
	s_nop 0
	global_load_lds_dwordx4 v[192:193], off
	s_waitcnt vmcnt(8)
	s_waitcnt lgkmcnt(0)
	s_barrier
	s_setprio 1
	s_waitcnt lgkmcnt(0)
	v_mfma_f32_16x16x32_bf16 v[126:129], v[130:133], v[180:183], v[126:129]
	v_mfma_f32_16x16x32_bf16 v[122:125], v[148:151], v[180:183], v[122:125]
	v_mfma_f32_16x16x32_bf16 v[110:113], v[130:133], v[188:191], v[110:113]
	v_mfma_f32_16x16x32_bf16 v[106:109], v[148:151], v[188:191], v[106:109]
	v_mfma_f32_16x16x32_bf16 v[94:97], v[130:133], v[208:211], v[94:97]
	v_mfma_f32_16x16x32_bf16 v[90:93], v[148:151], v[208:211], v[90:93]
	v_mfma_f32_16x16x32_bf16 v[78:81], v[130:133], v[216:219], v[78:81]
	v_mfma_f32_16x16x32_bf16 v[74:77], v[148:151], v[216:219], v[74:77]
	v_mfma_f32_16x16x32_bf16 v[126:129], v[134:137], v[184:187], v[126:129]
	v_mfma_f32_16x16x32_bf16 v[122:125], v[152:155], v[184:187], v[122:125]
	v_mfma_f32_16x16x32_bf16 v[110:113], v[134:137], v[204:207], v[110:113]
	v_mfma_f32_16x16x32_bf16 v[106:109], v[152:155], v[204:207], v[106:109]
	v_mfma_f32_16x16x32_bf16 v[94:97], v[134:137], v[212:215], v[94:97]
	v_mfma_f32_16x16x32_bf16 v[90:93], v[152:155], v[212:215], v[90:93]
	v_mfma_f32_16x16x32_bf16 v[78:81], v[134:137], v[220:223], v[78:81]
	v_mfma_f32_16x16x32_bf16 v[74:77], v[152:155], v[220:223], v[74:77]
	s_setprio 0
	s_setprio 1
	v_mfma_f32_16x16x32_bf16 v[118:121], v[164:167], v[180:183], v[118:121]
	v_mfma_f32_16x16x32_bf16 v[114:117], v[172:175], v[180:183], v[114:117]
	v_mfma_f32_16x16x32_bf16 v[102:105], v[164:167], v[188:191], v[102:105]
	v_mfma_f32_16x16x32_bf16 v[98:101], v[172:175], v[188:191], v[98:101]
	v_mfma_f32_16x16x32_bf16 v[86:89], v[164:167], v[208:211], v[86:89]
	v_mfma_f32_16x16x32_bf16 v[82:85], v[172:175], v[208:211], v[82:85]
	v_mfma_f32_16x16x32_bf16 v[70:73], v[164:167], v[216:219], v[70:73]
	v_mfma_f32_16x16x32_bf16 v[66:69], v[172:175], v[216:219], v[66:69]
	v_mfma_f32_16x16x32_bf16 v[118:121], v[168:171], v[184:187], v[118:121]
	v_mfma_f32_16x16x32_bf16 v[114:117], v[176:179], v[184:187], v[114:117]
	v_mfma_f32_16x16x32_bf16 v[102:105], v[168:171], v[204:207], v[102:105]
	v_mfma_f32_16x16x32_bf16 v[98:101], v[176:179], v[204:207], v[98:101]
	v_mfma_f32_16x16x32_bf16 v[86:89], v[168:171], v[212:215], v[86:89]
	v_mfma_f32_16x16x32_bf16 v[82:85], v[176:179], v[212:215], v[82:85]
	v_mfma_f32_16x16x32_bf16 v[70:73], v[168:171], v[220:223], v[70:73]
	v_mfma_f32_16x16x32_bf16 v[66:69], v[176:179], v[220:223], v[66:69]
	s_setprio 0
	s_barrier
	s_add_i32 s8, s37, s16
	v_lshl_add_u64 v[192:193], s[48:49], 0, v[0:1]
	s_mov_b32 m0, s8
	ds_read_b128 v[180:183], v161 offset:16384
	global_load_lds_dwordx4 v[192:193], off
	ds_read_b128 v[184:187], v161 offset:17408
	ds_read_b128 v[188:191], v161 offset:18432
	s_add_i32 m0, s8, 0x2000
	s_add_u32 s8, s48, 0xb0000
	v_lshl_add_u64 v[224:225], s[48:49], 0, v[138:139]
	s_addc_u32 s9, s49, 0
	s_add_i32 s37, s58, s16
	global_load_lds_dwordx4 v[224:225], off
	ds_read_b128 v[204:207], v161 offset:19456
	ds_read_b128 v[208:211], v161 offset:20480
	v_lshl_add_u64 v[226:227], s[8:9], 0, v[0:1]
	s_mov_b32 m0, s37
	v_lshl_add_u64 v[228:229], s[50:51], 0, v[140:141]
	global_load_lds_dwordx4 v[226:227], off
	ds_read_b128 v[212:215], v161 offset:21504
	ds_read_b128 v[216:219], v161 offset:22528
	v_lshl_add_u64 v[226:227], s[8:9], 0, v[138:139]
	s_add_i32 m0, s37, 0x2000
	s_nop 0
	global_load_lds_dwordx4 v[226:227], off
	ds_read_b128 v[220:223], v161 offset:23552
	v_lshl_add_u64 v[226:227], s[50:51], 0, v[142:143]
	s_mov_b32 m0, s18
	s_nop 0
	global_load_lds_dwordx4 v[226:227], off
	s_mov_b32 m0, s19
	s_nop 0
	global_load_lds_dwordx4 v[228:229], off
	s_waitcnt vmcnt(8)
	s_waitcnt lgkmcnt(0)
	s_barrier
; #define PG8_STAGE(bufoff, gbase, voff) do { _Pragma("unroll") for (int _i = 0; _i < 2; ++_i) \
;         __builtin_amdgcn_global_load_lds((const unsigned*)((const char*)(gbase) + (voff)[_i]), (PG8_LAS unsigned*)(lds + (bufoff) + ldsw + _i * 8192), 16, 0, 0); } while (0)
; #define PG8_LDA(dst, b, h) do { _Pragma("unroll") for (int m = 0; m < 4; ++m) _Pragma("unroll") for (int k = 0; k < 2; ++k) dst[m][k] = *(const PG8_LAS bf16x8*)(lds + PG8_SA(b, h) + aoff + m * 2048 + k * 1024); } while (0)
; #define PG8_LDB(dst, b, h) do { _Pragma("unroll") for (int n = 0; n < 2; ++n) _Pragma("unroll") for (int k = 0; k < 2; ++k) dst[n][k] = *(const PG8_LAS bf16x8*)(lds + PG8_SB(b, h) + boff + n * 2048 + k * 1024); } while (0)
; #define PG8_MMA(ai, bj, At, Bt) do { __builtin_amdgcn_s_setprio(1); _Pragma("unroll") for (int m = 0; m < 4; ++m) _Pragma("unroll") for (int n = 0; n < 2; ++n) _Pragma("unroll") for (int k = 0; k < 2; ++k) \
;         acc[ai][bj][m][n] = __builtin_amdgcn_mfma_f32_16x16x32_bf16(Bt[n][k], At[m][k], acc[ai][bj][m][n], 0, 0, 0); __builtin_amdgcn_s_setprio(0); } while (0)
; #define PG8_WAIT_V(n) asm volatile("s_waitcnt vmcnt(" #n ")" ::: "memory")
; #define PG8_WAIT_L(n) asm volatile("s_waitcnt lgkmcnt(" #n ")" ::: "memory")
; #define PG8_BAR __builtin_amdgcn_s_barrier()
; #define PG8_SCHED __builtin_amdgcn_sched_barrier(0)
; template <class Epi, class Sched, bool ALIGN_EPI = false, bool SP2 = false>
; __device__ __forceinline__ void gemm_phase(PG8_LAS unsigned char* lds, const Gemm g, const Sched& S, const Epi& E) {
;     ...
;             PG8_WAIT_V(8); PG8_WAIT_L(0); PG8_BAR; PG8_MMA(1, 0, At, B0); PG8_MMA(1, 1, At, B1); PG8_BAR; PG8_SCHED;
;             PG8_LDB(B0, 1, 0); PG8_LDB(B1, 1, 1); PG8_SCHED; PG8_LDA(At, 1, 0); PG8_STAGE(PG8_SA(0, 1), a2 + hstep, voffA);
;             PG8_WAIT_V(8); PG8_WAIT_L(0); PG8_BAR; PG8_MMA(0, 0, At, B0); PG8_MMA(0, 1, At, B1); PG8_BAR; PG8_SCHED;
;             PG8_LDA(At, 1, 1); PG8_STAGE(PG8_SB(1, 0), b3, voffB); PG8_STAGE(PG8_SB(1, 1), b3 + hstep, voffB); PG8_STAGE(PG8_SA(1, 0), a3, voffA);
	s_setprio 1
	s_waitcnt lgkmcnt(0)
	v_mfma_f32_16x16x32_bf16 v[62:65], v[130:133], v[180:183], v[62:65]
	v_mfma_f32_16x16x32_bf16 v[58:61], v[148:151], v[180:183], v[58:61]
	v_mfma_f32_16x16x32_bf16 v[46:49], v[130:133], v[188:191], v[46:49]
	v_mfma_f32_16x16x32_bf16 v[42:45], v[148:151], v[188:191], v[42:45]
	v_mfma_f32_16x16x32_bf16 v[30:33], v[130:133], v[208:211], v[30:33]
	v_mfma_f32_16x16x32_bf16 v[26:29], v[148:151], v[208:211], v[26:29]
	v_mfma_f32_16x16x32_bf16 v[14:17], v[130:133], v[216:219], v[14:17]
	v_mfma_f32_16x16x32_bf16 v[10:13], v[148:151], v[216:219], v[10:13]
	v_mfma_f32_16x16x32_bf16 v[62:65], v[134:137], v[184:187], v[62:65]
	v_mfma_f32_16x16x32_bf16 v[58:61], v[152:155], v[184:187], v[58:61]
	v_mfma_f32_16x16x32_bf16 v[46:49], v[134:137], v[204:207], v[46:49]
	v_mfma_f32_16x16x32_bf16 v[42:45], v[152:155], v[204:207], v[42:45]
	v_mfma_f32_16x16x32_bf16 v[30:33], v[134:137], v[212:215], v[30:33]
	v_mfma_f32_16x16x32_bf16 v[26:29], v[152:155], v[212:215], v[26:29]
	v_mfma_f32_16x16x32_bf16 v[14:17], v[134:137], v[220:223], v[14:17]
	v_mfma_f32_16x16x32_bf16 v[10:13], v[152:155], v[220:223], v[10:13]
	s_setprio 0
	s_setprio 1
	v_mfma_f32_16x16x32_bf16 v[54:57], v[164:167], v[180:183], v[54:57]
	v_mfma_f32_16x16x32_bf16 v[50:53], v[172:175], v[180:183], v[50:53]
	v_mfma_f32_16x16x32_bf16 v[38:41], v[164:167], v[188:191], v[38:41]
	v_mfma_f32_16x16x32_bf16 v[34:37], v[172:175], v[188:191], v[34:37]
	v_mfma_f32_16x16x32_bf16 v[22:25], v[164:167], v[208:211], v[22:25]
	v_mfma_f32_16x16x32_bf16 v[18:21], v[172:175], v[208:211], v[18:21]
	v_mfma_f32_16x16x32_bf16 v[6:9], v[164:167], v[216:219], v[6:9]
	v_mfma_f32_16x16x32_bf16 v[2:5], v[172:175], v[216:219], v[2:5]
	v_mfma_f32_16x16x32_bf16 v[54:57], v[168:171], v[184:187], v[54:57]
	v_mfma_f32_16x16x32_bf16 v[50:53], v[176:179], v[184:187], v[50:53]
	v_mfma_f32_16x16x32_bf16 v[38:41], v[168:171], v[204:207], v[38:41]
	v_mfma_f32_16x16x32_bf16 v[34:37], v[176:179], v[204:207], v[34:37]
	v_mfma_f32_16x16x32_bf16 v[22:25], v[168:171], v[212:215], v[22:25]
	v_mfma_f32_16x16x32_bf16 v[18:21], v[176:179], v[212:215], v[18:21]
	v_mfma_f32_16x16x32_bf16 v[6:9], v[168:171], v[220:223], v[6:9]
	v_mfma_f32_16x16x32_bf16 v[2:5], v[176:179], v[220:223], v[2:5]
	s_setprio 0
	s_barrier
	s_add_i32 s37, 0, 0x18000
	s_add_i32 s58, 0, 0x1c000
	v_add_u32_e32 v152, s37, v157
	v_add_u32_e32 v163, s58, v157
	ds_read_b128 v[130:133], v152
	ds_read_b128 v[134:137], v152 offset:1024
	ds_read_b128 v[148:151], v152 offset:2048
	ds_read_b128 v[152:155], v152 offset:3072
	ds_read_b128 v[164:167], v163
	ds_read_b128 v[168:171], v163 offset:1024
	ds_read_b128 v[172:175], v163 offset:2048
	ds_read_b128 v[176:179], v163 offset:3072
	s_add_u32 s8, s50, 0xb0000
	s_addc_u32 s9, s51, 0
	s_mov_b32 m0, s33
	v_lshl_add_u64 v[230:231], s[8:9], 0, v[142:143]
	ds_read_b128 v[180:183], v161 offset:32768
	ds_read_b128 v[184:187], v161 offset:33792
	ds_read_b128 v[188:191], v161 offset:34816
	ds_read_b128 v[204:207], v161 offset:35840
	ds_read_b128 v[208:211], v161 offset:36864
	ds_read_b128 v[212:215], v161 offset:37888
	ds_read_b128 v[216:219], v161 offset:38912
	ds_read_b128 v[220:223], v161 offset:39936
	global_load_lds_dwordx4 v[230:231], off
	v_lshl_add_u64 v[230:231], s[8:9], 0, v[140:141]
	s_mov_b32 m0, s34
	s_nop 0
	global_load_lds_dwordx4 v[230:231], off
	s_waitcnt vmcnt(8)
	s_waitcnt lgkmcnt(0)
	s_barrier
	s_setprio 1
	s_waitcnt lgkmcnt(0)
	v_mfma_f32_16x16x32_bf16 v[126:129], v[130:133], v[180:183], v[126:129]
	v_mfma_f32_16x16x32_bf16 v[122:125], v[148:151], v[180:183], v[122:125]
	v_mfma_f32_16x16x32_bf16 v[110:113], v[130:133], v[188:191], v[110:113]
	v_mfma_f32_16x16x32_bf16 v[106:109], v[148:151], v[188:191], v[106:109]
	v_mfma_f32_16x16x32_bf16 v[94:97], v[130:133], v[208:211], v[94:97]
	v_mfma_f32_16x16x32_bf16 v[90:93], v[148:151], v[208:211], v[90:93]
	v_mfma_f32_16x16x32_bf16 v[78:81], v[130:133], v[216:219], v[78:81]
	v_mfma_f32_16x16x32_bf16 v[74:77], v[148:151], v[216:219], v[74:77]
	v_mfma_f32_16x16x32_bf16 v[126:129], v[134:137], v[184:187], v[126:129]
	v_mfma_f32_16x16x32_bf16 v[122:125], v[152:155], v[184:187], v[122:125]
	v_mfma_f32_16x16x32_bf16 v[110:113], v[134:137], v[204:207], v[110:113]
	v_mfma_f32_16x16x32_bf16 v[106:109], v[152:155], v[204:207], v[106:109]
	v_mfma_f32_16x16x32_bf16 v[94:97], v[134:137], v[212:215], v[94:97]
	v_mfma_f32_16x16x32_bf16 v[90:93], v[152:155], v[212:215], v[90:93]
	v_mfma_f32_16x16x32_bf16 v[78:81], v[134:137], v[220:223], v[78:81]
	v_mfma_f32_16x16x32_bf16 v[74:77], v[152:155], v[220:223], v[74:77]
	s_setprio 0
	s_setprio 1
	v_mfma_f32_16x16x32_bf16 v[118:121], v[164:167], v[180:183], v[118:121]
	v_mfma_f32_16x16x32_bf16 v[114:117], v[172:175], v[180:183], v[114:117]
	v_mfma_f32_16x16x32_bf16 v[102:105], v[164:167], v[188:191], v[102:105]
	v_mfma_f32_16x16x32_bf16 v[98:101], v[172:175], v[188:191], v[98:101]
	v_mfma_f32_16x16x32_bf16 v[86:89], v[164:167], v[208:211], v[86:89]
	v_mfma_f32_16x16x32_bf16 v[82:85], v[172:175], v[208:211], v[82:85]
	v_mfma_f32_16x16x32_bf16 v[70:73], v[164:167], v[216:219], v[70:73]
	v_mfma_f32_16x16x32_bf16 v[66:69], v[172:175], v[216:219], v[66:69]
	v_mfma_f32_16x16x32_bf16 v[118:121], v[168:171], v[184:187], v[118:121]
	v_mfma_f32_16x16x32_bf16 v[114:117], v[176:179], v[184:187], v[114:117]
	v_mfma_f32_16x16x32_bf16 v[102:105], v[168:171], v[204:207], v[102:105]
	v_mfma_f32_16x16x32_bf16 v[98:101], v[176:179], v[204:207], v[98:101]
	v_mfma_f32_16x16x32_bf16 v[86:89], v[168:171], v[212:215], v[86:89]
	v_mfma_f32_16x16x32_bf16 v[82:85], v[176:179], v[212:215], v[82:85]
	v_mfma_f32_16x16x32_bf16 v[70:73], v[168:171], v[220:223], v[70:73]
	v_mfma_f32_16x16x32_bf16 v[66:69], v[176:179], v[220:223], v[66:69]
	s_setprio 0
	s_barrier
; #define PG8_STAGE(bufoff, gbase, voff) do { _Pragma("unroll") for (int _i = 0; _i < 2; ++_i) \
;         __builtin_amdgcn_global_load_lds((const unsigned*)((const char*)(gbase) + (voff)[_i]), (PG8_LAS unsigned*)(lds + (bufoff) + ldsw + _i * 8192), 16, 0, 0); } while (0)
; #define PG8_LDA(dst, b, h) do { _Pragma("unroll") for (int m = 0; m < 4; ++m) _Pragma("unroll") for (int k = 0; k < 2; ++k) dst[m][k] = *(const PG8_LAS bf16x8*)(lds + PG8_SA(b, h) + aoff + m * 2048 + k * 1024); } while (0)
; #define PG8_MMA(ai, bj, At, Bt) do { __builtin_amdgcn_s_setprio(1); _Pragma("unroll") for (int m = 0; m < 4; ++m) _Pragma("unroll") for (int n = 0; n < 2; ++n) _Pragma("unroll") for (int k = 0; k < 2; ++k) \
;         acc[ai][bj][m][n] = __builtin_amdgcn_mfma_f32_16x16x32_bf16(Bt[n][k], At[m][k], acc[ai][bj][m][n], 0, 0, 0); __builtin_amdgcn_s_setprio(0); } while (0)
; #define PG8_WAIT_V(n) asm volatile("s_waitcnt vmcnt(" #n ")" ::: "memory")
; #define PG8_WAIT_L(n) asm volatile("s_waitcnt lgkmcnt(" #n ")" ::: "memory")
; #define PG8_BAR __builtin_amdgcn_s_barrier()
; #define PG8_SCHED __builtin_amdgcn_sched_barrier(0)
; template <class Epi, class Sched, bool ALIGN_EPI = false, bool SP2 = false>
; __device__ __forceinline__ void gemm_phase(PG8_LAS unsigned char* lds, const Gemm g, const Sched& S, const Epi& E) {
;     ...
;             PG8_LDA(At, 1, 1); PG8_STAGE(PG8_SB(1, 0), b3, voffB); PG8_STAGE(PG8_SB(1, 1), b3 + hstep, voffB); PG8_STAGE(PG8_SA(1, 0), a3, voffA);
;             PG8_WAIT_V(8); PG8_WAIT_L(0); PG8_BAR; PG8_MMA(1, 0, At, B0); PG8_MMA(1, 1, At, B1); PG8_BAR; PG8_SCHED;
;     ...
;         if constexpr (ALIGN_EPI) { if (wr == 0) PG8_BAR; }
	s_add_i32 s8, s37, s16
	v_lshl_add_u64 v[192:193], v[192:193], 0, s[28:29]
	s_mov_b32 m0, s8
	ds_read_b128 v[180:183], v161 offset:49152
	global_load_lds_dwordx4 v[192:193], off
	ds_read_b128 v[184:187], v161 offset:50176
	ds_read_b128 v[188:191], v161 offset:51200
	s_add_i32 m0, s8, 0x2000
	s_add_u32 s8, s48, 0xb0080
	v_lshl_add_u64 v[192:193], v[224:225], 0, s[28:29]
	s_addc_u32 s9, s49, 0
	s_add_i32 s37, s58, s16
	global_load_lds_dwordx4 v[192:193], off
	ds_read_b128 v[204:207], v161 offset:52224
	ds_read_b128 v[208:211], v161 offset:53248
	v_lshl_add_u64 v[192:193], s[8:9], 0, v[0:1]
	s_mov_b32 m0, s37
	s_nop 0
	global_load_lds_dwordx4 v[192:193], off
	ds_read_b128 v[212:215], v161 offset:54272
	ds_read_b128 v[216:219], v161 offset:55296
	v_lshl_add_u64 v[192:193], s[8:9], 0, v[138:139]
	s_add_i32 m0, s37, 0x2000
	s_nop 0
	global_load_lds_dwordx4 v[192:193], off
	ds_read_b128 v[220:223], v161 offset:56320
	v_lshl_add_u64 v[192:193], v[226:227], 0, s[28:29]
	s_mov_b32 m0, s35
	s_nop 0
	global_load_lds_dwordx4 v[192:193], off
	v_lshl_add_u64 v[192:193], v[228:229], 0, s[28:29]
	s_mov_b32 m0, s36
	s_nop 0
	global_load_lds_dwordx4 v[192:193], off
	s_waitcnt vmcnt(8)
	s_waitcnt lgkmcnt(0)
	s_barrier
	s_setprio 1
	s_waitcnt lgkmcnt(0)
	v_mfma_f32_16x16x32_bf16 v[62:65], v[130:133], v[180:183], v[62:65]
	v_mfma_f32_16x16x32_bf16 v[58:61], v[148:151], v[180:183], v[58:61]
	v_mfma_f32_16x16x32_bf16 v[46:49], v[130:133], v[188:191], v[46:49]
	v_mfma_f32_16x16x32_bf16 v[42:45], v[148:151], v[188:191], v[42:45]
	v_mfma_f32_16x16x32_bf16 v[30:33], v[130:133], v[208:211], v[30:33]
	v_mfma_f32_16x16x32_bf16 v[26:29], v[148:151], v[208:211], v[26:29]
	v_mfma_f32_16x16x32_bf16 v[14:17], v[130:133], v[216:219], v[14:17]
	v_mfma_f32_16x16x32_bf16 v[10:13], v[148:151], v[216:219], v[10:13]
	v_mfma_f32_16x16x32_bf16 v[62:65], v[134:137], v[184:187], v[62:65]
	v_mfma_f32_16x16x32_bf16 v[58:61], v[152:155], v[184:187], v[58:61]
	v_mfma_f32_16x16x32_bf16 v[46:49], v[134:137], v[204:207], v[46:49]
	v_mfma_f32_16x16x32_bf16 v[42:45], v[152:155], v[204:207], v[42:45]
	v_mfma_f32_16x16x32_bf16 v[30:33], v[134:137], v[212:215], v[30:33]
	v_mfma_f32_16x16x32_bf16 v[26:29], v[152:155], v[212:215], v[26:29]
	v_mfma_f32_16x16x32_bf16 v[14:17], v[134:137], v[220:223], v[14:17]
	v_mfma_f32_16x16x32_bf16 v[10:13], v[152:155], v[220:223], v[10:13]
	s_setprio 0
	s_setprio 1
	v_mfma_f32_16x16x32_bf16 v[54:57], v[164:167], v[180:183], v[54:57]
	v_mfma_f32_16x16x32_bf16 v[50:53], v[172:175], v[180:183], v[50:53]
	v_mfma_f32_16x16x32_bf16 v[38:41], v[164:167], v[188:191], v[38:41]
	v_mfma_f32_16x16x32_bf16 v[34:37], v[172:175], v[188:191], v[34:37]
	v_mfma_f32_16x16x32_bf16 v[22:25], v[164:167], v[208:211], v[22:25]
	v_mfma_f32_16x16x32_bf16 v[18:21], v[172:175], v[208:211], v[18:21]
	v_mfma_f32_16x16x32_bf16 v[6:9], v[164:167], v[216:219], v[6:9]
	v_mfma_f32_16x16x32_bf16 v[2:5], v[172:175], v[216:219], v[2:5]
	v_mfma_f32_16x16x32_bf16 v[54:57], v[168:171], v[184:187], v[54:57]
	v_mfma_f32_16x16x32_bf16 v[50:53], v[176:179], v[184:187], v[50:53]
	v_mfma_f32_16x16x32_bf16 v[38:41], v[168:171], v[204:207], v[38:41]
	v_mfma_f32_16x16x32_bf16 v[34:37], v[176:179], v[204:207], v[34:37]
	v_mfma_f32_16x16x32_bf16 v[22:25], v[168:171], v[212:215], v[22:25]
	v_mfma_f32_16x16x32_bf16 v[18:21], v[176:179], v[212:215], v[18:21]
	v_mfma_f32_16x16x32_bf16 v[6:9], v[168:171], v[220:223], v[6:9]
	v_mfma_f32_16x16x32_bf16 v[2:5], v[176:179], v[220:223], v[2:5]
	s_setprio 0
	s_barrier
	s_add_i32 s57, s57, 2
	s_add_u32 s55, s55, 0x100
	s_addc_u32 s56, s56, 0
	s_cmp_gt_u32 s57, 41
	s_mov_b64 s[8:9], s[20:21]
	s_cbranch_scc0 .LBB0_390
	s_and_b64 vcc, exec, s[6:7]
	s_cbranch_vccz .LBB0_393
	s_barrier
; __device__ __forceinline__ unsigned pk(float lo, float hi) { f32x2v v = {lo, hi}; bf16x2v b = __builtin_convertvector(v, bf16x2v); return __builtin_bit_cast(unsigned, b); }
;     __device__ __forceinline__ void operator()(const f32x4 (&acc)[2][2][4][2], const Unit& u, int wr, int wc, int fr, int fq) const {
;     ...
; #pragma unroll
;         for (int ai = 0; ai < 2; ++ai)
; #pragma unroll
;           for (int mp = 0; mp < 2; ++mp) { u32x4 xv[2][2];
; #pragma unroll
;             for (int mm = 0; mm < 2; ++mm)
; #pragma unroll
;                 for (int bj = 0; bj < 2; ++bj) xv[mm][bj] = *(const u32x4*)(xb + (size_t)(row0 + ai * HALF + (2 * mp + mm) * 16) * DMODEL + col0 + bj * HALF);
; #pragma unroll
;             for (int mm = 0; mm < 2; ++mm) { const int m = 2 * mp + mm, row = row0 + ai * HALF + m * 16; float ss = 0.f;
; #pragma unroll
;                 for (int bj = 0; bj < 2; ++bj) { const u32x4 xr = xv[mm][bj];
;                     const f32x4 x0 = {__uint_as_float(xr.x << 16), __uint_as_float(xr.x & 0xffff0000u), __uint_as_float(xr.y << 16), __uint_as_float(xr.y & 0xffff0000u)};
;                     const f32x4 x1 = {__uint_as_float(xr.z << 16), __uint_as_float(xr.z & 0xffff0000u), __uint_as_float(xr.w << 16), __uint_as_float(xr.w & 0xffff0000u)};
;                     const f32x4 y0 = x0 + acc[ai][bj][m][0] * alpha, y1 = x1 + acc[ai][bj][m][1] * alpha;
;                     u32x4 w; w.x = pk(y0[0], y0[1]); w.y = pk(y0[2], y0[3]); w.z = pk(y1[0], y1[1]); w.w = pk(y1[2], y1[3]);
;                     *(u32x4*)(xb + (size_t)row * DMODEL + col0 + bj * HALF) = w;
;                     ss += ((y0[0] * y0[0] + y0[1] * y0[1]) + (y0[2] * y0[2] + y0[3] * y0[3])) + ((y1[0] * y1[0] + y1[1] * y1[1]) + (y1[2] * y1[2] + y1[3] * y1[3])); }
;                 ss += __shfl_xor(ss, 16); ss += __shfl_xor(ss, 32);
;                 if (fq == 0) red[(ai * HALF + wr * 64 + m * 16 + fr) * 4 + wc] = ss; }
.LBB0_393:
	v_and_b32_e32 v131, 64, v243
	v_xor_b32_e32 v130, 16, v243
	v_add_u32_e32 v131, 64, v131
	v_cmp_lt_i32_e32 vcc, v130, v131
	s_lshl_b32 s20, s27, 8
	v_lshl_or_b32 v148, s26, 8, v158
	v_cndmask_b32_e32 v130, v243, v130, vcc
	v_add_u32_e32 v150, s20, v156
	v_ashrrev_i32_e32 v149, 31, v148
	v_lshlrev_b32_e32 v164, 2, v130
	v_xor_b32_e32 v130, 32, v243
	v_cmp_lt_i32_e32 vcc, v130, v131
	v_lshlrev_b64 v[174:175], 1, v[148:149]
	v_ashrrev_i32_e32 v151, 31, v150
	v_cndmask_b32_e32 v130, v243, v130, vcc
	v_lshl_add_u64 v[152:153], s[10:11], 0, v[174:175]
	v_lshlrev_b64 v[176:177], 11, v[150:151]
	v_lshlrev_b32_e32 v163, 2, v130
	v_lshl_add_u64 v[130:131], v[152:153], 0, v[176:177]
	v_mov_b32_e32 v224, v130
	v_mov_b32_e32 v225, v131
	global_load_dwordx4 v[166:169], v[130:131], off
	global_load_dwordx4 v[170:173], v[130:131], off offset:256
	v_or_b32_e32 v130, 16, v150
	v_ashrrev_i32_e32 v131, 31, v130
	v_lshlrev_b64 v[154:155], 11, v[130:131]
	v_lshl_add_u64 v[130:131], v[152:153], 0, v[154:155]
	global_load_dwordx4 v[134:137], v[130:131], off
	s_nop 0
	global_load_dwordx4 v[130:133], v[130:131], off offset:256
	s_mov_b64 s[8:9], 0x10000
	v_lshl_add_u64 v[226:227], v[224:225], 0, s[8:9]
	global_load_dwordx4 v[182:185], v[226:227], off
	global_load_dwordx4 v[186:189], v[226:227], off offset:256
	s_mov_b64 s[8:9], 0x18000
	v_lshl_add_u64 v[226:227], v[224:225], 0, s[8:9]
	global_load_dwordx4 v[190:193], v[226:227], off
	global_load_dwordx4 v[204:207], v[226:227], off offset:256
	s_mov_b64 s[8:9], 0x40000
	v_lshl_add_u64 v[226:227], v[224:225], 0, s[8:9]
	global_load_dwordx4 v[208:211], v[226:227], off
	global_load_dwordx4 v[212:215], v[226:227], off offset:256
	s_mov_b64 s[8:9], 0x48000
	v_lshl_add_u64 v[226:227], v[224:225], 0, s[8:9]
	global_load_dwordx4 v[216:219], v[226:227], off
	global_load_dwordx4 v[220:223], v[226:227], off offset:256
	v_lshl_add_u64 v[176:177], s[10:11], 0, v[176:177]
	v_lshl_add_u64 v[174:175], v[176:177], 0, v[174:175]
	s_waitcnt vmcnt(8)
	v_lshlrev_b32_e32 v178, 16, v166
	v_and_b32_e32 v179, 0xffff0000, v166
	v_lshlrev_b32_e32 v166, 16, v167
	v_and_b32_e32 v167, 0xffff0000, v167
	v_lshlrev_b32_e32 v180, 16, v168
	v_and_b32_e32 v181, 0xffff0000, v168
	v_lshlrev_b32_e32 v168, 16, v169
	v_and_b32_e32 v169, 0xffff0000, v169
	v_pk_fma_f32 v[128:129], v[128:129], 0.5, v[166:167] op_sel_hi:[1,0,1]
	v_pk_fma_f32 v[126:127], v[126:127], 0.5, v[178:179] op_sel_hi:[1,0,1]
	v_pk_fma_f32 v[166:167], v[124:125], 0.5, v[168:169] op_sel_hi:[1,0,1]
	v_pk_fma_f32 v[168:169], v[122:123], 0.5, v[180:181] op_sel_hi:[1,0,1]
	v_cvt_pk_bf16_f32 v122, v126, v127
	v_cvt_pk_bf16_f32 v123, v128, v129
	v_cvt_pk_bf16_f32 v124, v168, v169
	v_cvt_pk_bf16_f32 v125, v166, v167
	global_store_dwordx4 v[174:175], v[122:125], off
	s_nop 1
	v_mul_f32_e32 v122, v127, v127
	v_mul_f32_e32 v123, v129, v129
	v_fmac_f32_e32 v122, v126, v126
	v_fmac_f32_e32 v123, v128, v128
	v_add_f32_e32 v122, v122, v123
	v_mul_f32_e32 v123, v169, v169
	v_mul_f32_e32 v124, v167, v167
	v_fmac_f32_e32 v123, v168, v168
	v_fmac_f32_e32 v124, v166, v166
	v_add_f32_e32 v123, v123, v124
	v_add_f32_e32 v165, v122, v123
	v_lshlrev_b32_e32 v122, 16, v170
	v_and_b32_e32 v123, 0xffff0000, v170
	v_lshlrev_b32_e32 v124, 16, v171
	v_and_b32_e32 v125, 0xffff0000, v171
	v_lshlrev_b32_e32 v126, 16, v172
	v_and_b32_e32 v127, 0xffff0000, v172
	v_lshlrev_b32_e32 v128, 16, v173
	v_and_b32_e32 v129, 0xffff0000, v173
	v_pk_fma_f32 v[120:121], v[120:121], 0.5, v[124:125] op_sel_hi:[1,0,1]
	v_pk_fma_f32 v[118:119], v[118:119], 0.5, v[122:123] op_sel_hi:[1,0,1]
	v_pk_fma_f32 v[122:123], v[116:117], 0.5, v[128:129] op_sel_hi:[1,0,1]
	v_pk_fma_f32 v[124:125], v[114:115], 0.5, v[126:127] op_sel_hi:[1,0,1]
	v_cvt_pk_bf16_f32 v114, v118, v119
	v_cvt_pk_bf16_f32 v115, v120, v121
	v_cvt_pk_bf16_f32 v116, v124, v125
	v_cvt_pk_bf16_f32 v117, v122, v123
	global_store_dwordx4 v[174:175], v[114:117], off offset:256
	s_nop 1
	v_mul_f32_e32 v114, v119, v119
	v_mul_f32_e32 v115, v121, v121
	v_fmac_f32_e32 v114, v118, v118
	v_fmac_f32_e32 v115, v120, v120
	v_add_f32_e32 v114, v114, v115
	v_mul_f32_e32 v115, v125, v125
	v_mul_f32_e32 v116, v123, v123
	v_fmac_f32_e32 v115, v124, v124
	v_fmac_f32_e32 v116, v122, v122
	v_add_f32_e32 v115, v115, v116
	v_add_f32_e32 v114, v114, v115
	v_add_f32_e32 v114, v165, v114
	ds_bpermute_b32 v115, v164, v114
	s_waitcnt lgkmcnt(0)
	v_add_f32_e32 v114, v114, v115
	ds_bpermute_b32 v115, v163, v114
	s_and_saveexec_b64 s[8:9], s[38:39]
	s_mov_b32 s37, 0x41c00000
	s_cbranch_execz .LBB0_395
	s_waitcnt lgkmcnt(0)
	v_add_f32_e32 v114, v114, v115
	ds_write_b32 v160, v114

; __device__ __forceinline__ unsigned pk(float lo, float hi) { f32x2v v = {lo, hi}; bf16x2v b = __builtin_convertvector(v, bf16x2v); return __builtin_bit_cast(unsigned, b); }
;     __device__ __forceinline__ void operator()(const f32x4 (&acc)[2][2][4][2], const Unit& u, int wr, int wc, int fr, int fq) const {
;     ...
;           for (int mp = 0; mp < 2; ++mp) { u32x4 xv[2][2];
; #pragma unroll
;             for (int mm = 0; mm < 2; ++mm)
; #pragma unroll
;                 for (int bj = 0; bj < 2; ++bj) xv[mm][bj] = *(const u32x4*)(xb + (size_t)(row0 + ai * HALF + (2 * mp + mm) * 16) * DMODEL + col0 + bj * HALF);
; #pragma unroll
;             for (int mm = 0; mm < 2; ++mm) { const int m = 2 * mp + mm, row = row0 + ai * HALF + m * 16; float ss = 0.f;
; #pragma unroll
;                 for (int bj = 0; bj < 2; ++bj) { const u32x4 xr = xv[mm][bj];
;                     const f32x4 x0 = {__uint_as_float(xr.x << 16), __uint_as_float(xr.x & 0xffff0000u), __uint_as_float(xr.y << 16), __uint_as_float(xr.y & 0xffff0000u)};
;                     const f32x4 x1 = {__uint_as_float(xr.z << 16), __uint_as_float(xr.z & 0xffff0000u), __uint_as_float(xr.w << 16), __uint_as_float(xr.w & 0xffff0000u)};
;                     const f32x4 y0 = x0 + acc[ai][bj][m][0] * alpha, y1 = x1 + acc[ai][bj][m][1] * alpha;
;                     u32x4 w; w.x = pk(y0[0], y0[1]); w.y = pk(y0[2], y0[3]); w.z = pk(y1[0], y1[1]); w.w = pk(y1[2], y1[3]);
;                     *(u32x4*)(xb + (size_t)row * DMODEL + col0 + bj * HALF) = w;
;                     ss += ((y0[0] * y0[0] + y0[1] * y0[1]) + (y0[2] * y0[2] + y0[3] * y0[3])) + ((y1[0] * y1[0] + y1[1] * y1[1]) + (y1[2] * y1[2] + y1[3] * y1[3])); }
;                 ss += __shfl_xor(ss, 16); ss += __shfl_xor(ss, 32);
;                 if (fq == 0) red[(ai * HALF + wr * 64 + m * 16 + fr) * 4 + wc] = ss; }
.LBB0_397:
	s_or_b64 exec, exec, s[8:9]
	v_or_b32_e32 v98, 32, v150
	s_waitcnt lgkmcnt(0)
	v_ashrrev_i32_e32 v99, 31, v98
	v_lshlrev_b64 v[116:117], 11, v[98:99]
	v_lshl_add_u64 v[98:99], v[152:153], 0, v[116:117]
	s_mov_b64 s[8:9], 0x50000
	v_lshl_add_u64 v[226:227], v[224:225], 0, s[8:9]
	global_load_dwordx4 v[166:169], v[226:227], off
	global_load_dwordx4 v[170:173], v[226:227], off offset:256
	s_mov_b64 s[8:9], 0x58000
	v_lshl_add_u64 v[226:227], v[224:225], 0, s[8:9]
	global_load_dwordx4 v[178:181], v[226:227], off
	global_load_dwordx4 v[134:137], v[226:227], off offset:256
	v_or_b32_e32 v98, 48, v150
	v_ashrrev_i32_e32 v99, 31, v98
	v_lshlrev_b64 v[106:107], 11, v[98:99]
	v_lshl_add_u64 v[98:99], v[152:153], 0, v[106:107]
	s_nop 0
	v_lshl_add_u64 v[116:117], s[10:11], 0, v[116:117]
	v_lshl_add_u64 v[116:117], v[148:149], 1, v[116:117]
	s_waitcnt vmcnt(12)
	v_mov_b32_e32 v108, v182
	v_mov_b32_e32 v109, v183
	v_mov_b32_e32 v110, v184
	v_mov_b32_e32 v111, v185
	v_mov_b32_e32 v112, v186
	v_mov_b32_e32 v113, v187
	v_mov_b32_e32 v114, v188
	v_mov_b32_e32 v115, v189
	v_mov_b32_e32 v102, v190
	v_mov_b32_e32 v103, v191
	v_mov_b32_e32 v104, v192
	v_mov_b32_e32 v105, v193
	v_mov_b32_e32 v98, v204
	v_mov_b32_e32 v99, v205
	v_mov_b32_e32 v100, v206
	v_mov_b32_e32 v101, v207
	v_lshlrev_b32_e32 v118, 16, v108
	v_and_b32_e32 v119, 0xffff0000, v108
	v_lshlrev_b32_e32 v108, 16, v109
	v_and_b32_e32 v109, 0xffff0000, v109
	v_lshlrev_b32_e32 v120, 16, v110
	v_and_b32_e32 v121, 0xffff0000, v110
	v_lshlrev_b32_e32 v110, 16, v111
	v_and_b32_e32 v111, 0xffff0000, v111
	v_pk_fma_f32 v[96:97], v[96:97], 0.5, v[108:109] op_sel_hi:[1,0,1]
	v_pk_fma_f32 v[94:95], v[94:95], 0.5, v[118:119] op_sel_hi:[1,0,1]
	v_pk_fma_f32 v[108:109], v[92:93], 0.5, v[110:111] op_sel_hi:[1,0,1]
	v_pk_fma_f32 v[110:111], v[90:91], 0.5, v[120:121] op_sel_hi:[1,0,1]
	v_cvt_pk_bf16_f32 v90, v94, v95
	v_cvt_pk_bf16_f32 v91, v96, v97
	v_cvt_pk_bf16_f32 v92, v110, v111
	v_cvt_pk_bf16_f32 v93, v108, v109
	global_store_dwordx4 v[116:117], v[90:93], off
	s_nop 1
	v_mul_f32_e32 v90, v95, v95
	v_mul_f32_e32 v91, v97, v97
	v_fmac_f32_e32 v90, v94, v94
	v_fmac_f32_e32 v91, v96, v96
	v_add_f32_e32 v90, v90, v91
	v_mul_f32_e32 v91, v111, v111
	v_mul_f32_e32 v92, v109, v109
	v_fmac_f32_e32 v91, v110, v110
	v_fmac_f32_e32 v92, v108, v108
	v_add_f32_e32 v91, v91, v92
	v_add_f32_e32 v108, v90, v91
	v_lshlrev_b32_e32 v90, 16, v112
	v_and_b32_e32 v91, 0xffff0000, v112
	v_lshlrev_b32_e32 v92, 16, v113
	v_and_b32_e32 v93, 0xffff0000, v113
	v_lshlrev_b32_e32 v94, 16, v114
	v_and_b32_e32 v95, 0xffff0000, v114
	v_lshlrev_b32_e32 v96, 16, v115
	v_and_b32_e32 v97, 0xffff0000, v115
	v_pk_fma_f32 v[88:89], v[88:89], 0.5, v[92:93] op_sel_hi:[1,0,1]
	v_pk_fma_f32 v[86:87], v[86:87], 0.5, v[90:91] op_sel_hi:[1,0,1]
	v_pk_fma_f32 v[90:91], v[84:85], 0.5, v[96:97] op_sel_hi:[1,0,1]
	v_pk_fma_f32 v[92:93], v[82:83], 0.5, v[94:95] op_sel_hi:[1,0,1]
	v_cvt_pk_bf16_f32 v82, v86, v87
	v_cvt_pk_bf16_f32 v83, v88, v89
	v_cvt_pk_bf16_f32 v84, v92, v93
	v_cvt_pk_bf16_f32 v85, v90, v91
	global_store_dwordx4 v[116:117], v[82:85], off offset:256
	s_nop 1
	v_mul_f32_e32 v82, v87, v87
	v_mul_f32_e32 v83, v89, v89
	v_fmac_f32_e32 v82, v86, v86
	v_fmac_f32_e32 v83, v88, v88
	v_add_f32_e32 v82, v82, v83
	v_mul_f32_e32 v83, v93, v93
	v_mul_f32_e32 v84, v91, v91
	v_fmac_f32_e32 v83, v92, v92
	v_fmac_f32_e32 v84, v90, v90
	v_add_f32_e32 v83, v83, v84
	v_add_f32_e32 v82, v82, v83
	v_add_f32_e32 v82, v108, v82
	ds_bpermute_b32 v83, v164, v82
	s_waitcnt lgkmcnt(0)
	v_add_f32_e32 v82, v82, v83
	ds_bpermute_b32 v83, v163, v82
	s_and_saveexec_b64 s[8:9], s[38:39]
	s_cbranch_execz .LBB0_399
	s_waitcnt lgkmcnt(0)
	v_add_f32_e32 v82, v82, v83
	ds_write_b32 v160, v82 offset:512
.LBB0_399:
	s_or_b64 exec, exec, s[8:9]
	v_lshlrev_b32_e32 v82, 16, v102
	s_waitcnt lgkmcnt(0)
	v_and_b32_e32 v83, 0xffff0000, v102
	v_lshlrev_b32_e32 v84, 16, v103
	v_and_b32_e32 v85, 0xffff0000, v103
	v_lshlrev_b32_e32 v86, 16, v104
	v_and_b32_e32 v87, 0xffff0000, v104
	v_pk_fma_f32 v[78:79], v[78:79], 0.5, v[82:83] op_sel_hi:[1,0,1]
	v_pk_fma_f32 v[80:81], v[80:81], 0.5, v[84:85] op_sel_hi:[1,0,1]
	v_pk_fma_f32 v[84:85], v[74:75], 0.5, v[86:87] op_sel_hi:[1,0,1]
	v_cvt_pk_bf16_f32 v74, v78, v79
	v_mul_f32_e32 v79, v79, v79
	v_lshlrev_b32_e32 v88, 16, v105
	v_and_b32_e32 v89, 0xffff0000, v105
	v_fmac_f32_e32 v79, v78, v78
	v_mul_f32_e32 v78, v81, v81
	v_pk_fma_f32 v[82:83], v[76:77], 0.5, v[88:89] op_sel_hi:[1,0,1]
	v_fmac_f32_e32 v78, v80, v80
	v_cvt_pk_bf16_f32 v75, v80, v81
	v_add_f32_e32 v78, v79, v78
	v_mul_f32_e32 v79, v85, v85
	v_mul_f32_e32 v80, v83, v83
	v_fmac_f32_e32 v79, v84, v84
	v_fmac_f32_e32 v80, v82, v82
	v_add_f32_e32 v79, v79, v80
	v_add_f32_e32 v86, v78, v79
	v_lshlrev_b32_e32 v78, 16, v98
	v_and_b32_e32 v79, 0xffff0000, v98
	v_lshlrev_b32_e32 v80, 16, v99
	v_and_b32_e32 v81, 0xffff0000, v99
	v_cvt_pk_bf16_f32 v77, v82, v83
	v_lshlrev_b32_e32 v82, 16, v100
	v_and_b32_e32 v83, 0xffff0000, v100
	v_pk_fma_f32 v[72:73], v[72:73], 0.5, v[80:81] op_sel_hi:[1,0,1]
	v_pk_fma_f32 v[70:71], v[70:71], 0.5, v[78:79] op_sel_hi:[1,0,1]
	v_cvt_pk_bf16_f32 v76, v84, v85
	v_lshlrev_b32_e32 v84, 16, v101
	v_and_b32_e32 v85, 0xffff0000, v101
	v_pk_fma_f32 v[80:81], v[66:67], 0.5, v[82:83] op_sel_hi:[1,0,1]
	v_mul_f32_e32 v66, v71, v71
	v_mul_f32_e32 v67, v73, v73
	v_pk_fma_f32 v[78:79], v[68:69], 0.5, v[84:85] op_sel_hi:[1,0,1]
	v_fmac_f32_e32 v66, v70, v70
	v_fmac_f32_e32 v67, v72, v72
	v_add_f32_e32 v66, v66, v67
	v_mul_f32_e32 v67, v81, v81
	v_mul_f32_e32 v68, v79, v79
	v_fmac_f32_e32 v67, v80, v80
	v_fmac_f32_e32 v68, v78, v78
	v_add_f32_e32 v67, v67, v68
	v_add_f32_e32 v66, v66, v67
	v_add_f32_e32 v69, v86, v66
	ds_bpermute_b32 v84, v164, v69
	v_lshl_add_u64 v[66:67], s[10:11], 0, v[106:107]
	v_lshl_add_u64 v[82:83], v[148:149], 1, v[66:67]
	v_cvt_pk_bf16_f32 v68, v70, v71
	v_cvt_pk_bf16_f32 v70, v80, v81
	s_waitcnt lgkmcnt(0)
	v_add_f32_e32 v66, v69, v84
	ds_bpermute_b32 v67, v163, v66
	v_cvt_pk_bf16_f32 v69, v72, v73
	v_cvt_pk_bf16_f32 v71, v78, v79
	global_store_dwordx4 v[82:83], v[74:77], off
	global_store_dwordx4 v[82:83], v[68:71], off offset:256
	s_and_saveexec_b64 s[8:9], s[38:39]
	s_cbranch_execz .LBB0_401
	s_waitcnt lgkmcnt(0)
	v_add_f32_e32 v66, v66, v67
	ds_write_b32 v160, v66 offset:768
; __device__ __forceinline__ unsigned pk(float lo, float hi) { f32x2v v = {lo, hi}; bf16x2v b = __builtin_convertvector(v, bf16x2v); return __builtin_bit_cast(unsigned, b); }
;     __device__ __forceinline__ void operator()(const f32x4 (&acc)[2][2][4][2], const Unit& u, int wr, int wc, int fr, int fq) const {
;     ...
;           for (int mp = 0; mp < 2; ++mp) { u32x4 xv[2][2];
; #pragma unroll
;             for (int mm = 0; mm < 2; ++mm)
; #pragma unroll
;                 for (int bj = 0; bj < 2; ++bj) xv[mm][bj] = *(const u32x4*)(xb + (size_t)(row0 + ai * HALF + (2 * mp + mm) * 16) * DMODEL + col0 + bj * HALF);
; #pragma unroll
;             for (int mm = 0; mm < 2; ++mm) { const int m = 2 * mp + mm, row = row0 + ai * HALF + m * 16; float ss = 0.f;
; #pragma unroll
;                 for (int bj = 0; bj < 2; ++bj) { const u32x4 xr = xv[mm][bj];
;                     const f32x4 x0 = {__uint_as_float(xr.x << 16), __uint_as_float(xr.x & 0xffff0000u), __uint_as_float(xr.y << 16), __uint_as_float(xr.y & 0xffff0000u)};
;                     const f32x4 x1 = {__uint_as_float(xr.z << 16), __uint_as_float(xr.z & 0xffff0000u), __uint_as_float(xr.w << 16), __uint_as_float(xr.w & 0xffff0000u)};
;                     const f32x4 y0 = x0 + acc[ai][bj][m][0] * alpha, y1 = x1 + acc[ai][bj][m][1] * alpha;
;                     u32x4 w; w.x = pk(y0[0], y0[1]); w.y = pk(y0[2], y0[3]); w.z = pk(y1[0], y1[1]); w.w = pk(y1[2], y1[3]);
;                     *(u32x4*)(xb + (size_t)row * DMODEL + col0 + bj * HALF) = w;
;                     ss += ((y0[0] * y0[0] + y0[1] * y0[1]) + (y0[2] * y0[2] + y0[3] * y0[3])) + ((y1[0] * y1[0] + y1[1] * y1[1]) + (y1[2] * y1[2] + y1[3] * y1[3])); }
;                 ss += __shfl_xor(ss, 16); ss += __shfl_xor(ss, 32);
;                 if (fq == 0) red[(ai * HALF + wr * 64 + m * 16 + fr) * 4 + wc] = ss; }
.LBB0_401:
	s_or_b64 exec, exec, s[8:9]
	s_waitcnt lgkmcnt(0)
	v_lshlrev_b64 v[66:67], 11, v[150:151]
	s_mov_b64 s[8:9], 0x40000
	v_lshl_add_u64 v[84:85], v[66:67], 0, s[8:9]
	v_lshl_add_u64 v[68:69], v[152:153], 0, v[84:85]
	s_mov_b64 s[8:9], 0x48000
	v_lshl_add_u64 v[74:75], v[66:67], 0, s[8:9]
	v_lshl_add_u64 v[66:67], v[152:153], 0, v[74:75]
	s_nop 0
	v_lshl_add_u64 v[84:85], s[10:11], 0, v[84:85]
	v_lshl_add_u64 v[84:85], v[148:149], 1, v[84:85]
	s_waitcnt vmcnt(12)
	v_mov_b32_e32 v76, v208
	v_mov_b32_e32 v77, v209
	v_mov_b32_e32 v78, v210
	v_mov_b32_e32 v79, v211
	v_mov_b32_e32 v80, v212
	v_mov_b32_e32 v81, v213
	v_mov_b32_e32 v82, v214
	v_mov_b32_e32 v83, v215
	v_mov_b32_e32 v70, v216
	v_mov_b32_e32 v71, v217
	v_mov_b32_e32 v72, v218
	v_mov_b32_e32 v73, v219
	v_mov_b32_e32 v66, v220
	v_mov_b32_e32 v67, v221
	v_mov_b32_e32 v68, v222
	v_mov_b32_e32 v69, v223
	v_lshlrev_b32_e32 v86, 16, v76
	v_and_b32_e32 v87, 0xffff0000, v76
	v_lshlrev_b32_e32 v76, 16, v77
	v_and_b32_e32 v77, 0xffff0000, v77
	v_lshlrev_b32_e32 v88, 16, v78
	v_and_b32_e32 v89, 0xffff0000, v78
	v_lshlrev_b32_e32 v78, 16, v79
	v_and_b32_e32 v79, 0xffff0000, v79
	v_pk_fma_f32 v[64:65], v[64:65], 0.5, v[76:77] op_sel_hi:[1,0,1]
	v_pk_fma_f32 v[62:63], v[62:63], 0.5, v[86:87] op_sel_hi:[1,0,1]
	v_pk_fma_f32 v[76:77], v[60:61], 0.5, v[78:79] op_sel_hi:[1,0,1]
	v_pk_fma_f32 v[78:79], v[58:59], 0.5, v[88:89] op_sel_hi:[1,0,1]
	v_cvt_pk_bf16_f32 v58, v62, v63
	v_cvt_pk_bf16_f32 v59, v64, v65
	v_cvt_pk_bf16_f32 v60, v78, v79
	v_cvt_pk_bf16_f32 v61, v76, v77
	global_store_dwordx4 v[84:85], v[58:61], off
	s_nop 1
	v_mul_f32_e32 v58, v63, v63
	v_mul_f32_e32 v59, v65, v65
	v_fmac_f32_e32 v58, v62, v62
	v_fmac_f32_e32 v59, v64, v64
	v_add_f32_e32 v58, v58, v59
	v_mul_f32_e32 v59, v79, v79
	v_mul_f32_e32 v60, v77, v77
	v_fmac_f32_e32 v59, v78, v78
	v_fmac_f32_e32 v60, v76, v76
	v_add_f32_e32 v59, v59, v60
	v_add_f32_e32 v76, v58, v59
	v_lshlrev_b32_e32 v58, 16, v80
	v_and_b32_e32 v59, 0xffff0000, v80
	v_lshlrev_b32_e32 v60, 16, v81
	v_and_b32_e32 v61, 0xffff0000, v81
	v_lshlrev_b32_e32 v62, 16, v82
	v_and_b32_e32 v63, 0xffff0000, v82
	v_lshlrev_b32_e32 v64, 16, v83
	v_and_b32_e32 v65, 0xffff0000, v83
	v_pk_fma_f32 v[56:57], v[56:57], 0.5, v[60:61] op_sel_hi:[1,0,1]
	v_pk_fma_f32 v[54:55], v[54:55], 0.5, v[58:59] op_sel_hi:[1,0,1]
	v_pk_fma_f32 v[58:59], v[52:53], 0.5, v[64:65] op_sel_hi:[1,0,1]
	v_pk_fma_f32 v[60:61], v[50:51], 0.5, v[62:63] op_sel_hi:[1,0,1]
	v_cvt_pk_bf16_f32 v50, v54, v55
	v_cvt_pk_bf16_f32 v51, v56, v57
	v_cvt_pk_bf16_f32 v52, v60, v61
	v_cvt_pk_bf16_f32 v53, v58, v59
	global_store_dwordx4 v[84:85], v[50:53], off offset:256
	s_nop 1
	v_mul_f32_e32 v50, v55, v55
	v_mul_f32_e32 v51, v57, v57
	v_fmac_f32_e32 v50, v54, v54
	v_fmac_f32_e32 v51, v56, v56
	v_add_f32_e32 v50, v50, v51
	v_mul_f32_e32 v51, v61, v61
	v_mul_f32_e32 v52, v59, v59
	v_fmac_f32_e32 v51, v60, v60
	v_fmac_f32_e32 v52, v58, v58
	v_add_f32_e32 v51, v51, v52
	v_add_f32_e32 v50, v50, v51
	v_add_f32_e32 v50, v76, v50
	ds_bpermute_b32 v51, v164, v50
	s_waitcnt lgkmcnt(0)
	v_add_f32_e32 v50, v50, v51
	ds_bpermute_b32 v51, v163, v50
	s_and_saveexec_b64 s[8:9], s[38:39]
	s_cbranch_execz .LBB0_403
	s_waitcnt lgkmcnt(0)
	v_add_f32_e32 v50, v50, v51
	ds_write_b32 v160, v50 offset:2048
.LBB0_403:
	s_or_b64 exec, exec, s[8:9]
	v_lshlrev_b32_e32 v50, 16, v70
	s_waitcnt lgkmcnt(0)
	v_and_b32_e32 v51, 0xffff0000, v70
	v_lshlrev_b32_e32 v52, 16, v71
	v_and_b32_e32 v53, 0xffff0000, v71
	v_lshlrev_b32_e32 v54, 16, v72
	v_and_b32_e32 v55, 0xffff0000, v72
	v_pk_fma_f32 v[46:47], v[46:47], 0.5, v[50:51] op_sel_hi:[1,0,1]
	v_pk_fma_f32 v[48:49], v[48:49], 0.5, v[52:53] op_sel_hi:[1,0,1]
	v_pk_fma_f32 v[52:53], v[42:43], 0.5, v[54:55] op_sel_hi:[1,0,1]
	v_cvt_pk_bf16_f32 v42, v46, v47
	v_mul_f32_e32 v47, v47, v47
	v_lshlrev_b32_e32 v56, 16, v73
	v_and_b32_e32 v57, 0xffff0000, v73
	v_fmac_f32_e32 v47, v46, v46
	v_mul_f32_e32 v46, v49, v49
	v_pk_fma_f32 v[50:51], v[44:45], 0.5, v[56:57] op_sel_hi:[1,0,1]
	v_fmac_f32_e32 v46, v48, v48
	v_cvt_pk_bf16_f32 v43, v48, v49
	v_add_f32_e32 v46, v47, v46
	v_mul_f32_e32 v47, v53, v53
	v_mul_f32_e32 v48, v51, v51
	v_fmac_f32_e32 v47, v52, v52
	v_fmac_f32_e32 v48, v50, v50
	v_add_f32_e32 v47, v47, v48
	v_add_f32_e32 v54, v46, v47
	v_lshlrev_b32_e32 v46, 16, v66
	v_and_b32_e32 v47, 0xffff0000, v66
	v_lshlrev_b32_e32 v48, 16, v67
	v_and_b32_e32 v49, 0xffff0000, v67
	v_cvt_pk_bf16_f32 v45, v50, v51
	v_lshlrev_b32_e32 v50, 16, v68
	v_and_b32_e32 v51, 0xffff0000, v68
	v_pk_fma_f32 v[40:41], v[40:41], 0.5, v[48:49] op_sel_hi:[1,0,1]
	v_pk_fma_f32 v[38:39], v[38:39], 0.5, v[46:47] op_sel_hi:[1,0,1]
	v_cvt_pk_bf16_f32 v44, v52, v53
	v_lshlrev_b32_e32 v52, 16, v69
	v_and_b32_e32 v53, 0xffff0000, v69
	v_pk_fma_f32 v[48:49], v[34:35], 0.5, v[50:51] op_sel_hi:[1,0,1]
	v_mul_f32_e32 v34, v39, v39
	v_mul_f32_e32 v35, v41, v41
	v_pk_fma_f32 v[46:47], v[36:37], 0.5, v[52:53] op_sel_hi:[1,0,1]
	v_fmac_f32_e32 v34, v38, v38
	v_fmac_f32_e32 v35, v40, v40
	v_add_f32_e32 v34, v34, v35
	v_mul_f32_e32 v35, v49, v49
	v_mul_f32_e32 v36, v47, v47
	v_fmac_f32_e32 v35, v48, v48
	v_fmac_f32_e32 v36, v46, v46
	v_add_f32_e32 v35, v35, v36
	v_add_f32_e32 v34, v34, v35
	v_add_f32_e32 v37, v54, v34
	ds_bpermute_b32 v52, v164, v37
	v_lshl_add_u64 v[34:35], s[10:11], 0, v[74:75]
	v_lshl_add_u64 v[50:51], v[148:149], 1, v[34:35]
	v_cvt_pk_bf16_f32 v36, v38, v39
	v_cvt_pk_bf16_f32 v38, v48, v49
	s_waitcnt lgkmcnt(0)
	v_add_f32_e32 v34, v37, v52
	ds_bpermute_b32 v35, v163, v34
	v_cvt_pk_bf16_f32 v37, v40, v41
	v_cvt_pk_bf16_f32 v39, v46, v47
	global_store_dwordx4 v[50:51], v[42:45], off
	global_store_dwordx4 v[50:51], v[36:39], off offset:256
	s_and_saveexec_b64 s[8:9], s[38:39]
	s_cbranch_execz .LBB0_405
	s_waitcnt lgkmcnt(0)
	v_add_f32_e32 v34, v34, v35
	ds_write_b32 v160, v34 offset:2304
; __device__ __forceinline__ unsigned pk(float lo, float hi) { f32x2v v = {lo, hi}; bf16x2v b = __builtin_convertvector(v, bf16x2v); return __builtin_bit_cast(unsigned, b); }
;     __device__ __forceinline__ void operator()(const f32x4 (&acc)[2][2][4][2], const Unit& u, int wr, int wc, int fr, int fq) const {
;     ...
;           for (int mp = 0; mp < 2; ++mp) { u32x4 xv[2][2];
; #pragma unroll
;             for (int mm = 0; mm < 2; ++mm)
; #pragma unroll
;                 for (int bj = 0; bj < 2; ++bj) xv[mm][bj] = *(const u32x4*)(xb + (size_t)(row0 + ai * HALF + (2 * mp + mm) * 16) * DMODEL + col0 + bj * HALF);
; #pragma unroll
;             for (int mm = 0; mm < 2; ++mm) { const int m = 2 * mp + mm, row = row0 + ai * HALF + m * 16; float ss = 0.f;
; #pragma unroll
;                 for (int bj = 0; bj < 2; ++bj) { const u32x4 xr = xv[mm][bj];
;                     const f32x4 x0 = {__uint_as_float(xr.x << 16), __uint_as_float(xr.x & 0xffff0000u), __uint_as_float(xr.y << 16), __uint_as_float(xr.y & 0xffff0000u)};
;                     const f32x4 x1 = {__uint_as_float(xr.z << 16), __uint_as_float(xr.z & 0xffff0000u), __uint_as_float(xr.w << 16), __uint_as_float(xr.w & 0xffff0000u)};
;                     const f32x4 y0 = x0 + acc[ai][bj][m][0] * alpha, y1 = x1 + acc[ai][bj][m][1] * alpha;
;                     u32x4 w; w.x = pk(y0[0], y0[1]); w.y = pk(y0[2], y0[3]); w.z = pk(y1[0], y1[1]); w.w = pk(y1[2], y1[3]);
;                     *(u32x4*)(xb + (size_t)row * DMODEL + col0 + bj * HALF) = w;
;                     ss += ((y0[0] * y0[0] + y0[1] * y0[1]) + (y0[2] * y0[2] + y0[3] * y0[3])) + ((y1[0] * y1[0] + y1[1] * y1[1]) + (y1[2] * y1[2] + y1[3] * y1[3])); }
;                 ss += __shfl_xor(ss, 16); ss += __shfl_xor(ss, 32);
;                 if (fq == 0) red[(ai * HALF + wr * 64 + m * 16 + fr) * 4 + wc] = ss; }
.LBB0_405:
	s_or_b64 exec, exec, s[8:9]
	s_waitcnt lgkmcnt(0)
	v_lshlrev_b64 v[34:35], 11, v[150:151]
	s_mov_b64 s[8:9], 0x50000
	v_lshl_add_u64 v[52:53], v[34:35], 0, s[8:9]
	v_lshl_add_u64 v[36:37], v[152:153], 0, v[52:53]
	s_mov_b64 s[8:9], 0x58000
	v_lshl_add_u64 v[42:43], v[34:35], 0, s[8:9]
	v_lshl_add_u64 v[34:35], v[152:153], 0, v[42:43]
	s_nop 0
	v_lshl_add_u64 v[52:53], s[10:11], 0, v[52:53]
	v_lshl_add_u64 v[52:53], v[148:149], 1, v[52:53]
	s_waitcnt vmcnt(8)
	v_mov_b32_e32 v44, v166
	v_mov_b32_e32 v45, v167
	v_mov_b32_e32 v46, v168
	v_mov_b32_e32 v47, v169
	v_mov_b32_e32 v48, v170
	v_mov_b32_e32 v49, v171
	v_mov_b32_e32 v50, v172
	v_mov_b32_e32 v51, v173
	v_mov_b32_e32 v38, v178
	v_mov_b32_e32 v39, v179
	v_mov_b32_e32 v40, v180
	v_mov_b32_e32 v41, v181
	v_mov_b32_e32 v34, v134
	v_mov_b32_e32 v35, v135
	v_mov_b32_e32 v36, v136
	v_mov_b32_e32 v37, v137
	v_lshlrev_b32_e32 v54, 16, v44
	v_and_b32_e32 v55, 0xffff0000, v44
	v_lshlrev_b32_e32 v44, 16, v45
	v_and_b32_e32 v45, 0xffff0000, v45
	v_lshlrev_b32_e32 v56, 16, v46
	v_and_b32_e32 v57, 0xffff0000, v46
	v_lshlrev_b32_e32 v46, 16, v47
	v_and_b32_e32 v47, 0xffff0000, v47
	v_pk_fma_f32 v[32:33], v[32:33], 0.5, v[44:45] op_sel_hi:[1,0,1]
	v_pk_fma_f32 v[30:31], v[30:31], 0.5, v[54:55] op_sel_hi:[1,0,1]
	v_pk_fma_f32 v[44:45], v[28:29], 0.5, v[46:47] op_sel_hi:[1,0,1]
	v_pk_fma_f32 v[46:47], v[26:27], 0.5, v[56:57] op_sel_hi:[1,0,1]
	v_cvt_pk_bf16_f32 v26, v30, v31
	v_cvt_pk_bf16_f32 v27, v32, v33
	v_cvt_pk_bf16_f32 v28, v46, v47
	v_cvt_pk_bf16_f32 v29, v44, v45
	global_store_dwordx4 v[52:53], v[26:29], off
	s_nop 1
	v_mul_f32_e32 v26, v31, v31
	v_mul_f32_e32 v27, v33, v33
	v_fmac_f32_e32 v26, v30, v30
	v_fmac_f32_e32 v27, v32, v32
	v_add_f32_e32 v26, v26, v27
	v_mul_f32_e32 v27, v47, v47
	v_mul_f32_e32 v28, v45, v45
	v_fmac_f32_e32 v27, v46, v46
	v_fmac_f32_e32 v28, v44, v44
	v_add_f32_e32 v27, v27, v28
	v_add_f32_e32 v44, v26, v27
	v_lshlrev_b32_e32 v26, 16, v48
	v_and_b32_e32 v27, 0xffff0000, v48
	v_lshlrev_b32_e32 v28, 16, v49
	v_and_b32_e32 v29, 0xffff0000, v49
	v_lshlrev_b32_e32 v30, 16, v50
	v_and_b32_e32 v31, 0xffff0000, v50
	v_lshlrev_b32_e32 v32, 16, v51
	v_and_b32_e32 v33, 0xffff0000, v51
	v_pk_fma_f32 v[24:25], v[24:25], 0.5, v[28:29] op_sel_hi:[1,0,1]
	v_pk_fma_f32 v[22:23], v[22:23], 0.5, v[26:27] op_sel_hi:[1,0,1]
	v_pk_fma_f32 v[26:27], v[20:21], 0.5, v[32:33] op_sel_hi:[1,0,1]
	v_pk_fma_f32 v[28:29], v[18:19], 0.5, v[30:31] op_sel_hi:[1,0,1]
	v_cvt_pk_bf16_f32 v18, v22, v23
	v_cvt_pk_bf16_f32 v19, v24, v25
	v_cvt_pk_bf16_f32 v20, v28, v29
	v_cvt_pk_bf16_f32 v21, v26, v27
	global_store_dwordx4 v[52:53], v[18:21], off offset:256
	s_nop 1
	v_mul_f32_e32 v18, v23, v23
	v_mul_f32_e32 v19, v25, v25
	v_fmac_f32_e32 v18, v22, v22
	v_fmac_f32_e32 v19, v24, v24
	v_add_f32_e32 v18, v18, v19
	v_mul_f32_e32 v19, v29, v29
	v_mul_f32_e32 v20, v27, v27
	v_fmac_f32_e32 v19, v28, v28
	v_fmac_f32_e32 v20, v26, v26
	v_add_f32_e32 v19, v19, v20
	v_add_f32_e32 v18, v18, v19
	v_add_f32_e32 v18, v44, v18
	ds_bpermute_b32 v19, v164, v18
	s_waitcnt lgkmcnt(0)
	v_add_f32_e32 v18, v18, v19
	ds_bpermute_b32 v19, v163, v18
	s_and_saveexec_b64 s[8:9], s[38:39]
	s_cbranch_execz .LBB0_407
	s_waitcnt lgkmcnt(0)
	v_add_f32_e32 v18, v18, v19
	ds_write_b32 v160, v18 offset:2560
.LBB0_407:
	s_or_b64 exec, exec, s[8:9]
	v_lshlrev_b32_e32 v18, 16, v38
	s_waitcnt lgkmcnt(0)
	v_and_b32_e32 v19, 0xffff0000, v38
	v_lshlrev_b32_e32 v20, 16, v39
	v_and_b32_e32 v21, 0xffff0000, v39
	v_lshlrev_b32_e32 v22, 16, v40
	v_and_b32_e32 v23, 0xffff0000, v40
	v_pk_fma_f32 v[14:15], v[14:15], 0.5, v[18:19] op_sel_hi:[1,0,1]
	v_pk_fma_f32 v[16:17], v[16:17], 0.5, v[20:21] op_sel_hi:[1,0,1]
	v_pk_fma_f32 v[20:21], v[10:11], 0.5, v[22:23] op_sel_hi:[1,0,1]
	v_cvt_pk_bf16_f32 v10, v14, v15
	v_mul_f32_e32 v15, v15, v15
	v_lshlrev_b32_e32 v24, 16, v41
	v_and_b32_e32 v25, 0xffff0000, v41
	v_fmac_f32_e32 v15, v14, v14
	v_mul_f32_e32 v14, v17, v17
	v_pk_fma_f32 v[18:19], v[12:13], 0.5, v[24:25] op_sel_hi:[1,0,1]
	v_fmac_f32_e32 v14, v16, v16
	v_cvt_pk_bf16_f32 v11, v16, v17
	v_add_f32_e32 v14, v15, v14
	v_mul_f32_e32 v15, v21, v21
	v_mul_f32_e32 v16, v19, v19
	v_fmac_f32_e32 v15, v20, v20
	v_fmac_f32_e32 v16, v18, v18
	v_add_f32_e32 v15, v15, v16
	v_add_f32_e32 v22, v14, v15
	v_lshlrev_b32_e32 v14, 16, v34
	v_and_b32_e32 v15, 0xffff0000, v34
	v_lshlrev_b32_e32 v16, 16, v35
	v_and_b32_e32 v17, 0xffff0000, v35
	v_cvt_pk_bf16_f32 v13, v18, v19
	v_lshlrev_b32_e32 v18, 16, v36
	v_and_b32_e32 v19, 0xffff0000, v36
	v_pk_fma_f32 v[8:9], v[8:9], 0.5, v[16:17] op_sel_hi:[1,0,1]
	v_pk_fma_f32 v[6:7], v[6:7], 0.5, v[14:15] op_sel_hi:[1,0,1]
	v_cvt_pk_bf16_f32 v12, v20, v21
	v_lshlrev_b32_e32 v20, 16, v37
	v_and_b32_e32 v21, 0xffff0000, v37
	v_pk_fma_f32 v[16:17], v[2:3], 0.5, v[18:19] op_sel_hi:[1,0,1]
	v_mul_f32_e32 v2, v7, v7
	v_mul_f32_e32 v3, v9, v9
	v_pk_fma_f32 v[14:15], v[4:5], 0.5, v[20:21] op_sel_hi:[1,0,1]
	v_fmac_f32_e32 v2, v6, v6
	v_fmac_f32_e32 v3, v8, v8
	v_add_f32_e32 v2, v2, v3
	v_mul_f32_e32 v3, v17, v17
	v_mul_f32_e32 v4, v15, v15
	v_fmac_f32_e32 v3, v16, v16
	v_fmac_f32_e32 v4, v14, v14
	v_add_f32_e32 v3, v3, v4
	v_add_f32_e32 v2, v2, v3
	v_add_f32_e32 v5, v22, v2
	ds_bpermute_b32 v20, v164, v5
	v_lshl_add_u64 v[2:3], s[10:11], 0, v[42:43]
	v_lshl_add_u64 v[18:19], v[148:149], 1, v[2:3]
	v_cvt_pk_bf16_f32 v4, v6, v7
	v_cvt_pk_bf16_f32 v6, v16, v17
	s_waitcnt lgkmcnt(0)
	v_add_f32_e32 v2, v5, v20
	ds_bpermute_b32 v3, v163, v2
	v_cvt_pk_bf16_f32 v5, v8, v9
	v_cvt_pk_bf16_f32 v7, v14, v15
	global_store_dwordx4 v[18:19], v[10:13], off
	global_store_dwordx4 v[18:19], v[4:7], off offset:256
	s_and_saveexec_b64 s[8:9], s[38:39]
	s_cbranch_execz .LBB0_409
	s_waitcnt lgkmcnt(0)
	v_add_f32_e32 v2, v2, v3
	ds_write_b32 v160, v2 offset:2816

; #define PG8_STAGE(bufoff, gbase, voff) do { _Pragma("unroll") for (int _i = 0; _i < 2; ++_i) \
;         __builtin_amdgcn_global_load_lds((const unsigned*)((const char*)(gbase) + (voff)[_i]), (PG8_LAS unsigned*)(lds + (bufoff) + ldsw + _i * 8192), 16, 0, 0); } while (0)
; #define PG8_LDA(dst, b, h) do { _Pragma("unroll") for (int m = 0; m < 4; ++m) _Pragma("unroll") for (int k = 0; k < 2; ++k) dst[m][k] = *(const PG8_LAS bf16x8*)(lds + PG8_SA(b, h) + aoff + m * 2048 + k * 1024); } while (0)
; #define PG8_LDB(dst, b, h) do { _Pragma("unroll") for (int n = 0; n < 2; ++n) _Pragma("unroll") for (int k = 0; k < 2; ++k) dst[n][k] = *(const PG8_LAS bf16x8*)(lds + PG8_SB(b, h) + boff + n * 2048 + k * 1024); } while (0)
; #define PG8_MMA(ai, bj, At, Bt) do { __builtin_amdgcn_s_setprio(1); _Pragma("unroll") for (int m = 0; m < 4; ++m) _Pragma("unroll") for (int n = 0; n < 2; ++n) _Pragma("unroll") for (int k = 0; k < 2; ++k) \
;         acc[ai][bj][m][n] = __builtin_amdgcn_mfma_f32_16x16x32_bf16(Bt[n][k], At[m][k], acc[ai][bj][m][n], 0, 0, 0); __builtin_amdgcn_s_setprio(0); } while (0)
; #define PG8_WAIT_V(n) asm volatile("s_waitcnt vmcnt(" #n ")" ::: "memory")
; #define PG8_BAR __builtin_amdgcn_s_barrier()
; template <class Epi, class Sched, bool ALIGN_EPI = false, bool SP2 = false>
; __device__ __forceinline__ void gemm_phase(PG8_LAS unsigned char* lds, const Gemm g, const Sched& S, const Epi& E) {
;     ...
;         for (int t = 0; t < nt; t += 2) {
;             const bool last = (t == nt - 2);
;             const char* a1 = cA + (size_t)(t + 1) * kstep;
;             const char* a2 = last ? nA : cA + (size_t)(t + 2) * kstep; const char* b2 = last ? nB : cB + (size_t)(t + 2) * kstep;
;             const char* a3 = a2 + kstep; const char* b3 = b2 + kstep;
;             if (last && has_next) S.a_ready(nxt);
;             if constexpr (SP2) {
;             PG8_LDB(B0, 0, 0); PG8_LDB(B1, 0, 1); PG8_SCHED; PG8_LDA(At, 0, 0); PG8_STAGE(PG8_SA(1, 1), a1 + hstep, voffA);
;             PG8_WAIT_V(8); PG8_WAIT_L(0); PG8_BAR; PG8_MMA(0, 0, At, B0); PG8_MMA(0, 1, At, B1); PG8_BAR; PG8_SCHED;
;             PG8_LDA(At, 0, 1); PG8_STAGE(PG8_SB(0, 0), b2, voffB); PG8_STAGE(PG8_SB(0, 1), b2 + hstep, voffB); PG8_STAGE(PG8_SA(0, 0), a2, voffA);
;             PG8_WAIT_V(8); PG8_WAIT_L(0); PG8_BAR; PG8_MMA(1, 0, At, B0); PG8_MMA(1, 1, At, B1); PG8_BAR; PG8_SCHED;
.LBB0_478:
	s_add_u32 s37, s20, 0xfffc0080
	s_addc_u32 s40, s21, -1
	s_add_i32 s51, 0, 0x10000
	s_cmp_eq_u32 s50, 12
	s_cselect_b32 s43, s9, s40
	s_cselect_b32 s42, s44, s37
	v_add_u32_e32 v0, s51, v248
	s_cselect_b32 s41, s7, s49
	s_cselect_b32 s40, s45, s48
	s_add_i32 s37, 0, 0x14000
	ds_read_b128 v[74:77], v0
	ds_read_b128 v[86:89], v0 offset:1024
	ds_read_b128 v[98:101], v0 offset:2048
	ds_read_b128 v[102:105], v0 offset:3072
	v_add_u32_e32 v0, s37, v248
	ds_read_b128 v[114:117], v0
	ds_read_b128 v[118:121], v0 offset:1024
	ds_read_b128 v[130:133], v0 offset:2048
	ds_read_b128 v[134:137], v0 offset:3072
	v_lshl_add_u64 v[220:221], s[20:21], 0, v[216:217]
	s_add_i32 m0, s3, 0xc000
	ds_read_b128 v[142:145], v250
	ds_read_b128 v[150:153], v250 offset:1024
	ds_read_b128 v[158:161], v250 offset:2048
	ds_read_b128 v[166:169], v250 offset:3072
	ds_read_b128 v[178:181], v250 offset:4096
	ds_read_b128 v[182:185], v250 offset:5120
	ds_read_b128 v[186:189], v250 offset:6144
	ds_read_b128 v[190:193], v250 offset:7168
	global_load_lds_dwordx4 v[220:221], off
	v_lshl_add_u64 v[220:221], s[20:21], 0, v[218:219]
	s_add_i32 m0, s3, 0xe000
	s_nop 0
	global_load_lds_dwordx4 v[220:221], off
	s_waitcnt vmcnt(8)
	s_waitcnt lgkmcnt(0)
	s_barrier
	s_setprio 1
	s_waitcnt lgkmcnt(0)
	v_mfma_f32_16x16x32_bf16 v[174:177], v[74:77], v[142:145], v[174:177]
	v_mfma_f32_16x16x32_bf16 v[170:173], v[98:101], v[142:145], v[170:173]
	v_mfma_f32_16x16x32_bf16 v[146:149], v[74:77], v[158:161], v[146:149]
	v_mfma_f32_16x16x32_bf16 v[138:141], v[98:101], v[158:161], v[138:141]
	v_mfma_f32_16x16x32_bf16 v[110:113], v[74:77], v[178:181], v[110:113]
	v_mfma_f32_16x16x32_bf16 v[106:109], v[98:101], v[178:181], v[106:109]
	v_mfma_f32_16x16x32_bf16 v[82:85], v[74:77], v[186:189], v[82:85]
	v_mfma_f32_16x16x32_bf16 v[78:81], v[98:101], v[186:189], v[78:81]
	v_mfma_f32_16x16x32_bf16 v[174:177], v[86:89], v[150:153], v[174:177]
	v_mfma_f32_16x16x32_bf16 v[170:173], v[102:105], v[150:153], v[170:173]
	v_mfma_f32_16x16x32_bf16 v[146:149], v[86:89], v[166:169], v[146:149]
	v_mfma_f32_16x16x32_bf16 v[138:141], v[102:105], v[166:169], v[138:141]
	v_mfma_f32_16x16x32_bf16 v[110:113], v[86:89], v[182:185], v[110:113]
	v_mfma_f32_16x16x32_bf16 v[106:109], v[102:105], v[182:185], v[106:109]
	v_mfma_f32_16x16x32_bf16 v[82:85], v[86:89], v[190:193], v[82:85]
	v_mfma_f32_16x16x32_bf16 v[78:81], v[102:105], v[190:193], v[78:81]
	s_setprio 0
	s_setprio 1
	v_mfma_f32_16x16x32_bf16 v[162:165], v[114:117], v[142:145], v[162:165]
	v_mfma_f32_16x16x32_bf16 v[126:129], v[114:117], v[158:161], v[126:129]
	v_mfma_f32_16x16x32_bf16 v[122:125], v[130:133], v[158:161], v[122:125]
	v_mfma_f32_16x16x32_bf16 v[94:97], v[114:117], v[178:181], v[94:97]
	v_mfma_f32_16x16x32_bf16 v[90:93], v[130:133], v[178:181], v[90:93]
	v_mfma_f32_16x16x32_bf16 v[70:73], v[114:117], v[186:189], v[70:73]
	v_mfma_f32_16x16x32_bf16 v[66:69], v[130:133], v[186:189], v[66:69]
	v_mfma_f32_16x16x32_bf16 v[162:165], v[118:121], v[150:153], v[162:165]
	v_mfma_f32_16x16x32_bf16 v[142:145], v[130:133], v[142:145], v[154:157]
	v_mfma_f32_16x16x32_bf16 v[126:129], v[118:121], v[166:169], v[126:129]
	v_mfma_f32_16x16x32_bf16 v[122:125], v[134:137], v[166:169], v[122:125]
	v_mfma_f32_16x16x32_bf16 v[94:97], v[118:121], v[182:185], v[94:97]
	v_mfma_f32_16x16x32_bf16 v[90:93], v[134:137], v[182:185], v[90:93]
	v_mfma_f32_16x16x32_bf16 v[70:73], v[118:121], v[190:193], v[70:73]
	v_mfma_f32_16x16x32_bf16 v[66:69], v[134:137], v[190:193], v[66:69]
	v_mfma_f32_16x16x32_bf16 v[142:145], v[134:137], v[150:153], v[142:145]
	s_setprio 0
	s_barrier
	s_add_i32 s51, s51, s2
	v_lshl_add_u64 v[220:221], s[40:41], 0, v[208:209]
	s_mov_b32 m0, s51
	ds_read_b128 v[150:153], v250 offset:16384
	global_load_lds_dwordx4 v[220:221], off
	ds_read_b128 v[154:157], v250 offset:17408
	ds_read_b128 v[158:161], v250 offset:18432
	s_add_i32 m0, s51, 0x2000
	s_add_u32 s54, s40, 0x40000
	v_lshl_add_u64 v[222:223], s[40:41], 0, v[204:205]
	s_addc_u32 s55, s41, 0
	s_add_i32 s37, s37, s2
	global_load_lds_dwordx4 v[222:223], off
	ds_read_b128 v[166:169], v250 offset:19456
	ds_read_b128 v[178:181], v250 offset:20480
	v_lshl_add_u64 v[224:225], s[54:55], 0, v[208:209]
	s_mov_b32 m0, s37
	v_lshl_add_u64 v[226:227], s[42:43], 0, v[206:207]
	global_load_lds_dwordx4 v[224:225], off
	ds_read_b128 v[182:185], v250 offset:21504
	ds_read_b128 v[186:189], v250 offset:22528
	v_lshl_add_u64 v[224:225], s[54:55], 0, v[204:205]
	s_add_i32 m0, s37, 0x2000
	s_nop 0
	global_load_lds_dwordx4 v[224:225], off
	ds_read_b128 v[190:193], v250 offset:23552
	v_lshl_add_u64 v[224:225], s[42:43], 0, v[210:211]
	s_mov_b32 m0, s3
	s_nop 0
	global_load_lds_dwordx4 v[224:225], off
	s_mov_b32 m0, s18
	s_nop 0
	global_load_lds_dwordx4 v[226:227], off
	s_waitcnt vmcnt(8)
	s_waitcnt lgkmcnt(0)
	s_barrier
; #define PG8_STAGE(bufoff, gbase, voff) do { _Pragma("unroll") for (int _i = 0; _i < 2; ++_i) \
;         __builtin_amdgcn_global_load_lds((const unsigned*)((const char*)(gbase) + (voff)[_i]), (PG8_LAS unsigned*)(lds + (bufoff) + ldsw + _i * 8192), 16, 0, 0); } while (0)
; #define PG8_LDA(dst, b, h) do { _Pragma("unroll") for (int m = 0; m < 4; ++m) _Pragma("unroll") for (int k = 0; k < 2; ++k) dst[m][k] = *(const PG8_LAS bf16x8*)(lds + PG8_SA(b, h) + aoff + m * 2048 + k * 1024); } while (0)
; #define PG8_LDB(dst, b, h) do { _Pragma("unroll") for (int n = 0; n < 2; ++n) _Pragma("unroll") for (int k = 0; k < 2; ++k) dst[n][k] = *(const PG8_LAS bf16x8*)(lds + PG8_SB(b, h) + boff + n * 2048 + k * 1024); } while (0)
; #define PG8_MMA(ai, bj, At, Bt) do { __builtin_amdgcn_s_setprio(1); _Pragma("unroll") for (int m = 0; m < 4; ++m) _Pragma("unroll") for (int n = 0; n < 2; ++n) _Pragma("unroll") for (int k = 0; k < 2; ++k) \
;         acc[ai][bj][m][n] = __builtin_amdgcn_mfma_f32_16x16x32_bf16(Bt[n][k], At[m][k], acc[ai][bj][m][n], 0, 0, 0); __builtin_amdgcn_s_setprio(0); } while (0)
; #define PG8_WAIT_V(n) asm volatile("s_waitcnt vmcnt(" #n ")" ::: "memory")
; #define PG8_WAIT_L(n) asm volatile("s_waitcnt lgkmcnt(" #n ")" ::: "memory")
; #define PG8_BAR __builtin_amdgcn_s_barrier()
; #define PG8_SCHED __builtin_amdgcn_sched_barrier(0)
; template <class Epi, class Sched, bool ALIGN_EPI = false, bool SP2 = false>
; __device__ __forceinline__ void gemm_phase(PG8_LAS unsigned char* lds, const Gemm g, const Sched& S, const Epi& E) {
;     ...
;             PG8_WAIT_V(8); PG8_WAIT_L(0); PG8_BAR; PG8_MMA(1, 0, At, B0); PG8_MMA(1, 1, At, B1); PG8_BAR; PG8_SCHED;
;             PG8_LDB(B0, 1, 0); PG8_LDB(B1, 1, 1); PG8_SCHED; PG8_LDA(At, 1, 0); PG8_STAGE(PG8_SA(0, 1), a2 + hstep, voffA);
;             PG8_WAIT_V(8); PG8_WAIT_L(0); PG8_BAR; PG8_MMA(0, 0, At, B0); PG8_MMA(0, 1, At, B1); PG8_BAR; PG8_SCHED;
;             PG8_LDA(At, 1, 1); PG8_STAGE(PG8_SB(1, 0), b3, voffB); PG8_STAGE(PG8_SB(1, 1), b3 + hstep, voffB); PG8_STAGE(PG8_SA(1, 0), a3, voffA);
	s_setprio 1
	s_waitcnt lgkmcnt(0)
	v_mfma_f32_16x16x32_bf16 v[62:65], v[74:77], v[150:153], v[62:65]
	v_mfma_f32_16x16x32_bf16 v[58:61], v[98:101], v[150:153], v[58:61]
	v_mfma_f32_16x16x32_bf16 v[46:49], v[74:77], v[158:161], v[46:49]
	v_mfma_f32_16x16x32_bf16 v[42:45], v[98:101], v[158:161], v[42:45]
	v_mfma_f32_16x16x32_bf16 v[30:33], v[74:77], v[178:181], v[30:33]
	v_mfma_f32_16x16x32_bf16 v[26:29], v[98:101], v[178:181], v[26:29]
	v_mfma_f32_16x16x32_bf16 v[14:17], v[74:77], v[186:189], v[14:17]
	v_mfma_f32_16x16x32_bf16 v[10:13], v[98:101], v[186:189], v[10:13]
	v_mfma_f32_16x16x32_bf16 v[62:65], v[86:89], v[154:157], v[62:65]
	v_mfma_f32_16x16x32_bf16 v[58:61], v[102:105], v[154:157], v[58:61]
	v_mfma_f32_16x16x32_bf16 v[46:49], v[86:89], v[166:169], v[46:49]
	v_mfma_f32_16x16x32_bf16 v[42:45], v[102:105], v[166:169], v[42:45]
	v_mfma_f32_16x16x32_bf16 v[30:33], v[86:89], v[182:185], v[30:33]
	v_mfma_f32_16x16x32_bf16 v[26:29], v[102:105], v[182:185], v[26:29]
	v_mfma_f32_16x16x32_bf16 v[14:17], v[86:89], v[190:193], v[14:17]
	v_mfma_f32_16x16x32_bf16 v[10:13], v[102:105], v[190:193], v[10:13]
	s_setprio 0
	s_setprio 1
	v_mfma_f32_16x16x32_bf16 v[54:57], v[114:117], v[150:153], v[54:57]
	v_mfma_f32_16x16x32_bf16 v[50:53], v[130:133], v[150:153], v[50:53]
	v_mfma_f32_16x16x32_bf16 v[38:41], v[114:117], v[158:161], v[38:41]
	v_mfma_f32_16x16x32_bf16 v[34:37], v[130:133], v[158:161], v[34:37]
	v_mfma_f32_16x16x32_bf16 v[22:25], v[114:117], v[178:181], v[22:25]
	v_mfma_f32_16x16x32_bf16 v[18:21], v[130:133], v[178:181], v[18:21]
	v_mfma_f32_16x16x32_bf16 v[6:9], v[114:117], v[186:189], v[6:9]
	v_mfma_f32_16x16x32_bf16 v[2:5], v[130:133], v[186:189], v[2:5]
	v_mfma_f32_16x16x32_bf16 v[54:57], v[118:121], v[154:157], v[54:57]
	v_mfma_f32_16x16x32_bf16 v[50:53], v[134:137], v[154:157], v[50:53]
	v_mfma_f32_16x16x32_bf16 v[38:41], v[118:121], v[166:169], v[38:41]
	v_mfma_f32_16x16x32_bf16 v[34:37], v[134:137], v[166:169], v[34:37]
	v_mfma_f32_16x16x32_bf16 v[22:25], v[118:121], v[182:185], v[22:25]
	v_mfma_f32_16x16x32_bf16 v[18:21], v[134:137], v[182:185], v[18:21]
	v_mfma_f32_16x16x32_bf16 v[6:9], v[118:121], v[190:193], v[6:9]
	v_mfma_f32_16x16x32_bf16 v[2:5], v[134:137], v[190:193], v[2:5]
	s_setprio 0
	s_barrier
	s_add_i32 s37, 0, 0x18000
	v_add_u32_e32 v0, s37, v248
	s_add_i32 s51, 0, 0x1c000
	ds_read_b128 v[74:77], v0
	ds_read_b128 v[86:89], v0 offset:1024
	ds_read_b128 v[98:101], v0 offset:2048
	ds_read_b128 v[102:105], v0 offset:3072
	v_add_u32_e32 v0, s51, v248
	ds_read_b128 v[114:117], v0
	ds_read_b128 v[118:121], v0 offset:1024
	ds_read_b128 v[130:133], v0 offset:2048
	ds_read_b128 v[134:137], v0 offset:3072
	s_add_u32 s42, s42, 0x40000
	s_addc_u32 s43, s43, 0
	s_mov_b32 m0, s19
	v_lshl_add_u64 v[228:229], s[42:43], 0, v[210:211]
	ds_read_b128 v[150:153], v250 offset:32768
	ds_read_b128 v[154:157], v250 offset:33792
	ds_read_b128 v[158:161], v250 offset:34816
	ds_read_b128 v[166:169], v250 offset:35840
	ds_read_b128 v[178:181], v250 offset:36864
	ds_read_b128 v[182:185], v250 offset:37888
	ds_read_b128 v[186:189], v250 offset:38912
	ds_read_b128 v[190:193], v250 offset:39936
	global_load_lds_dwordx4 v[228:229], off
	v_lshl_add_u64 v[228:229], s[42:43], 0, v[206:207]
	s_mov_b32 m0, s33
	s_nop 0
	global_load_lds_dwordx4 v[228:229], off
	s_waitcnt vmcnt(8)
	s_waitcnt lgkmcnt(0)
	s_barrier
	s_setprio 1
	s_waitcnt lgkmcnt(0)
	v_mfma_f32_16x16x32_bf16 v[174:177], v[74:77], v[150:153], v[174:177]
	v_mfma_f32_16x16x32_bf16 v[170:173], v[98:101], v[150:153], v[170:173]
	v_mfma_f32_16x16x32_bf16 v[146:149], v[74:77], v[158:161], v[146:149]
	v_mfma_f32_16x16x32_bf16 v[138:141], v[98:101], v[158:161], v[138:141]
	v_mfma_f32_16x16x32_bf16 v[110:113], v[74:77], v[178:181], v[110:113]
	v_mfma_f32_16x16x32_bf16 v[106:109], v[98:101], v[178:181], v[106:109]
	v_mfma_f32_16x16x32_bf16 v[82:85], v[74:77], v[186:189], v[82:85]
	v_mfma_f32_16x16x32_bf16 v[78:81], v[98:101], v[186:189], v[78:81]
	v_mfma_f32_16x16x32_bf16 v[174:177], v[86:89], v[154:157], v[174:177]
	v_mfma_f32_16x16x32_bf16 v[170:173], v[102:105], v[154:157], v[170:173]
	v_mfma_f32_16x16x32_bf16 v[146:149], v[86:89], v[166:169], v[146:149]
	v_mfma_f32_16x16x32_bf16 v[138:141], v[102:105], v[166:169], v[138:141]
	v_mfma_f32_16x16x32_bf16 v[110:113], v[86:89], v[182:185], v[110:113]
	v_mfma_f32_16x16x32_bf16 v[106:109], v[102:105], v[182:185], v[106:109]
	v_mfma_f32_16x16x32_bf16 v[82:85], v[86:89], v[190:193], v[82:85]
	v_mfma_f32_16x16x32_bf16 v[78:81], v[102:105], v[190:193], v[78:81]
	s_setprio 0
	s_setprio 1
	v_mfma_f32_16x16x32_bf16 v[162:165], v[114:117], v[150:153], v[162:165]
	v_mfma_f32_16x16x32_bf16 v[142:145], v[130:133], v[150:153], v[142:145]
	v_mfma_f32_16x16x32_bf16 v[126:129], v[114:117], v[158:161], v[126:129]
	v_mfma_f32_16x16x32_bf16 v[122:125], v[130:133], v[158:161], v[122:125]
	v_mfma_f32_16x16x32_bf16 v[94:97], v[114:117], v[178:181], v[94:97]
	v_mfma_f32_16x16x32_bf16 v[90:93], v[130:133], v[178:181], v[90:93]
	v_mfma_f32_16x16x32_bf16 v[70:73], v[114:117], v[186:189], v[70:73]
	v_mfma_f32_16x16x32_bf16 v[66:69], v[130:133], v[186:189], v[66:69]
	v_mfma_f32_16x16x32_bf16 v[162:165], v[118:121], v[154:157], v[162:165]
	v_mfma_f32_16x16x32_bf16 v[154:157], v[134:137], v[154:157], v[142:145]
	v_mfma_f32_16x16x32_bf16 v[126:129], v[118:121], v[166:169], v[126:129]
	v_mfma_f32_16x16x32_bf16 v[122:125], v[134:137], v[166:169], v[122:125]
	v_mfma_f32_16x16x32_bf16 v[94:97], v[118:121], v[182:185], v[94:97]
	v_mfma_f32_16x16x32_bf16 v[90:93], v[134:137], v[182:185], v[90:93]
	v_mfma_f32_16x16x32_bf16 v[70:73], v[118:121], v[190:193], v[70:73]
	v_mfma_f32_16x16x32_bf16 v[66:69], v[134:137], v[190:193], v[66:69]
	s_setprio 0
	s_barrier
; #define PG8_STAGE(bufoff, gbase, voff) do { _Pragma("unroll") for (int _i = 0; _i < 2; ++_i) \
;         __builtin_amdgcn_global_load_lds((const unsigned*)((const char*)(gbase) + (voff)[_i]), (PG8_LAS unsigned*)(lds + (bufoff) + ldsw + _i * 8192), 16, 0, 0); } while (0)
; #define PG8_LDA(dst, b, h) do { _Pragma("unroll") for (int m = 0; m < 4; ++m) _Pragma("unroll") for (int k = 0; k < 2; ++k) dst[m][k] = *(const PG8_LAS bf16x8*)(lds + PG8_SA(b, h) + aoff + m * 2048 + k * 1024); } while (0)
; #define PG8_MMA(ai, bj, At, Bt) do { __builtin_amdgcn_s_setprio(1); _Pragma("unroll") for (int m = 0; m < 4; ++m) _Pragma("unroll") for (int n = 0; n < 2; ++n) _Pragma("unroll") for (int k = 0; k < 2; ++k) \
;         acc[ai][bj][m][n] = __builtin_amdgcn_mfma_f32_16x16x32_bf16(Bt[n][k], At[m][k], acc[ai][bj][m][n], 0, 0, 0); __builtin_amdgcn_s_setprio(0); } while (0)
; #define PG8_WAIT_V(n) asm volatile("s_waitcnt vmcnt(" #n ")" ::: "memory")
; #define PG8_WAIT_L(n) asm volatile("s_waitcnt lgkmcnt(" #n ")" ::: "memory")
; #define PG8_BAR __builtin_amdgcn_s_barrier()
; #define PG8_SCHED __builtin_amdgcn_sched_barrier(0)
; template <class Epi, class Sched, bool ALIGN_EPI = false, bool SP2 = false>
; __device__ __forceinline__ void gemm_phase(PG8_LAS unsigned char* lds, const Gemm g, const Sched& S, const Epi& E) {
;     ...
;             PG8_LDA(At, 1, 1); PG8_STAGE(PG8_SB(1, 0), b3, voffB); PG8_STAGE(PG8_SB(1, 1), b3 + hstep, voffB); PG8_STAGE(PG8_SA(1, 0), a3, voffA);
;             PG8_WAIT_V(8); PG8_WAIT_L(0); PG8_BAR; PG8_MMA(1, 0, At, B0); PG8_MMA(1, 1, At, B1); PG8_BAR; PG8_SCHED;
	s_add_i32 s37, s37, s2
	v_lshl_add_u64 v[220:221], v[220:221], 0, s[28:29]
	s_mov_b32 m0, s37
	ds_read_b128 v[142:145], v250 offset:49152
	global_load_lds_dwordx4 v[220:221], off
	ds_read_b128 v[150:153], v250 offset:50176
	ds_read_b128 v[158:161], v250 offset:51200
	s_add_i32 m0, s37, 0x2000
	s_add_u32 s40, s40, 0x40080
	v_lshl_add_u64 v[220:221], v[222:223], 0, s[28:29]
	s_addc_u32 s41, s41, 0
	s_add_i32 s37, s51, s2
	global_load_lds_dwordx4 v[220:221], off
	ds_read_b128 v[166:169], v250 offset:52224
	ds_read_b128 v[178:181], v250 offset:53248
	v_lshl_add_u64 v[220:221], s[40:41], 0, v[208:209]
	s_mov_b32 m0, s37
	s_nop 0
	global_load_lds_dwordx4 v[220:221], off
	ds_read_b128 v[182:185], v250 offset:54272
	ds_read_b128 v[186:189], v250 offset:55296
	v_lshl_add_u64 v[220:221], s[40:41], 0, v[204:205]
	s_add_i32 m0, s37, 0x2000
	s_nop 0
	global_load_lds_dwordx4 v[220:221], off
	ds_read_b128 v[190:193], v250 offset:56320
	v_lshl_add_u64 v[220:221], v[224:225], 0, s[28:29]
	s_mov_b32 m0, s34
	s_nop 0
	global_load_lds_dwordx4 v[220:221], off
	v_lshl_add_u64 v[220:221], v[226:227], 0, s[28:29]
	s_mov_b32 m0, s35
	s_nop 0
	global_load_lds_dwordx4 v[220:221], off
	s_waitcnt vmcnt(8)
	s_waitcnt lgkmcnt(0)
	s_barrier
	s_setprio 1
	s_waitcnt lgkmcnt(0)
	v_mfma_f32_16x16x32_bf16 v[62:65], v[74:77], v[142:145], v[62:65]
	v_mfma_f32_16x16x32_bf16 v[58:61], v[98:101], v[142:145], v[58:61]
	v_mfma_f32_16x16x32_bf16 v[46:49], v[74:77], v[158:161], v[46:49]
	v_mfma_f32_16x16x32_bf16 v[42:45], v[98:101], v[158:161], v[42:45]
	v_mfma_f32_16x16x32_bf16 v[30:33], v[74:77], v[178:181], v[30:33]
	v_mfma_f32_16x16x32_bf16 v[26:29], v[98:101], v[178:181], v[26:29]
	v_mfma_f32_16x16x32_bf16 v[14:17], v[74:77], v[186:189], v[14:17]
	v_mfma_f32_16x16x32_bf16 v[10:13], v[98:101], v[186:189], v[10:13]
	v_mfma_f32_16x16x32_bf16 v[62:65], v[86:89], v[150:153], v[62:65]
	v_mfma_f32_16x16x32_bf16 v[58:61], v[102:105], v[150:153], v[58:61]
	v_mfma_f32_16x16x32_bf16 v[46:49], v[86:89], v[166:169], v[46:49]
	v_mfma_f32_16x16x32_bf16 v[42:45], v[102:105], v[166:169], v[42:45]
	v_mfma_f32_16x16x32_bf16 v[30:33], v[86:89], v[182:185], v[30:33]
	v_mfma_f32_16x16x32_bf16 v[26:29], v[102:105], v[182:185], v[26:29]
	v_mfma_f32_16x16x32_bf16 v[14:17], v[86:89], v[190:193], v[14:17]
	v_mfma_f32_16x16x32_bf16 v[10:13], v[102:105], v[190:193], v[10:13]
	s_setprio 0
	s_setprio 1
	v_mfma_f32_16x16x32_bf16 v[54:57], v[114:117], v[142:145], v[54:57]
	v_mfma_f32_16x16x32_bf16 v[50:53], v[130:133], v[142:145], v[50:53]
	v_mfma_f32_16x16x32_bf16 v[38:41], v[114:117], v[158:161], v[38:41]
	v_mfma_f32_16x16x32_bf16 v[34:37], v[130:133], v[158:161], v[34:37]
	v_mfma_f32_16x16x32_bf16 v[22:25], v[114:117], v[178:181], v[22:25]
	v_mfma_f32_16x16x32_bf16 v[18:21], v[130:133], v[178:181], v[18:21]
	v_mfma_f32_16x16x32_bf16 v[6:9], v[114:117], v[186:189], v[6:9]
	v_mfma_f32_16x16x32_bf16 v[2:5], v[130:133], v[186:189], v[2:5]
	v_mfma_f32_16x16x32_bf16 v[54:57], v[118:121], v[150:153], v[54:57]
	v_mfma_f32_16x16x32_bf16 v[50:53], v[134:137], v[150:153], v[50:53]
	v_mfma_f32_16x16x32_bf16 v[38:41], v[118:121], v[166:169], v[38:41]
	v_mfma_f32_16x16x32_bf16 v[34:37], v[134:137], v[166:169], v[34:37]
	v_mfma_f32_16x16x32_bf16 v[22:25], v[118:121], v[182:185], v[22:25]
	v_mfma_f32_16x16x32_bf16 v[18:21], v[134:137], v[182:185], v[18:21]
	v_mfma_f32_16x16x32_bf16 v[6:9], v[118:121], v[190:193], v[6:9]
	v_mfma_f32_16x16x32_bf16 v[2:5], v[134:137], v[190:193], v[2:5]
	s_setprio 0
	s_barrier
	s_add_i32 s50, s50, 2
	s_add_u32 s20, s20, 0x100
	s_addc_u32 s21, s21, 0
	s_add_u32 s48, s48, 0x100
	s_addc_u32 s49, s49, 0
	s_cmp_gt_u32 s50, 13
	s_cbranch_scc0 .LBB0_478
	s_and_b64 vcc, exec, s[4:5]
	s_cbranch_vccz .LBB0_481
	s_barrier

; #define PG8_STAGE(bufoff, gbase, voff) do { _Pragma("unroll") for (int _i = 0; _i < 2; ++_i) \
;         __builtin_amdgcn_global_load_lds((const unsigned*)((const char*)(gbase) + (voff)[_i]), (PG8_LAS unsigned*)(lds + (bufoff) + ldsw + _i * 8192), 16, 0, 0); } while (0)
; #define PG8_LDA(dst, b, h) do { _Pragma("unroll") for (int m = 0; m < 4; ++m) _Pragma("unroll") for (int k = 0; k < 2; ++k) dst[m][k] = *(const PG8_LAS bf16x8*)(lds + PG8_SA(b, h) + aoff + m * 2048 + k * 1024); } while (0)
; #define PG8_LDB(dst, b, h) do { _Pragma("unroll") for (int n = 0; n < 2; ++n) _Pragma("unroll") for (int k = 0; k < 2; ++k) dst[n][k] = *(const PG8_LAS bf16x8*)(lds + PG8_SB(b, h) + boff + n * 2048 + k * 1024); } while (0)
; #define PG8_MMA(ai, bj, At, Bt) do { __builtin_amdgcn_s_setprio(1); _Pragma("unroll") for (int m = 0; m < 4; ++m) _Pragma("unroll") for (int n = 0; n < 2; ++n) _Pragma("unroll") for (int k = 0; k < 2; ++k) \
;         acc[ai][bj][m][n] = __builtin_amdgcn_mfma_f32_16x16x32_bf16(Bt[n][k], At[m][k], acc[ai][bj][m][n], 0, 0, 0); __builtin_amdgcn_s_setprio(0); } while (0)
; #define PG8_WAIT_V(n) asm volatile("s_waitcnt vmcnt(" #n ")" ::: "memory")
; #define PG8_BAR __builtin_amdgcn_s_barrier()
; template <class Epi, class Sched, bool ALIGN_EPI = false, bool SP2 = false>
; __device__ __forceinline__ void gemm_phase(PG8_LAS unsigned char* lds, const Gemm g, const Sched& S, const Epi& E) {
;     ...
;         for (int t = 0; t < nt; t += 2) {
;             const bool last = (t == nt - 2);
;             const char* a1 = cA + (size_t)(t + 1) * kstep;
;             const char* a2 = last ? nA : cA + (size_t)(t + 2) * kstep; const char* b2 = last ? nB : cB + (size_t)(t + 2) * kstep;
;             const char* a3 = a2 + kstep; const char* b3 = b2 + kstep;
;             if (last && has_next) S.a_ready(nxt);
;             if constexpr (SP2) {
;             PG8_LDB(B0, 0, 0); PG8_LDB(B1, 0, 1); PG8_SCHED; PG8_LDA(At, 0, 0); PG8_STAGE(PG8_SA(1, 1), a1 + hstep, voffA);
;             PG8_WAIT_V(8); PG8_WAIT_L(0); PG8_BAR; PG8_MMA(0, 0, At, B0); PG8_MMA(0, 1, At, B1); PG8_BAR; PG8_SCHED;
;             PG8_LDA(At, 0, 1); PG8_STAGE(PG8_SB(0, 0), b2, voffB); PG8_STAGE(PG8_SB(0, 1), b2 + hstep, voffB); PG8_STAGE(PG8_SA(0, 0), a2, voffA);
;             PG8_WAIT_V(8); PG8_WAIT_L(0); PG8_BAR; PG8_MMA(1, 0, At, B0); PG8_MMA(1, 1, At, B1); PG8_BAR; PG8_SCHED;
.LBB0_558:
	s_add_u32 s37, s20, 0xfffc0080
	s_addc_u32 s42, s21, -1
	s_add_i32 s53, 0, 0x10000
	s_cmp_eq_u32 s52, 12
	s_cselect_b32 s45, s9, s42
	s_cselect_b32 s44, s48, s37
	s_cselect_b32 s43, s7, s51
	s_cselect_b32 s42, s49, s50
	s_add_i32 s37, 0, 0x14000
	v_add_u32_e32 v152, s53, v160
	v_add_u32_e32 v156, s37, v160
	ds_read_b128 v[140:143], v152
	ds_read_b128 v[144:147], v152 offset:1024
	ds_read_b128 v[148:151], v152 offset:2048
	ds_read_b128 v[152:155], v152 offset:3072
	ds_read_b128 v[164:167], v156
	ds_read_b128 v[168:171], v156 offset:1024
	ds_read_b128 v[172:175], v156 offset:2048
	ds_read_b128 v[176:179], v156 offset:3072
	v_lshl_add_u64 v[156:157], s[20:21], 0, v[136:137]
	s_add_i32 m0, s3, 0xc000
	ds_read_b128 v[180:183], v162
	ds_read_b128 v[184:187], v162 offset:1024
	ds_read_b128 v[188:191], v162 offset:2048
	ds_read_b128 v[204:207], v162 offset:3072
	ds_read_b128 v[208:211], v162 offset:4096
	ds_read_b128 v[212:215], v162 offset:5120
	ds_read_b128 v[216:219], v162 offset:6144
	ds_read_b128 v[220:223], v162 offset:7168
	global_load_lds_dwordx4 v[156:157], off
	v_lshl_add_u64 v[156:157], s[20:21], 0, v[138:139]
	s_add_i32 m0, s3, 0xe000
	s_nop 0
	global_load_lds_dwordx4 v[156:157], off
	s_waitcnt vmcnt(8)
	s_waitcnt lgkmcnt(0)
	s_barrier
	s_setprio 1
	s_waitcnt lgkmcnt(0)
	v_mfma_f32_16x16x32_bf16 v[126:129], v[140:143], v[180:183], v[126:129]
	v_mfma_f32_16x16x32_bf16 v[94:97], v[148:151], v[180:183], v[94:97]
	v_mfma_f32_16x16x32_bf16 v[122:125], v[140:143], v[188:191], v[122:125]
	v_mfma_f32_16x16x32_bf16 v[90:93], v[148:151], v[188:191], v[90:93]
	v_mfma_f32_16x16x32_bf16 v[118:121], v[140:143], v[208:211], v[118:121]
	v_mfma_f32_16x16x32_bf16 v[86:89], v[148:151], v[208:211], v[86:89]
	v_mfma_f32_16x16x32_bf16 v[114:117], v[140:143], v[216:219], v[114:117]
	v_mfma_f32_16x16x32_bf16 v[82:85], v[148:151], v[216:219], v[82:85]
	v_mfma_f32_16x16x32_bf16 v[126:129], v[144:147], v[184:187], v[126:129]
	v_mfma_f32_16x16x32_bf16 v[94:97], v[152:155], v[184:187], v[94:97]
	v_mfma_f32_16x16x32_bf16 v[122:125], v[144:147], v[204:207], v[122:125]
	v_mfma_f32_16x16x32_bf16 v[90:93], v[152:155], v[204:207], v[90:93]
	v_mfma_f32_16x16x32_bf16 v[118:121], v[144:147], v[212:215], v[118:121]
	v_mfma_f32_16x16x32_bf16 v[86:89], v[152:155], v[212:215], v[86:89]
	v_mfma_f32_16x16x32_bf16 v[114:117], v[144:147], v[220:223], v[114:117]
	v_mfma_f32_16x16x32_bf16 v[82:85], v[152:155], v[220:223], v[82:85]
	s_setprio 0
	s_setprio 1
	v_mfma_f32_16x16x32_bf16 v[62:65], v[164:167], v[180:183], v[62:65]
	v_mfma_f32_16x16x32_bf16 v[30:33], v[172:175], v[180:183], v[30:33]
	v_mfma_f32_16x16x32_bf16 v[58:61], v[164:167], v[188:191], v[58:61]
	v_mfma_f32_16x16x32_bf16 v[26:29], v[172:175], v[188:191], v[26:29]
	v_mfma_f32_16x16x32_bf16 v[54:57], v[164:167], v[208:211], v[54:57]
	v_mfma_f32_16x16x32_bf16 v[22:25], v[172:175], v[208:211], v[22:25]
	v_mfma_f32_16x16x32_bf16 v[50:53], v[164:167], v[216:219], v[50:53]
	v_mfma_f32_16x16x32_bf16 v[18:21], v[172:175], v[216:219], v[18:21]
	v_mfma_f32_16x16x32_bf16 v[62:65], v[168:171], v[184:187], v[62:65]
	v_mfma_f32_16x16x32_bf16 v[30:33], v[176:179], v[184:187], v[30:33]
	v_mfma_f32_16x16x32_bf16 v[58:61], v[168:171], v[204:207], v[58:61]
	v_mfma_f32_16x16x32_bf16 v[26:29], v[176:179], v[204:207], v[26:29]
	v_mfma_f32_16x16x32_bf16 v[54:57], v[168:171], v[212:215], v[54:57]
	v_mfma_f32_16x16x32_bf16 v[22:25], v[176:179], v[212:215], v[22:25]
	v_mfma_f32_16x16x32_bf16 v[50:53], v[168:171], v[220:223], v[50:53]
	v_mfma_f32_16x16x32_bf16 v[18:21], v[176:179], v[220:223], v[18:21]
	s_setprio 0
	s_barrier
	s_add_i32 s53, s53, s2
	v_lshl_add_u64 v[156:157], s[42:43], 0, v[0:1]
	s_mov_b32 m0, s53
	ds_read_b128 v[180:183], v162 offset:16384
	global_load_lds_dwordx4 v[156:157], off
	ds_read_b128 v[184:187], v162 offset:17408
	ds_read_b128 v[188:191], v162 offset:18432
	s_add_i32 m0, s53, 0x2000
	s_add_u32 s54, s42, 0x40000
	v_lshl_add_u64 v[192:193], s[42:43], 0, v[130:131]
	s_addc_u32 s55, s43, 0
	s_add_i32 s37, s37, s2
	global_load_lds_dwordx4 v[192:193], off
	ds_read_b128 v[204:207], v162 offset:19456
	ds_read_b128 v[208:211], v162 offset:20480
	v_lshl_add_u64 v[194:195], s[54:55], 0, v[0:1]
	s_mov_b32 m0, s37
	v_lshl_add_u64 v[224:225], s[44:45], 0, v[132:133]
	global_load_lds_dwordx4 v[194:195], off
	ds_read_b128 v[212:215], v162 offset:21504
	ds_read_b128 v[216:219], v162 offset:22528
	v_lshl_add_u64 v[194:195], s[54:55], 0, v[130:131]
	s_add_i32 m0, s37, 0x2000
	s_nop 0
	global_load_lds_dwordx4 v[194:195], off
	ds_read_b128 v[220:223], v162 offset:23552
	v_lshl_add_u64 v[194:195], s[44:45], 0, v[134:135]
	s_mov_b32 m0, s3
	s_nop 0
	global_load_lds_dwordx4 v[194:195], off
	s_mov_b32 m0, s16
	s_nop 0
	global_load_lds_dwordx4 v[224:225], off
	s_waitcnt vmcnt(8)
	s_waitcnt lgkmcnt(0)
	s_barrier
; #define PG8_STAGE(bufoff, gbase, voff) do { _Pragma("unroll") for (int _i = 0; _i < 2; ++_i) \
;         __builtin_amdgcn_global_load_lds((const unsigned*)((const char*)(gbase) + (voff)[_i]), (PG8_LAS unsigned*)(lds + (bufoff) + ldsw + _i * 8192), 16, 0, 0); } while (0)
; #define PG8_LDA(dst, b, h) do { _Pragma("unroll") for (int m = 0; m < 4; ++m) _Pragma("unroll") for (int k = 0; k < 2; ++k) dst[m][k] = *(const PG8_LAS bf16x8*)(lds + PG8_SA(b, h) + aoff + m * 2048 + k * 1024); } while (0)
; #define PG8_LDB(dst, b, h) do { _Pragma("unroll") for (int n = 0; n < 2; ++n) _Pragma("unroll") for (int k = 0; k < 2; ++k) dst[n][k] = *(const PG8_LAS bf16x8*)(lds + PG8_SB(b, h) + boff + n * 2048 + k * 1024); } while (0)
; #define PG8_MMA(ai, bj, At, Bt) do { __builtin_amdgcn_s_setprio(1); _Pragma("unroll") for (int m = 0; m < 4; ++m) _Pragma("unroll") for (int n = 0; n < 2; ++n) _Pragma("unroll") for (int k = 0; k < 2; ++k) \
;         acc[ai][bj][m][n] = __builtin_amdgcn_mfma_f32_16x16x32_bf16(Bt[n][k], At[m][k], acc[ai][bj][m][n], 0, 0, 0); __builtin_amdgcn_s_setprio(0); } while (0)
; #define PG8_WAIT_V(n) asm volatile("s_waitcnt vmcnt(" #n ")" ::: "memory")
; #define PG8_WAIT_L(n) asm volatile("s_waitcnt lgkmcnt(" #n ")" ::: "memory")
; #define PG8_BAR __builtin_amdgcn_s_barrier()
; #define PG8_SCHED __builtin_amdgcn_sched_barrier(0)
; template <class Epi, class Sched, bool ALIGN_EPI = false, bool SP2 = false>
; __device__ __forceinline__ void gemm_phase(PG8_LAS unsigned char* lds, const Gemm g, const Sched& S, const Epi& E) {
;     ...
;             PG8_WAIT_V(8); PG8_WAIT_L(0); PG8_BAR; PG8_MMA(1, 0, At, B0); PG8_MMA(1, 1, At, B1); PG8_BAR; PG8_SCHED;
;             PG8_LDB(B0, 1, 0); PG8_LDB(B1, 1, 1); PG8_SCHED; PG8_LDA(At, 1, 0); PG8_STAGE(PG8_SA(0, 1), a2 + hstep, voffA);
;             PG8_WAIT_V(8); PG8_WAIT_L(0); PG8_BAR; PG8_MMA(0, 0, At, B0); PG8_MMA(0, 1, At, B1); PG8_BAR; PG8_SCHED;
;             PG8_LDA(At, 1, 1); PG8_STAGE(PG8_SB(1, 0), b3, voffB); PG8_STAGE(PG8_SB(1, 1), b3 + hstep, voffB); PG8_STAGE(PG8_SA(1, 0), a3, voffA);
	s_setprio 1
	s_waitcnt lgkmcnt(0)
	v_mfma_f32_16x16x32_bf16 v[110:113], v[140:143], v[180:183], v[110:113]
	v_mfma_f32_16x16x32_bf16 v[78:81], v[148:151], v[180:183], v[78:81]
	v_mfma_f32_16x16x32_bf16 v[106:109], v[140:143], v[188:191], v[106:109]
	v_mfma_f32_16x16x32_bf16 v[74:77], v[148:151], v[188:191], v[74:77]
	v_mfma_f32_16x16x32_bf16 v[102:105], v[140:143], v[208:211], v[102:105]
	v_mfma_f32_16x16x32_bf16 v[70:73], v[148:151], v[208:211], v[70:73]
	v_mfma_f32_16x16x32_bf16 v[98:101], v[140:143], v[216:219], v[98:101]
	v_mfma_f32_16x16x32_bf16 v[66:69], v[148:151], v[216:219], v[66:69]
	v_mfma_f32_16x16x32_bf16 v[110:113], v[144:147], v[184:187], v[110:113]
	v_mfma_f32_16x16x32_bf16 v[78:81], v[152:155], v[184:187], v[78:81]
	v_mfma_f32_16x16x32_bf16 v[106:109], v[144:147], v[204:207], v[106:109]
	v_mfma_f32_16x16x32_bf16 v[74:77], v[152:155], v[204:207], v[74:77]
	v_mfma_f32_16x16x32_bf16 v[102:105], v[144:147], v[212:215], v[102:105]
	v_mfma_f32_16x16x32_bf16 v[70:73], v[152:155], v[212:215], v[70:73]
	v_mfma_f32_16x16x32_bf16 v[98:101], v[144:147], v[220:223], v[98:101]
	v_mfma_f32_16x16x32_bf16 v[66:69], v[152:155], v[220:223], v[66:69]
	s_setprio 0
	s_setprio 1
	v_mfma_f32_16x16x32_bf16 v[46:49], v[164:167], v[180:183], v[46:49]
	v_mfma_f32_16x16x32_bf16 v[14:17], v[172:175], v[180:183], v[14:17]
	v_mfma_f32_16x16x32_bf16 v[42:45], v[164:167], v[188:191], v[42:45]
	v_mfma_f32_16x16x32_bf16 v[10:13], v[172:175], v[188:191], v[10:13]
	v_mfma_f32_16x16x32_bf16 v[38:41], v[164:167], v[208:211], v[38:41]
	v_mfma_f32_16x16x32_bf16 v[6:9], v[172:175], v[208:211], v[6:9]
	v_mfma_f32_16x16x32_bf16 v[34:37], v[164:167], v[216:219], v[34:37]
	v_mfma_f32_16x16x32_bf16 v[2:5], v[172:175], v[216:219], v[2:5]
	v_mfma_f32_16x16x32_bf16 v[46:49], v[168:171], v[184:187], v[46:49]
	v_mfma_f32_16x16x32_bf16 v[14:17], v[176:179], v[184:187], v[14:17]
	v_mfma_f32_16x16x32_bf16 v[42:45], v[168:171], v[204:207], v[42:45]
	v_mfma_f32_16x16x32_bf16 v[10:13], v[176:179], v[204:207], v[10:13]
	v_mfma_f32_16x16x32_bf16 v[38:41], v[168:171], v[212:215], v[38:41]
	v_mfma_f32_16x16x32_bf16 v[6:9], v[176:179], v[212:215], v[6:9]
	v_mfma_f32_16x16x32_bf16 v[34:37], v[168:171], v[220:223], v[34:37]
	v_mfma_f32_16x16x32_bf16 v[2:5], v[176:179], v[220:223], v[2:5]
	s_setprio 0
	s_barrier
	s_add_i32 s37, 0, 0x18000
	s_add_i32 s53, 0, 0x1c000
	v_add_u32_e32 v152, s37, v160
	v_add_u32_e32 v163, s53, v160
	ds_read_b128 v[140:143], v152
	ds_read_b128 v[144:147], v152 offset:1024
	ds_read_b128 v[148:151], v152 offset:2048
	ds_read_b128 v[152:155], v152 offset:3072
	ds_read_b128 v[164:167], v163
	ds_read_b128 v[168:171], v163 offset:1024
	ds_read_b128 v[172:175], v163 offset:2048
	ds_read_b128 v[176:179], v163 offset:3072
	s_add_u32 s44, s44, 0x40000
	s_addc_u32 s45, s45, 0
	s_mov_b32 m0, s18
	v_lshl_add_u64 v[226:227], s[44:45], 0, v[134:135]
	ds_read_b128 v[180:183], v162 offset:32768
	ds_read_b128 v[184:187], v162 offset:33792
	ds_read_b128 v[188:191], v162 offset:34816
	ds_read_b128 v[204:207], v162 offset:35840
	ds_read_b128 v[208:211], v162 offset:36864
	ds_read_b128 v[212:215], v162 offset:37888
	ds_read_b128 v[216:219], v162 offset:38912
	ds_read_b128 v[220:223], v162 offset:39936
	global_load_lds_dwordx4 v[226:227], off
	v_lshl_add_u64 v[226:227], s[44:45], 0, v[132:133]
	s_mov_b32 m0, s19
	s_nop 0
	global_load_lds_dwordx4 v[226:227], off
	s_waitcnt vmcnt(8)
	s_waitcnt lgkmcnt(0)
	s_barrier
	s_setprio 1
	s_waitcnt lgkmcnt(0)
	v_mfma_f32_16x16x32_bf16 v[126:129], v[140:143], v[180:183], v[126:129]
	v_mfma_f32_16x16x32_bf16 v[94:97], v[148:151], v[180:183], v[94:97]
	v_mfma_f32_16x16x32_bf16 v[122:125], v[140:143], v[188:191], v[122:125]
	v_mfma_f32_16x16x32_bf16 v[90:93], v[148:151], v[188:191], v[90:93]
	v_mfma_f32_16x16x32_bf16 v[118:121], v[140:143], v[208:211], v[118:121]
	v_mfma_f32_16x16x32_bf16 v[86:89], v[148:151], v[208:211], v[86:89]
	v_mfma_f32_16x16x32_bf16 v[114:117], v[140:143], v[216:219], v[114:117]
	v_mfma_f32_16x16x32_bf16 v[82:85], v[148:151], v[216:219], v[82:85]
	v_mfma_f32_16x16x32_bf16 v[126:129], v[144:147], v[184:187], v[126:129]
	v_mfma_f32_16x16x32_bf16 v[94:97], v[152:155], v[184:187], v[94:97]
	v_mfma_f32_16x16x32_bf16 v[122:125], v[144:147], v[204:207], v[122:125]
	v_mfma_f32_16x16x32_bf16 v[90:93], v[152:155], v[204:207], v[90:93]
	v_mfma_f32_16x16x32_bf16 v[118:121], v[144:147], v[212:215], v[118:121]
	v_mfma_f32_16x16x32_bf16 v[86:89], v[152:155], v[212:215], v[86:89]
	v_mfma_f32_16x16x32_bf16 v[114:117], v[144:147], v[220:223], v[114:117]
	v_mfma_f32_16x16x32_bf16 v[82:85], v[152:155], v[220:223], v[82:85]
	s_setprio 0
	s_setprio 1
	v_mfma_f32_16x16x32_bf16 v[62:65], v[164:167], v[180:183], v[62:65]
	v_mfma_f32_16x16x32_bf16 v[30:33], v[172:175], v[180:183], v[30:33]
	v_mfma_f32_16x16x32_bf16 v[58:61], v[164:167], v[188:191], v[58:61]
	v_mfma_f32_16x16x32_bf16 v[26:29], v[172:175], v[188:191], v[26:29]
	v_mfma_f32_16x16x32_bf16 v[54:57], v[164:167], v[208:211], v[54:57]
	v_mfma_f32_16x16x32_bf16 v[22:25], v[172:175], v[208:211], v[22:25]
	v_mfma_f32_16x16x32_bf16 v[50:53], v[164:167], v[216:219], v[50:53]
	v_mfma_f32_16x16x32_bf16 v[18:21], v[172:175], v[216:219], v[18:21]
	v_mfma_f32_16x16x32_bf16 v[62:65], v[168:171], v[184:187], v[62:65]
	v_mfma_f32_16x16x32_bf16 v[30:33], v[176:179], v[184:187], v[30:33]
	v_mfma_f32_16x16x32_bf16 v[58:61], v[168:171], v[204:207], v[58:61]
	v_mfma_f32_16x16x32_bf16 v[26:29], v[176:179], v[204:207], v[26:29]
	v_mfma_f32_16x16x32_bf16 v[54:57], v[168:171], v[212:215], v[54:57]
	v_mfma_f32_16x16x32_bf16 v[22:25], v[176:179], v[212:215], v[22:25]
	v_mfma_f32_16x16x32_bf16 v[50:53], v[168:171], v[220:223], v[50:53]
	v_mfma_f32_16x16x32_bf16 v[18:21], v[176:179], v[220:223], v[18:21]
	s_setprio 0
	s_barrier
; #define PG8_STAGE(bufoff, gbase, voff) do { _Pragma("unroll") for (int _i = 0; _i < 2; ++_i) \
;         __builtin_amdgcn_global_load_lds((const unsigned*)((const char*)(gbase) + (voff)[_i]), (PG8_LAS unsigned*)(lds + (bufoff) + ldsw + _i * 8192), 16, 0, 0); } while (0)
; #define PG8_LDA(dst, b, h) do { _Pragma("unroll") for (int m = 0; m < 4; ++m) _Pragma("unroll") for (int k = 0; k < 2; ++k) dst[m][k] = *(const PG8_LAS bf16x8*)(lds + PG8_SA(b, h) + aoff + m * 2048 + k * 1024); } while (0)
; #define PG8_MMA(ai, bj, At, Bt) do { __builtin_amdgcn_s_setprio(1); _Pragma("unroll") for (int m = 0; m < 4; ++m) _Pragma("unroll") for (int n = 0; n < 2; ++n) _Pragma("unroll") for (int k = 0; k < 2; ++k) \
;         acc[ai][bj][m][n] = __builtin_amdgcn_mfma_f32_16x16x32_bf16(Bt[n][k], At[m][k], acc[ai][bj][m][n], 0, 0, 0); __builtin_amdgcn_s_setprio(0); } while (0)
; #define PG8_WAIT_V(n) asm volatile("s_waitcnt vmcnt(" #n ")" ::: "memory")
; #define PG8_WAIT_L(n) asm volatile("s_waitcnt lgkmcnt(" #n ")" ::: "memory")
; #define PG8_BAR __builtin_amdgcn_s_barrier()
; #define PG8_SCHED __builtin_amdgcn_sched_barrier(0)
; template <class Epi, class Sched, bool ALIGN_EPI = false, bool SP2 = false>
; __device__ __forceinline__ void gemm_phase(PG8_LAS unsigned char* lds, const Gemm g, const Sched& S, const Epi& E) {
;     ...
;             PG8_LDA(At, 1, 1); PG8_STAGE(PG8_SB(1, 0), b3, voffB); PG8_STAGE(PG8_SB(1, 1), b3 + hstep, voffB); PG8_STAGE(PG8_SA(1, 0), a3, voffA);
;             PG8_WAIT_V(8); PG8_WAIT_L(0); PG8_BAR; PG8_MMA(1, 0, At, B0); PG8_MMA(1, 1, At, B1); PG8_BAR; PG8_SCHED;
	s_add_i32 s37, s37, s2
	v_lshl_add_u64 v[156:157], v[156:157], 0, s[28:29]
	s_mov_b32 m0, s37
	ds_read_b128 v[180:183], v162 offset:49152
	global_load_lds_dwordx4 v[156:157], off
	ds_read_b128 v[184:187], v162 offset:50176
	ds_read_b128 v[188:191], v162 offset:51200
	s_add_i32 m0, s37, 0x2000
	s_add_u32 s42, s42, 0x40080
	v_lshl_add_u64 v[156:157], v[192:193], 0, s[28:29]
	s_addc_u32 s43, s43, 0
	s_add_i32 s37, s53, s2
	global_load_lds_dwordx4 v[156:157], off
	ds_read_b128 v[204:207], v162 offset:52224
	ds_read_b128 v[208:211], v162 offset:53248
	v_lshl_add_u64 v[156:157], s[42:43], 0, v[0:1]
	s_mov_b32 m0, s37
	s_nop 0
	global_load_lds_dwordx4 v[156:157], off
	ds_read_b128 v[212:215], v162 offset:54272
	ds_read_b128 v[216:219], v162 offset:55296
	v_lshl_add_u64 v[156:157], s[42:43], 0, v[130:131]
	s_add_i32 m0, s37, 0x2000
	s_nop 0
	global_load_lds_dwordx4 v[156:157], off
	ds_read_b128 v[220:223], v162 offset:56320
	v_lshl_add_u64 v[156:157], v[194:195], 0, s[28:29]
	s_mov_b32 m0, s34
	s_nop 0
	global_load_lds_dwordx4 v[156:157], off
	v_lshl_add_u64 v[156:157], v[224:225], 0, s[28:29]
	s_mov_b32 m0, s35
	s_nop 0
	global_load_lds_dwordx4 v[156:157], off
	s_waitcnt vmcnt(8)
	s_waitcnt lgkmcnt(0)
	s_barrier
	s_setprio 1
	s_waitcnt lgkmcnt(0)
	v_mfma_f32_16x16x32_bf16 v[110:113], v[140:143], v[180:183], v[110:113]
	v_mfma_f32_16x16x32_bf16 v[78:81], v[148:151], v[180:183], v[78:81]
	v_mfma_f32_16x16x32_bf16 v[106:109], v[140:143], v[188:191], v[106:109]
	v_mfma_f32_16x16x32_bf16 v[74:77], v[148:151], v[188:191], v[74:77]
	v_mfma_f32_16x16x32_bf16 v[102:105], v[140:143], v[208:211], v[102:105]
	v_mfma_f32_16x16x32_bf16 v[70:73], v[148:151], v[208:211], v[70:73]
	v_mfma_f32_16x16x32_bf16 v[98:101], v[140:143], v[216:219], v[98:101]
	v_mfma_f32_16x16x32_bf16 v[66:69], v[148:151], v[216:219], v[66:69]
	v_mfma_f32_16x16x32_bf16 v[110:113], v[144:147], v[184:187], v[110:113]
	v_mfma_f32_16x16x32_bf16 v[78:81], v[152:155], v[184:187], v[78:81]
	v_mfma_f32_16x16x32_bf16 v[106:109], v[144:147], v[204:207], v[106:109]
	v_mfma_f32_16x16x32_bf16 v[74:77], v[152:155], v[204:207], v[74:77]
	v_mfma_f32_16x16x32_bf16 v[102:105], v[144:147], v[212:215], v[102:105]
	v_mfma_f32_16x16x32_bf16 v[70:73], v[152:155], v[212:215], v[70:73]
	v_mfma_f32_16x16x32_bf16 v[98:101], v[144:147], v[220:223], v[98:101]
	v_mfma_f32_16x16x32_bf16 v[66:69], v[152:155], v[220:223], v[66:69]
	s_setprio 0
	s_setprio 1
	v_mfma_f32_16x16x32_bf16 v[46:49], v[164:167], v[180:183], v[46:49]
	v_mfma_f32_16x16x32_bf16 v[14:17], v[172:175], v[180:183], v[14:17]
	v_mfma_f32_16x16x32_bf16 v[42:45], v[164:167], v[188:191], v[42:45]
	v_mfma_f32_16x16x32_bf16 v[10:13], v[172:175], v[188:191], v[10:13]
	v_mfma_f32_16x16x32_bf16 v[38:41], v[164:167], v[208:211], v[38:41]
	v_mfma_f32_16x16x32_bf16 v[6:9], v[172:175], v[208:211], v[6:9]
	v_mfma_f32_16x16x32_bf16 v[34:37], v[164:167], v[216:219], v[34:37]
	v_mfma_f32_16x16x32_bf16 v[2:5], v[172:175], v[216:219], v[2:5]
	v_mfma_f32_16x16x32_bf16 v[46:49], v[168:171], v[184:187], v[46:49]
	v_mfma_f32_16x16x32_bf16 v[14:17], v[176:179], v[184:187], v[14:17]
	v_mfma_f32_16x16x32_bf16 v[42:45], v[168:171], v[204:207], v[42:45]
	v_mfma_f32_16x16x32_bf16 v[10:13], v[176:179], v[204:207], v[10:13]
	v_mfma_f32_16x16x32_bf16 v[38:41], v[168:171], v[212:215], v[38:41]
	v_mfma_f32_16x16x32_bf16 v[6:9], v[176:179], v[212:215], v[6:9]
	v_mfma_f32_16x16x32_bf16 v[34:37], v[168:171], v[220:223], v[34:37]
	v_mfma_f32_16x16x32_bf16 v[2:5], v[176:179], v[220:223], v[2:5]
	s_setprio 0
	s_barrier
	s_add_i32 s52, s52, 2
	s_add_u32 s20, s20, 0x100
	s_addc_u32 s21, s21, 0
	s_add_u32 s50, s50, 0x100
	s_addc_u32 s51, s51, 0
	s_cmp_gt_u32 s52, 13
	s_cbranch_scc0 .LBB0_558
	s_and_b64 vcc, exec, s[4:5]
	s_cbranch_vccz .LBB0_561
	s_barrier

; #define LAS __attribute__((address_space(3)))
; __device__ __forceinline__ void attn_fox512(LAS unsigned char* lds, const AttnP& P, int b, int h, int qb2) {
;     ...
;     {
;         LAS float* c2 = (LAS float*)(lds + L_C); LAS float* scan = (LAS float*)(lds + L_SCAN);
;         const int nel = 512 * (qb2 + 1); const float bf = P.b_f[h]; float v[8]; float run = 0.f;
; #pragma unroll
;         for (int e = 0; e < 8; ++e) { const int s = 8 * tid + e; float ls = 0.f;
;             if (s < nel) { const float x = P.FG[(size_t)(tokbase + s) * 8 + h] + bf;
;                 ls = fminf(x, 0.f) * LOG2E - __builtin_amdgcn_logf(1.0f + __builtin_amdgcn_exp2f(-fabsf(x) * LOG2E)); }
;             run += ls; v[e] = run; }
;         float inc = run;
; #pragma unroll
;         for (int o = 1; o < 64; o <<= 1) { const float t = __shfl_up(inc, o); if (lane >= o) inc += t; }
;         if (lane == 63) scan[wid] = inc;
;         __syncthreads();
;         float woff = 0.f;
; #pragma unroll
;         for (int w = 0; w < 8; ++w) { const float t = scan[w]; if (w < wid) woff += t; }
;         const float base = woff + inc - run;
;         if (8 * tid < nel) {
; #pragma unroll
;             for (int e = 0; e < 8; ++e) c2[8 * tid + e] = -(base + v[e]); }
;     }
; __global__ void __launch_bounds__(NTHREADS, 2) mega_fwd(Args args) {
;     ...
;                         if (tid == 0) nxt[0] = atomicAdd(ctl + 64 * l + 8 * (xq + 1), 1u);
;                         __syncthreads();
;                         const unsigned u = nxt[0];
;                         __syncthreads();
;                         if (u >= 256u) break;
;                         const int jj = (int)(u & 63u), qb = 15 - (jj >> 2), rem = xq + 8 * (4 * (int)(u >> 6) + (jj & 3));
;     ...
;                         if (rem < 48) attn_unit<1>(lds, P, rem / 6, rem % 6, qb);
;                         else if (rem < 96) { if (qb & 1) attn_fox512(lds, P, (rem - 48) / 6, (rem - 48) % 6, qb >> 1); }
.LBB0_627:
	s_or_b64 exec, exec, s[0:1]
	v_readlane_b32 s0, v252, 7
	s_waitcnt lgkmcnt(0)
	s_barrier
	v_mov_b32_e32 v0, s0
	ds_read_b32 v0, v0
	s_movk_i32 s0, 0xff
	s_waitcnt lgkmcnt(0)
	s_barrier
	v_cmp_lt_u32_e32 vcc, s0, v0
	v_readfirstlane_b32 s2, v0
	s_mov_b64 s[0:1], -1
	s_cbranch_vccnz .LBB0_622
	s_not_b32 s0, s2
	s_bfe_u32 s0, s0, 0x40002
	v_writelane_b32 v251, s0, 39
	s_lshr_b32 s0, s2, 4
	s_and_b32 s0, s0, 12
	s_and_b32 s1, s2, 3
	s_or_b32 s1, s0, s1
	s_lshl_b32 s2, s1, 3
	v_readlane_b32 s3, v253, 43
	s_or_b32 s2, s2, s3
	s_cmp_gt_u32 s1, 5
	s_cbranch_scc0 .LBB0_738
	s_cmp_lg_u32 s0, 12
	s_cbranch_scc0 .LBB0_739
	v_readlane_b32 s0, v251, 39
	s_bitcmp1_b32 s0, 0
	s_cselect_b64 s[0:1], -1, 0
	s_and_b64 vcc, exec, s[0:1]
	s_mov_b64 s[0:1], 0
	s_cbranch_vccz .LBB0_741
	s_sub_i32 s0, s2, 48
	s_mul_hi_u32 s1, s0, 0xaaaaaaab
	s_lshr_b32 s1, s1, 2
	v_writelane_b32 v251, s2, 40
	s_mul_i32 s2, s1, 6
	s_sub_i32 s16, s0, s2
	v_readlane_b32 s0, v251, 39
	s_lshr_b32 s9, s0, 1
	s_lshl_b32 s8, s9, 9
	s_lshl_b32 s3, s1, 12
	s_add_i32 s18, s8, 0x200
	s_lshl_b64 s[0:1], s[16:17], 2
	v_readlane_b32 s2, v251, 3
	s_add_u32 s4, s2, s0
	v_readlane_b32 s2, v251, 4
	v_mov_b32_e32 v10, v240
	s_addc_u32 s5, s2, s1
	global_load_dword v3, v1, s[4:5]
	v_readlane_b32 s4, v252, 27
	v_lshlrev_b32_e32 v0, 3, v10
	v_readlane_b32 s5, v252, 28
	s_add_u32 s4, s4, s0
	v_readfirstlane_b32 s2, v10
	s_addc_u32 s5, s5, s1
	v_cmp_gt_i32_e32 vcc, s18, v0
	v_mov_b32_e32 v2, 0
	v_mov_b32_e32 v4, 0
	v_mov_b32_e32 v6, 0
	v_mov_b32_e32 v5, 0
	v_mov_b32_e32 v11, 0
	v_mov_b32_e32 v7, 0
	v_mov_b32_e32 v13, 0
	v_mov_b32_e32 v12, 0
	s_and_saveexec_b64 s[0:1], vcc
	s_cbranch_execz .Lfoxscan_done
	v_add_u32_e32 v18, s3, v0
	v_ashrrev_i32_e32 v19, 31, v18
	v_lshlrev_b64 v[18:19], 5, v[18:19]
	v_lshl_add_u64 v[18:19], s[4:5], 0, v[18:19]
	global_load_dword v20, v[18:19], off
	global_load_dword v21, v[18:19], off offset:32
	global_load_dword v22, v[18:19], off offset:64
	global_load_dword v23, v[18:19], off offset:96
	global_load_dword v24, v[18:19], off offset:128
	global_load_dword v25, v[18:19], off offset:160
	global_load_dword v26, v[18:19], off offset:192
	global_load_dword v27, v[18:19], off offset:224
	s_mov_b32 s6, 0xbfb8aa3b
	s_mov_b32 s7, 0x3fb8aa3b
	s_waitcnt vmcnt(0)
	v_add_f32_e32 v20, v3, v20
	v_add_f32_e32 v21, v3, v21
	v_add_f32_e32 v22, v3, v22
	v_add_f32_e32 v23, v3, v23
	v_add_f32_e32 v24, v3, v24
	v_add_f32_e32 v25, v3, v25
	v_add_f32_e32 v26, v3, v26
	v_add_f32_e32 v27, v3, v27
	v_mul_f32_e64 v28, |v20|, s6
	v_mul_f32_e64 v29, |v21|, s6
	v_mul_f32_e64 v30, |v22|, s6
	v_mul_f32_e64 v31, |v23|, s6
	v_mul_f32_e64 v32, |v24|, s6
	v_mul_f32_e64 v33, |v25|, s6
	v_mul_f32_e64 v34, |v26|, s6
	v_mul_f32_e64 v35, |v27|, s6
	v_exp_f32_e32 v28, v28
	v_exp_f32_e32 v29, v29
	v_exp_f32_e32 v30, v30
	v_exp_f32_e32 v31, v31
	v_exp_f32_e32 v32, v32
	v_exp_f32_e32 v33, v33
	v_exp_f32_e32 v34, v34
	v_exp_f32_e32 v35, v35
	v_min_f32_e32 v20, 0, v20
	v_min_f32_e32 v21, 0, v21
	v_min_f32_e32 v22, 0, v22
	v_min_f32_e32 v23, 0, v23
	v_min_f32_e32 v24, 0, v24
	v_min_f32_e32 v25, 0, v25
	v_min_f32_e32 v26, 0, v26
	v_min_f32_e32 v27, 0, v27
	v_add_f32_e32 v28, 1.0, v28
	v_add_f32_e32 v29, 1.0, v29
	v_add_f32_e32 v30, 1.0, v30
	v_add_f32_e32 v31, 1.0, v31
	v_add_f32_e32 v32, 1.0, v32
	v_add_f32_e32 v33, 1.0, v33
	v_add_f32_e32 v34, 1.0, v34
	v_add_f32_e32 v35, 1.0, v35
	v_log_f32_e32 v28, v28
	v_log_f32_e32 v29, v29
	v_log_f32_e32 v30, v30
	v_log_f32_e32 v31, v31
	v_log_f32_e32 v32, v32
	v_log_f32_e32 v33, v33
	v_log_f32_e32 v34, v34
	v_log_f32_e32 v35, v35
	v_fma_f32 v2, v20, s7, -v28
	v_fma_f32 v4, v21, s7, -v29
	v_fma_f32 v6, v22, s7, -v30
	v_fma_f32 v5, v23, s7, -v31
	v_fma_f32 v11, v24, s7, -v32
	v_fma_f32 v7, v25, s7, -v33
	v_fma_f32 v13, v26, s7, -v34
	v_fma_f32 v12, v27, s7, -v35
	v_add_f32_e32 v2, 0, v2
.Lfoxscan_done:
	s_or_b64 exec, exec, s[0:1]
	s_waitcnt vmcnt(0)
	v_add_f32_e32 v3, v2, v4
	v_add_f32_e32 v8, v3, v6
	v_add_f32_e32 v9, v8, v5
	v_add_f32_e32 v6, v9, v11
	v_add_f32_e32 v7, v6, v7
	v_add_f32_e32 v4, v7, v13
	v_and_b32_e32 v13, 64, v243
	v_add_u32_e32 v11, -1, v243
	v_cmp_lt_i32_e64 s[0:1], v11, v13
	v_add_f32_e32 v5, v4, v12
	v_add_u32_e32 v14, -2, v243
	v_cndmask_b32_e64 v11, v11, v243, s[0:1]
	v_lshlrev_b32_e32 v11, 2, v11
	ds_bpermute_b32 v12, v11, v5
	v_and_b32_e32 v11, 63, v10
	v_cmp_eq_u32_e64 s[0:1], 0, v11
	s_ashr_i32 s2, s2, 6
	s_waitcnt lgkmcnt(0)
	v_add_f32_e32 v12, v5, v12
	v_cndmask_b32_e64 v12, v12, v5, s[0:1]
	v_cmp_lt_i32_e64 s[0:1], v14, v13
	s_nop 1
	v_cndmask_b32_e64 v14, v14, v243, s[0:1]
	v_lshlrev_b32_e32 v14, 2, v14
	ds_bpermute_b32 v14, v14, v12
	v_cmp_gt_u32_e64 s[0:1], 2, v11
	s_waitcnt lgkmcnt(0)
	v_add_f32_e32 v14, v12, v14
	v_cndmask_b32_e64 v12, v14, v12, s[0:1]
	v_add_u32_e32 v14, -4, v243
	v_cmp_lt_i32_e64 s[0:1], v14, v13
	s_nop 1
	v_cndmask_b32_e64 v14, v14, v243, s[0:1]
	v_lshlrev_b32_e32 v14, 2, v14
	ds_bpermute_b32 v14, v14, v12
	v_cmp_gt_u32_e64 s[0:1], 4, v11
	s_waitcnt lgkmcnt(0)
	v_add_f32_e32 v14, v12, v14
	v_cndmask_b32_e64 v12, v14, v12, s[0:1]
	v_add_u32_e32 v14, -8, v243
	v_cmp_lt_i32_e64 s[0:1], v14, v13
	s_nop 1
	v_cndmask_b32_e64 v14, v14, v243, s[0:1]
	v_lshlrev_b32_e32 v14, 2, v14
	ds_bpermute_b32 v14, v14, v12
	v_cmp_gt_u32_e64 s[0:1], 8, v11
	s_waitcnt lgkmcnt(0)
	v_add_f32_e32 v14, v12, v14
	v_cndmask_b32_e64 v12, v14, v12, s[0:1]
	v_add_u32_e32 v14, -16, v243
	v_cmp_lt_i32_e64 s[0:1], v14, v13
	s_nop 1
	v_cndmask_b32_e64 v14, v14, v243, s[0:1]
	v_lshlrev_b32_e32 v14, 2, v14
	ds_bpermute_b32 v14, v14, v12
	v_cmp_gt_u32_e64 s[0:1], 16, v11
	s_waitcnt lgkmcnt(0)
	v_add_f32_e32 v14, v12, v14
	v_cndmask_b32_e64 v12, v14, v12, s[0:1]
	v_subrev_u32_e32 v14, 32, v243
	v_cmp_lt_i32_e64 s[0:1], v14, v13
	s_nop 1
	v_cndmask_b32_e64 v13, v14, v243, s[0:1]
	v_lshlrev_b32_e32 v13, 2, v13
	ds_bpermute_b32 v13, v13, v12
	v_cmp_eq_u32_e64 s[0:1], 63, v11
	s_waitcnt lgkmcnt(0)
	v_add_f32_e32 v13, v12, v13
	s_and_saveexec_b64 s[4:5], s[0:1]
	s_lshl_b32 s0, s2, 2
	s_add_i32 s0, s0, 0
	s_add_i32 s0, s0, 0x15800
	v_mov_b32_e32 v14, s0
	ds_write_b32 v14, v13
	s_or_b64 exec, exec, s[4:5]
	s_cmp_gt_i32 s2, 0
	s_waitcnt lgkmcnt(0)
	s_barrier
	s_cbranch_scc0 .LBB0_856
	s_add_i32 s0, 0, 0x15800
	v_mov_b32_e32 v14, s0
	ds_read_b32 v14, v14
	s_waitcnt lgkmcnt(0)
	v_add_f32_e32 v14, 0, v14
	s_cmp_lt_i32 s2, 2
	s_cbranch_scc1 .LBB0_652

; #define LAS __attribute__((address_space(3)))
; #define MFMA32(a, b, c) __builtin_amdgcn_mfma_f32_32x32x16_bf16((a), (b), (c), 0, 0, 0)
; template <int MODE> __device__ __forceinline__ void attn_unit(LAS unsigned char* lds, const AttnP& P, int b, int h, int qb) {
;     ...
;                 { f32x16 a0 = negm1, a1 = negm1;
; #pragma unroll
;                   for (int c = 0; c < 2; ++c) { const bf16x8 k0 = *(const LAS bf16x8*)(kb_ + c * 32), k1 = *(const LAS bf16x8*)(kb_ + 32 * ROWB + c * 32); a0 = MFMA32(k0, qf[c], a0); a1 = MFMA32(k1, qf[c], a1); }
;                   if (64 * t + 63 > q0w) { int dd = dlt0; asm volatile("" : "+v"(dd)); causal_mask(a0, a1, dd); }
.LBB0_804:
	v_add_u32_e32 v210, s2, v219
	ds_read_b128 v[114:117], v210
	ds_read_b128 v[130:133], v210 offset:4608
	ds_read_b128 v[232:235], v210 offset:32
	ds_read_b128 v[236:239], v210 offset:4640
	s_add_i32 s0, s27, 63
	s_cmp_gt_i32 s0, s26
	s_cselect_b64 s[20:21], -1, 0
	s_cmp_le_i32 s0, s26
	s_waitcnt lgkmcnt(3)
	v_mfma_f32_32x32x16_bf16 v[98:113], v[114:117], v[178:181], v[82:97]
	s_waitcnt lgkmcnt(2)
	v_mfma_f32_32x32x16_bf16 v[114:129], v[130:133], v[178:181], v[82:97]
	s_waitcnt lgkmcnt(1)
	v_mfma_f32_32x32x16_bf16 v[98:113], v[232:235], v[182:185], v[98:113]
	s_waitcnt lgkmcnt(0)
	v_mfma_f32_32x32x16_bf16 v[114:129], v[236:239], v[182:185], v[114:129]
	s_cbranch_scc1 .LBB0_806
	v_mov_b32_e32 v130, v221
	s_nop 0
	v_cmp_gt_i32_e64 s[0:1], 26, v130
	v_cmp_gt_i32_e32 vcc, 27, v130
	v_cmp_gt_i32_e64 s[96:97], 25, v130
	v_cmp_gt_i32_e64 s[94:95], 24, v130
	s_nop 1
	v_cndmask_b32_e32 v113, v113, v246, vcc
	s_and_b64 vcc, vcc, s[0:1]
	v_cndmask_b32_e32 v112, v112, v246, vcc
	s_and_b64 vcc, vcc, s[96:97]
	v_cmp_gt_i32_e64 s[92:93], 19, v130
	v_cndmask_b32_e32 v111, v111, v246, vcc
	s_and_b64 vcc, vcc, s[94:95]
	v_cmp_gt_i32_e64 s[90:91], 18, v130
	v_cndmask_b32_e32 v110, v110, v246, vcc
	s_and_b64 vcc, vcc, s[92:93]
	v_cmp_gt_i32_e64 s[88:89], 17, v130
	v_cndmask_b32_e32 v109, v109, v246, vcc
	s_and_b64 vcc, vcc, s[90:91]
	v_cmp_gt_i32_e64 s[86:87], 16, v130
	v_cndmask_b32_e32 v108, v108, v246, vcc
	s_and_b64 vcc, vcc, s[88:89]
	v_cmp_gt_i32_e64 s[84:85], 11, v130
	v_cndmask_b32_e32 v107, v107, v246, vcc
	s_and_b64 vcc, vcc, s[86:87]
	v_cmp_gt_i32_e64 s[82:83], 10, v130
	v_cndmask_b32_e32 v106, v106, v246, vcc
	s_and_b64 vcc, vcc, s[84:85]
	v_cmp_gt_i32_e64 s[80:81], 9, v130
	v_cndmask_b32_e32 v105, v105, v246, vcc
	s_and_b64 vcc, vcc, s[82:83]
	v_cmp_gt_i32_e64 s[78:79], 8, v130
	v_cndmask_b32_e32 v104, v104, v246, vcc
	s_and_b64 vcc, vcc, s[80:81]
	v_cmp_gt_i32_e64 s[76:77], 3, v130
	v_cndmask_b32_e32 v103, v103, v246, vcc
	s_and_b64 vcc, vcc, s[78:79]
	v_cmp_gt_i32_e64 s[74:75], 2, v130
	v_cndmask_b32_e32 v102, v102, v246, vcc
	s_and_b64 vcc, vcc, s[76:77]
	v_cmp_gt_i32_e64 s[72:73], 1, v130
	v_cndmask_b32_e32 v101, v101, v246, vcc
	s_and_b64 vcc, vcc, s[74:75]
	v_cmp_gt_i32_e64 s[68:69], 0, v130
	v_cndmask_b32_e32 v100, v100, v246, vcc
	s_and_b64 vcc, vcc, s[72:73]
	v_cndmask_b32_e32 v99, v99, v246, vcc
	s_and_b64 vcc, vcc, s[68:69]
	v_cmp_gt_i32_e64 s[66:67], 58, v130
	v_cndmask_b32_e32 v98, v98, v246, vcc
	v_cmp_gt_i32_e32 vcc, 59, v130
	v_cmp_gt_i32_e64 s[64:65], 57, v130
	v_cmp_gt_i32_e64 s[62:63], 56, v130
	v_cndmask_b32_e32 v129, v129, v246, vcc
	s_and_b64 vcc, vcc, s[66:67]
	v_cndmask_b32_e32 v128, v128, v246, vcc
	s_and_b64 vcc, vcc, s[64:65]
	v_cmp_gt_i32_e64 s[60:61], 51, v130
	v_cndmask_b32_e32 v127, v127, v246, vcc
	s_and_b64 vcc, vcc, s[62:63]
	v_cmp_gt_i32_e64 s[58:59], 50, v130
	v_cndmask_b32_e32 v126, v126, v246, vcc
	s_and_b64 vcc, vcc, s[60:61]
	v_cmp_gt_i32_e64 s[56:57], 49, v130
	v_cndmask_b32_e32 v125, v125, v246, vcc
	s_and_b64 vcc, vcc, s[58:59]
	v_cmp_gt_i32_e64 s[54:55], 48, v130
	v_cndmask_b32_e32 v124, v124, v246, vcc
	s_and_b64 vcc, vcc, s[56:57]
	v_cmp_gt_i32_e64 s[52:53], 43, v130
	v_cndmask_b32_e32 v123, v123, v246, vcc
	s_and_b64 vcc, vcc, s[54:55]
	v_cmp_gt_i32_e64 s[50:51], 42, v130
	v_cndmask_b32_e32 v122, v122, v246, vcc
	s_and_b64 vcc, vcc, s[52:53]
	v_cmp_gt_i32_e64 s[48:49], 41, v130
	v_cndmask_b32_e32 v121, v121, v246, vcc
	s_and_b64 vcc, vcc, s[50:51]
	v_cmp_gt_i32_e64 s[46:47], 40, v130
	v_cndmask_b32_e32 v120, v120, v246, vcc
	s_and_b64 vcc, vcc, s[48:49]
	v_cmp_gt_i32_e64 s[44:45], 35, v130
	v_cndmask_b32_e32 v119, v119, v246, vcc
	s_and_b64 vcc, vcc, s[46:47]
	v_cmp_gt_i32_e64 s[42:43], 34, v130
	v_cndmask_b32_e32 v118, v118, v246, vcc
	s_and_b64 vcc, vcc, s[44:45]
	v_cmp_gt_i32_e64 s[40:41], 33, v130
	v_cndmask_b32_e32 v117, v117, v246, vcc
	s_and_b64 vcc, vcc, s[42:43]
	v_cmp_gt_i32_e64 s[4:5], 32, v130
	v_cndmask_b32_e32 v116, v116, v246, vcc
	s_and_b64 vcc, vcc, s[40:41]
	v_cndmask_b32_e32 v115, v115, v246, vcc
	s_and_b64 vcc, vcc, s[4:5]
	v_cndmask_b32_e32 v114, v114, v246, vcc

; #define LAS __attribute__((address_space(3)))
; #define MFMA32(a, b, c) __builtin_amdgcn_mfma_f32_32x32x16_bf16((a), (b), (c), 0, 0, 0)
; template <int MODE> __device__ __forceinline__ void attn_unit(LAS unsigned char* lds, const AttnP& P, int b, int h, int qb) {
;     ...
;                 { f32x16 b0 = negm2, b1 = negm2;
; #pragma unroll
;                   for (int c = 2; c < 4; ++c) { const bf16x8 k0 = *(const LAS bf16x8*)(kb_ + c * 32), k1 = *(const LAS bf16x8*)(kb_ + 32 * ROWB + c * 32); b0 = MFMA32(k0, qf[c], b0); b1 = MFMA32(k1, qf[c], b1); }
;                   if (64 * t + 63 > q0w) { int dd = dlt0; asm volatile("" : "+v"(dd)); causal_mask(b0, b1, dd); }
.LBB0_813:
	ds_read_b128 v[146:149], v210 offset:64
	ds_read_b128 v[224:227], v210 offset:4672
	ds_read_b128 v[232:235], v210 offset:96
	ds_read_b128 v[236:239], v210 offset:4704
	s_andn2_b64 vcc, exec, s[20:21]
	s_waitcnt lgkmcnt(3)
	v_mfma_f32_32x32x16_bf16 v[130:145], v[146:149], v[186:189], v[66:81]
	s_waitcnt lgkmcnt(2)
	v_mfma_f32_32x32x16_bf16 v[146:161], v[224:227], v[186:189], v[66:81]
	s_waitcnt lgkmcnt(1)
	v_mfma_f32_32x32x16_bf16 v[130:145], v[232:235], v[190:193], v[130:145]
	s_waitcnt lgkmcnt(0)
	v_mfma_f32_32x32x16_bf16 v[146:161], v[236:239], v[190:193], v[146:161]
	s_cbranch_vccnz .LBB0_815
	v_mov_b32_e32 v194, v221
	s_nop 0
	v_cmp_gt_i32_e64 s[94:95], 26, v194
	v_cmp_gt_i32_e64 s[96:97], 27, v194
	v_cmp_gt_i32_e64 s[92:93], 25, v194
	s_and_b64 s[94:95], s[96:97], s[94:95]
	v_cmp_gt_i32_e64 s[90:91], 24, v194
	s_and_b64 s[92:93], s[94:95], s[92:93]
	v_cmp_gt_i32_e64 s[88:89], 19, v194
	s_and_b64 s[90:91], s[92:93], s[90:91]
	v_cmp_gt_i32_e64 s[86:87], 18, v194
	s_and_b64 s[88:89], s[90:91], s[88:89]
	v_cmp_gt_i32_e64 s[84:85], 17, v194
	s_and_b64 s[86:87], s[88:89], s[86:87]
	v_cmp_gt_i32_e64 s[82:83], 16, v194
	s_and_b64 s[84:85], s[86:87], s[84:85]
	v_cmp_gt_i32_e64 s[80:81], 11, v194
	s_and_b64 s[82:83], s[84:85], s[82:83]
	v_cmp_gt_i32_e64 s[78:79], 10, v194
	s_and_b64 s[80:81], s[82:83], s[80:81]
	v_cmp_gt_i32_e64 s[76:77], 9, v194
	s_and_b64 s[78:79], s[80:81], s[78:79]
	v_cmp_gt_i32_e64 s[74:75], 8, v194
	s_and_b64 s[76:77], s[78:79], s[76:77]
	v_cmp_gt_i32_e64 s[72:73], 3, v194
	s_and_b64 s[74:75], s[76:77], s[74:75]
	v_cmp_gt_i32_e64 s[68:69], 2, v194
	s_and_b64 s[72:73], s[74:75], s[72:73]
	v_cmp_gt_i32_e64 s[4:5], 1, v194
	s_and_b64 s[68:69], s[72:73], s[68:69]
	v_cmp_gt_i32_e64 s[0:1], 0, v194
	s_and_b64 s[4:5], s[68:69], s[4:5]
	s_and_b64 s[0:1], s[4:5], s[0:1]
	v_cmp_gt_i32_e64 s[66:67], 58, v194
	v_cndmask_b32_e64 v130, v130, v246, s[0:1]
	v_cmp_gt_i32_e64 s[0:1], 59, v194
	v_cmp_gt_i32_e64 s[64:65], 57, v194
	v_cmp_gt_i32_e64 s[62:63], 56, v194
	v_cndmask_b32_e64 v161, v161, v246, s[0:1]
	s_and_b64 s[0:1], s[0:1], s[66:67]
	v_cndmask_b32_e64 v160, v160, v246, s[0:1]
	s_and_b64 s[0:1], s[0:1], s[64:65]
	v_cmp_gt_i32_e64 s[60:61], 51, v194
	v_cndmask_b32_e64 v159, v159, v246, s[0:1]
	s_and_b64 s[0:1], s[0:1], s[62:63]
	v_cmp_gt_i32_e64 s[58:59], 50, v194
	v_cndmask_b32_e64 v158, v158, v246, s[0:1]
	s_and_b64 s[0:1], s[0:1], s[60:61]
	v_cmp_gt_i32_e64 s[56:57], 49, v194
	v_cndmask_b32_e64 v157, v157, v246, s[0:1]
	s_and_b64 s[0:1], s[0:1], s[58:59]
	v_cmp_gt_i32_e64 s[54:55], 48, v194
	v_cndmask_b32_e64 v156, v156, v246, s[0:1]
	s_and_b64 s[0:1], s[0:1], s[56:57]
	v_cmp_gt_i32_e64 s[52:53], 43, v194
	v_cndmask_b32_e64 v155, v155, v246, s[0:1]
	s_and_b64 s[0:1], s[0:1], s[54:55]
	v_cmp_gt_i32_e64 s[50:51], 42, v194
	v_cndmask_b32_e64 v154, v154, v246, s[0:1]
	s_and_b64 s[0:1], s[0:1], s[52:53]
	v_cmp_gt_i32_e64 s[48:49], 41, v194
	v_cndmask_b32_e64 v153, v153, v246, s[0:1]
	s_and_b64 s[0:1], s[0:1], s[50:51]
	v_cmp_gt_i32_e64 s[46:47], 40, v194
	v_cndmask_b32_e64 v152, v152, v246, s[0:1]
	s_and_b64 s[0:1], s[0:1], s[48:49]
	v_cmp_gt_i32_e64 s[44:45], 35, v194
	v_cndmask_b32_e64 v151, v151, v246, s[0:1]
	s_and_b64 s[0:1], s[0:1], s[46:47]
	v_cmp_gt_i32_e64 s[42:43], 34, v194
	v_cndmask_b32_e64 v150, v150, v246, s[0:1]
	s_and_b64 s[0:1], s[0:1], s[44:45]
	v_cmp_gt_i32_e64 s[40:41], 33, v194
	v_cndmask_b32_e64 v149, v149, v246, s[0:1]
	s_and_b64 s[0:1], s[0:1], s[42:43]
	v_cmp_gt_i32_e32 vcc, 32, v194
	v_cndmask_b32_e64 v148, v148, v246, s[0:1]
	s_and_b64 s[0:1], s[0:1], s[40:41]
	s_and_b64 vcc, s[0:1], vcc
	v_cndmask_b32_e64 v145, v145, v246, s[96:97]
	v_cndmask_b32_e64 v144, v144, v246, s[94:95]
	v_cndmask_b32_e64 v143, v143, v246, s[92:93]
	v_cndmask_b32_e64 v142, v142, v246, s[90:91]
	v_cndmask_b32_e64 v141, v141, v246, s[88:89]
	v_cndmask_b32_e64 v140, v140, v246, s[86:87]
	v_cndmask_b32_e64 v139, v139, v246, s[84:85]
	v_cndmask_b32_e64 v138, v138, v246, s[82:83]
	v_cndmask_b32_e64 v137, v137, v246, s[80:81]
	v_cndmask_b32_e64 v136, v136, v246, s[78:79]
	v_cndmask_b32_e64 v135, v135, v246, s[76:77]
	v_cndmask_b32_e64 v134, v134, v246, s[74:75]
	v_cndmask_b32_e64 v133, v133, v246, s[72:73]
	v_cndmask_b32_e64 v132, v132, v246, s[68:69]
	v_cndmask_b32_e64 v131, v131, v246, s[4:5]
	v_cndmask_b32_e64 v147, v147, v246, s[0:1]
	v_cndmask_b32_e32 v146, v146, v246, vcc

; #define LAS __attribute__((address_space(3)))
; #define MFMA32(a, b, c) __builtin_amdgcn_mfma_f32_32x32x16_bf16((a), (b), (c), 0, 0, 0)
; __device__ __forceinline__ void causal_mask(f32x16& p0, f32x16& p1, int dlt0  ) {
; #pragma unroll
;     for (int r = 0; r < 16; ++r) { const int d0 = dlt0 - ((r & 3) + 8 * (r >> 2)); if (d0 < 0) p0[r] = -1e30f; if (d0 - 32 < 0) p1[r] = -1e30f; }
; }
; template <int MODE> __device__ __forceinline__ void attn_unit(LAS unsigned char* lds, const AttnP& P, int b, int h, int qb) {
;     ...
;                 { f32x16 a0 = negm1, a1 = negm1;
; #pragma unroll
;                   for (int c = 0; c < 2; ++c) { const bf16x8 k0 = *(const LAS bf16x8*)(kb_ + c * 32), k1 = *(const LAS bf16x8*)(kb_ + 32 * ROWB + c * 32); a0 = MFMA32(k0, qf[c], a0); a1 = MFMA32(k1, qf[c], a1); }
;                   if (64 * t + 63 > q0w) { int dd = dlt0; asm volatile("" : "+v"(dd)); causal_mask(a0, a1, dd); }
.LBB0_823:
	s_add_i32 s2, s2, 0
	v_add_u32_e32 v224, s2, v215
	ds_read_b128 v[114:117], v224 offset:9216
	ds_read_b128 v[130:133], v224 offset:13824
	ds_read_b128 v[232:235], v224 offset:9248
	ds_read_b128 v[236:239], v224 offset:13856
	s_add_i32 s0, s27, 0x7f
	s_cmp_gt_i32 s0, s26
	v_subrev_u32_e32 v210, 64, v221
	s_cselect_b64 s[20:21], -1, 0
	s_cmp_le_i32 s0, s26
	s_waitcnt lgkmcnt(3)
	v_mfma_f32_32x32x16_bf16 v[98:113], v[114:117], v[178:181], v[82:97]
	s_waitcnt lgkmcnt(2)
	v_mfma_f32_32x32x16_bf16 v[114:129], v[130:133], v[178:181], v[82:97]
	s_waitcnt lgkmcnt(1)
	v_mfma_f32_32x32x16_bf16 v[98:113], v[232:235], v[182:185], v[98:113]
	s_waitcnt lgkmcnt(0)
	v_mfma_f32_32x32x16_bf16 v[114:129], v[236:239], v[182:185], v[114:129]
	s_cbranch_scc1 .LBB0_825
	v_mov_b32_e32 v130, v210
	s_nop 0
	v_cmp_gt_i32_e64 s[94:95], 26, v130
	v_cmp_gt_i32_e64 s[96:97], 27, v130
	v_cmp_gt_i32_e64 s[92:93], 25, v130
	s_and_b64 s[94:95], s[96:97], s[94:95]
	v_cmp_gt_i32_e64 s[90:91], 24, v130
	s_and_b64 s[92:93], s[94:95], s[92:93]
	v_cmp_gt_i32_e64 s[88:89], 19, v130
	s_and_b64 s[90:91], s[92:93], s[90:91]
	v_cmp_gt_i32_e64 s[86:87], 18, v130
	s_and_b64 s[88:89], s[90:91], s[88:89]
	v_cmp_gt_i32_e64 s[84:85], 17, v130
	s_and_b64 s[86:87], s[88:89], s[86:87]
	v_cmp_gt_i32_e64 s[82:83], 16, v130
	s_and_b64 s[84:85], s[86:87], s[84:85]
	v_cmp_gt_i32_e64 s[80:81], 11, v130
	s_and_b64 s[82:83], s[84:85], s[82:83]
	v_cmp_gt_i32_e64 s[78:79], 10, v130
	s_and_b64 s[80:81], s[82:83], s[80:81]
	v_cmp_gt_i32_e64 s[76:77], 9, v130
	s_and_b64 s[78:79], s[80:81], s[78:79]
	v_cmp_gt_i32_e64 s[74:75], 8, v130
	s_and_b64 s[76:77], s[78:79], s[76:77]
	v_cmp_gt_i32_e64 s[72:73], 3, v130
	s_and_b64 s[74:75], s[76:77], s[74:75]
	v_cmp_gt_i32_e64 s[68:69], 2, v130
	s_and_b64 s[72:73], s[74:75], s[72:73]
	v_cmp_gt_i32_e64 s[4:5], 1, v130
	s_and_b64 s[68:69], s[72:73], s[68:69]
	v_cmp_gt_i32_e64 s[0:1], 0, v130
	s_and_b64 s[4:5], s[68:69], s[4:5]
	s_and_b64 s[0:1], s[4:5], s[0:1]
	v_cmp_gt_i32_e64 s[66:67], 58, v130
	v_cndmask_b32_e64 v98, v98, v246, s[0:1]
	v_cmp_gt_i32_e64 s[0:1], 59, v130
	v_cmp_gt_i32_e64 s[64:65], 57, v130
	v_cmp_gt_i32_e64 s[62:63], 56, v130
	v_cndmask_b32_e64 v129, v129, v246, s[0:1]
	s_and_b64 s[0:1], s[0:1], s[66:67]
	v_cndmask_b32_e64 v128, v128, v246, s[0:1]
	s_and_b64 s[0:1], s[0:1], s[64:65]
	v_cmp_gt_i32_e64 s[60:61], 51, v130
	v_cndmask_b32_e64 v127, v127, v246, s[0:1]
	s_and_b64 s[0:1], s[0:1], s[62:63]
	v_cmp_gt_i32_e64 s[58:59], 50, v130
	v_cndmask_b32_e64 v126, v126, v246, s[0:1]
	s_and_b64 s[0:1], s[0:1], s[60:61]
	v_cmp_gt_i32_e64 s[56:57], 49, v130
	v_cndmask_b32_e64 v125, v125, v246, s[0:1]
	s_and_b64 s[0:1], s[0:1], s[58:59]
	v_cmp_gt_i32_e64 s[54:55], 48, v130
	v_cndmask_b32_e64 v124, v124, v246, s[0:1]
	s_and_b64 s[0:1], s[0:1], s[56:57]
	v_cmp_gt_i32_e64 s[52:53], 43, v130
	v_cndmask_b32_e64 v123, v123, v246, s[0:1]
	s_and_b64 s[0:1], s[0:1], s[54:55]
	v_cmp_gt_i32_e64 s[50:51], 42, v130
	v_cndmask_b32_e64 v122, v122, v246, s[0:1]
	s_and_b64 s[0:1], s[0:1], s[52:53]
	v_cmp_gt_i32_e64 s[48:49], 41, v130
	v_cndmask_b32_e64 v121, v121, v246, s[0:1]
	s_and_b64 s[0:1], s[0:1], s[50:51]
	v_cmp_gt_i32_e64 s[46:47], 40, v130
	v_cndmask_b32_e64 v120, v120, v246, s[0:1]
	s_and_b64 s[0:1], s[0:1], s[48:49]
	v_cmp_gt_i32_e64 s[44:45], 35, v130
	v_cndmask_b32_e64 v119, v119, v246, s[0:1]
	s_and_b64 s[0:1], s[0:1], s[46:47]
	v_cmp_gt_i32_e64 s[42:43], 34, v130
	v_cndmask_b32_e64 v118, v118, v246, s[0:1]
	s_and_b64 s[0:1], s[0:1], s[44:45]
	v_cmp_gt_i32_e64 s[40:41], 33, v130
	v_cndmask_b32_e64 v117, v117, v246, s[0:1]
	s_and_b64 s[0:1], s[0:1], s[42:43]
	v_cmp_gt_i32_e32 vcc, 32, v130
	v_cndmask_b32_e64 v116, v116, v246, s[0:1]
	s_and_b64 s[0:1], s[0:1], s[40:41]
	s_and_b64 vcc, s[0:1], vcc
	v_cndmask_b32_e64 v113, v113, v246, s[96:97]
	v_cndmask_b32_e64 v112, v112, v246, s[94:95]
	v_cndmask_b32_e64 v111, v111, v246, s[92:93]
	v_cndmask_b32_e64 v110, v110, v246, s[90:91]
	v_cndmask_b32_e64 v109, v109, v246, s[88:89]
	v_cndmask_b32_e64 v108, v108, v246, s[86:87]
	v_cndmask_b32_e64 v107, v107, v246, s[84:85]
	v_cndmask_b32_e64 v106, v106, v246, s[82:83]
	v_cndmask_b32_e64 v105, v105, v246, s[80:81]
	v_cndmask_b32_e64 v104, v104, v246, s[78:79]
	v_cndmask_b32_e64 v103, v103, v246, s[76:77]
	v_cndmask_b32_e64 v102, v102, v246, s[74:75]
	v_cndmask_b32_e64 v101, v101, v246, s[72:73]
	v_cndmask_b32_e64 v100, v100, v246, s[68:69]
	v_cndmask_b32_e64 v99, v99, v246, s[4:5]
	v_cndmask_b32_e64 v115, v115, v246, s[0:1]
	v_cndmask_b32_e32 v114, v114, v246, vcc

; #define LAS __attribute__((address_space(3)))
; #define MFMA32(a, b, c) __builtin_amdgcn_mfma_f32_32x32x16_bf16((a), (b), (c), 0, 0, 0)
; __device__ __forceinline__ void causal_mask(f32x16& p0, f32x16& p1, int dlt0  ) {
; #pragma unroll
;     for (int r = 0; r < 16; ++r) { const int d0 = dlt0 - ((r & 3) + 8 * (r >> 2)); if (d0 < 0) p0[r] = -1e30f; if (d0 - 32 < 0) p1[r] = -1e30f; }
; }
; template <int MODE> __device__ __forceinline__ void attn_unit(LAS unsigned char* lds, const AttnP& P, int b, int h, int qb) {
;     ...
;                 { f32x16 b0 = negm2, b1 = negm2;
; #pragma unroll
;                   for (int c = 2; c < 4; ++c) { const bf16x8 k0 = *(const LAS bf16x8*)(kb_ + c * 32), k1 = *(const LAS bf16x8*)(kb_ + 32 * ROWB + c * 32); b0 = MFMA32(k0, qf[c], b0); b1 = MFMA32(k1, qf[c], b1); }
;                   if (64 * t + 63 > q0w) { int dd = dlt0; asm volatile("" : "+v"(dd)); causal_mask(b0, b1, dd); }
.LBB0_832:
	ds_read_b128 v[146:149], v224 offset:9280
	ds_read_b128 v[226:229], v224 offset:13888
	ds_read_b128 v[232:235], v224 offset:9312
	ds_read_b128 v[236:239], v224 offset:13920
	s_andn2_b64 vcc, exec, s[20:21]
	s_waitcnt lgkmcnt(3)
	v_mfma_f32_32x32x16_bf16 v[130:145], v[146:149], v[186:189], v[66:81]
	s_waitcnt lgkmcnt(2)
	v_mfma_f32_32x32x16_bf16 v[146:161], v[226:229], v[186:189], v[66:81]
	s_waitcnt lgkmcnt(1)
	v_mfma_f32_32x32x16_bf16 v[130:145], v[232:235], v[190:193], v[130:145]
	s_waitcnt lgkmcnt(0)
	v_mfma_f32_32x32x16_bf16 v[146:161], v[236:239], v[190:193], v[146:161]
	s_cbranch_vccnz .LBB0_834
	s_nop 0
	v_cmp_gt_i32_e64 s[94:95], 26, v210
	v_cmp_gt_i32_e64 s[96:97], 27, v210
	v_cmp_gt_i32_e64 s[92:93], 25, v210
	s_and_b64 s[94:95], s[96:97], s[94:95]
	v_cmp_gt_i32_e64 s[90:91], 24, v210
	s_and_b64 s[92:93], s[94:95], s[92:93]
	v_cmp_gt_i32_e64 s[88:89], 19, v210
	s_and_b64 s[90:91], s[92:93], s[90:91]
	v_cmp_gt_i32_e64 s[86:87], 18, v210
	s_and_b64 s[88:89], s[90:91], s[88:89]
	v_cmp_gt_i32_e64 s[84:85], 17, v210
	s_and_b64 s[86:87], s[88:89], s[86:87]
	v_cmp_gt_i32_e64 s[82:83], 16, v210
	s_and_b64 s[84:85], s[86:87], s[84:85]
	v_cmp_gt_i32_e64 s[80:81], 11, v210
	s_and_b64 s[82:83], s[84:85], s[82:83]
	v_cmp_gt_i32_e64 s[78:79], 10, v210
	s_and_b64 s[80:81], s[82:83], s[80:81]
	v_cmp_gt_i32_e64 s[76:77], 9, v210
	s_and_b64 s[78:79], s[80:81], s[78:79]
	v_cmp_gt_i32_e64 s[74:75], 8, v210
	s_and_b64 s[76:77], s[78:79], s[76:77]
	v_cmp_gt_i32_e64 s[72:73], 3, v210
	s_and_b64 s[74:75], s[76:77], s[74:75]
	v_cmp_gt_i32_e64 s[68:69], 2, v210
	s_and_b64 s[72:73], s[74:75], s[72:73]
	v_cmp_gt_i32_e64 s[4:5], 1, v210
	s_and_b64 s[68:69], s[72:73], s[68:69]
	v_cmp_gt_i32_e64 s[0:1], 0, v210
	s_and_b64 s[4:5], s[68:69], s[4:5]
	s_and_b64 s[0:1], s[4:5], s[0:1]
	v_cmp_gt_i32_e64 s[66:67], 58, v210
	v_cndmask_b32_e64 v130, v130, v246, s[0:1]
	v_cmp_gt_i32_e64 s[0:1], 59, v210
	v_cmp_gt_i32_e64 s[64:65], 57, v210
	v_cmp_gt_i32_e64 s[62:63], 56, v210
	v_cndmask_b32_e64 v161, v161, v246, s[0:1]
	s_and_b64 s[0:1], s[0:1], s[66:67]
	v_cndmask_b32_e64 v160, v160, v246, s[0:1]
	s_and_b64 s[0:1], s[0:1], s[64:65]
	v_cmp_gt_i32_e64 s[60:61], 51, v210
	v_cndmask_b32_e64 v159, v159, v246, s[0:1]
	s_and_b64 s[0:1], s[0:1], s[62:63]
	v_cmp_gt_i32_e64 s[58:59], 50, v210
	v_cndmask_b32_e64 v158, v158, v246, s[0:1]
	s_and_b64 s[0:1], s[0:1], s[60:61]
	v_cmp_gt_i32_e64 s[56:57], 49, v210
	v_cndmask_b32_e64 v157, v157, v246, s[0:1]
	s_and_b64 s[0:1], s[0:1], s[58:59]
	v_cmp_gt_i32_e64 s[54:55], 48, v210
	v_cndmask_b32_e64 v156, v156, v246, s[0:1]
	s_and_b64 s[0:1], s[0:1], s[56:57]
	v_cmp_gt_i32_e64 s[52:53], 43, v210
	v_cndmask_b32_e64 v155, v155, v246, s[0:1]
	s_and_b64 s[0:1], s[0:1], s[54:55]
	v_cmp_gt_i32_e64 s[50:51], 42, v210
	v_cndmask_b32_e64 v154, v154, v246, s[0:1]
	s_and_b64 s[0:1], s[0:1], s[52:53]
	v_cmp_gt_i32_e64 s[48:49], 41, v210
	v_cndmask_b32_e64 v153, v153, v246, s[0:1]
	s_and_b64 s[0:1], s[0:1], s[50:51]
	v_cmp_gt_i32_e64 s[46:47], 40, v210
	v_cndmask_b32_e64 v152, v152, v246, s[0:1]
	s_and_b64 s[0:1], s[0:1], s[48:49]
	v_cmp_gt_i32_e64 s[44:45], 35, v210
	v_cndmask_b32_e64 v151, v151, v246, s[0:1]
	s_and_b64 s[0:1], s[0:1], s[46:47]
	v_cmp_gt_i32_e64 s[42:43], 34, v210
	v_cndmask_b32_e64 v150, v150, v246, s[0:1]
	s_and_b64 s[0:1], s[0:1], s[44:45]
	v_cmp_gt_i32_e64 s[40:41], 33, v210
	v_cndmask_b32_e64 v149, v149, v246, s[0:1]
	s_and_b64 s[0:1], s[0:1], s[42:43]
	v_cmp_gt_i32_e32 vcc, 32, v210
	v_cndmask_b32_e64 v148, v148, v246, s[0:1]
	s_and_b64 s[0:1], s[0:1], s[40:41]
	s_and_b64 vcc, s[0:1], vcc
	v_cndmask_b32_e64 v145, v145, v246, s[96:97]
	v_cndmask_b32_e64 v144, v144, v246, s[94:95]
	v_cndmask_b32_e64 v143, v143, v246, s[92:93]
	v_cndmask_b32_e64 v142, v142, v246, s[90:91]
	v_cndmask_b32_e64 v141, v141, v246, s[88:89]
	v_cndmask_b32_e64 v140, v140, v246, s[86:87]
	v_cndmask_b32_e64 v139, v139, v246, s[84:85]
	v_cndmask_b32_e64 v138, v138, v246, s[82:83]
	v_cndmask_b32_e64 v137, v137, v246, s[80:81]
	v_cndmask_b32_e64 v136, v136, v246, s[78:79]
	v_cndmask_b32_e64 v135, v135, v246, s[76:77]
	v_cndmask_b32_e64 v134, v134, v246, s[74:75]
	v_cndmask_b32_e64 v133, v133, v246, s[72:73]
	v_cndmask_b32_e64 v132, v132, v246, s[68:69]
	v_cndmask_b32_e64 v131, v131, v246, s[4:5]
	v_cndmask_b32_e64 v147, v147, v246, s[0:1]
	v_cndmask_b32_e32 v146, v146, v246, vcc

; #define PG8_STAGE(bufoff, gbase, voff) do { _Pragma("unroll") for (int _i = 0; _i < 2; ++_i) \
;         __builtin_amdgcn_global_load_lds((const unsigned*)((const char*)(gbase) + (voff)[_i]), (PG8_LAS unsigned*)(lds + (bufoff) + ldsw + _i * 8192), 16, 0, 0); } while (0)
; #define PG8_LDA(dst, b, h) do { _Pragma("unroll") for (int m = 0; m < 4; ++m) _Pragma("unroll") for (int k = 0; k < 2; ++k) dst[m][k] = *(const PG8_LAS bf16x8*)(lds + PG8_SA(b, h) + aoff + m * 2048 + k * 1024); } while (0)
; #define PG8_LDB(dst, b, h) do { _Pragma("unroll") for (int n = 0; n < 2; ++n) _Pragma("unroll") for (int k = 0; k < 2; ++k) dst[n][k] = *(const PG8_LAS bf16x8*)(lds + PG8_SB(b, h) + boff + n * 2048 + k * 1024); } while (0)
; #define PG8_MMA(ai, bj, At, Bt) do { __builtin_amdgcn_s_setprio(1); _Pragma("unroll") for (int m = 0; m < 4; ++m) _Pragma("unroll") for (int n = 0; n < 2; ++n) _Pragma("unroll") for (int k = 0; k < 2; ++k) \
;         acc[ai][bj][m][n] = __builtin_amdgcn_mfma_f32_16x16x32_bf16(Bt[n][k], At[m][k], acc[ai][bj][m][n], 0, 0, 0); __builtin_amdgcn_s_setprio(0); } while (0)
; #define PG8_WAIT_V(n) asm volatile("s_waitcnt vmcnt(" #n ")" ::: "memory")
; #define PG8_WAIT_L(n) asm volatile("s_waitcnt lgkmcnt(" #n ")" ::: "memory")
; #define PG8_BAR __builtin_amdgcn_s_barrier()
; #define PG8_SCHED __builtin_amdgcn_sched_barrier(0)
; template <class Epi, class Sched, bool ALIGN_EPI = false, bool SP2 = false>
; __device__ __forceinline__ void gemm_phase(PG8_LAS unsigned char* lds, const Gemm g, const Sched& S, const Epi& E) {
;     ...
;             PG8_LDB(B0, 0, 0); PG8_LDB(B1, 0, 1); PG8_SCHED; PG8_LDA(At, 0, 0); PG8_STAGE(PG8_SA(1, 1), a1 + hstep, voffA);
;             PG8_WAIT_V(8); PG8_WAIT_L(0); PG8_BAR; PG8_MMA(0, 0, At, B0); PG8_MMA(0, 1, At, B1); PG8_BAR; PG8_SCHED;
;             PG8_LDA(At, 0, 1); PG8_STAGE(PG8_SB(0, 0), b2, voffB); PG8_STAGE(PG8_SB(0, 1), b2 + hstep, voffB); PG8_STAGE(PG8_SA(0, 0), a2, voffA);
;             PG8_WAIT_V(8); PG8_WAIT_L(0); PG8_BAR; PG8_MMA(1, 0, At, B0); PG8_MMA(1, 1, At, B1); PG8_BAR; PG8_SCHED;
.LBB0_918:
	s_add_u32 s20, s8, 0xfffc0080
	s_addc_u32 s21, s9, -1
	s_add_i32 s37, 0, 0x10000
	s_cmp_eq_u32 s55, 12
	s_cselect_b32 s51, s36, s21
	s_cselect_b32 s50, s45, s20
	s_cselect_b32 s21, s27, s54
	s_cselect_b32 s20, s52, s53
	s_add_i32 s58, 0, 0x14000
	v_add_u32_e32 v152, s37, v157
	v_add_u32_e32 v163, s58, v157
	ds_read_b128 v[130:133], v152
	ds_read_b128 v[134:137], v152 offset:1024
	ds_read_b128 v[148:151], v152 offset:2048
	ds_read_b128 v[152:155], v152 offset:3072
	ds_read_b128 v[164:167], v163
	ds_read_b128 v[168:171], v163 offset:1024
	ds_read_b128 v[172:175], v163 offset:2048
	ds_read_b128 v[176:179], v163 offset:3072
	v_lshl_add_u64 v[192:193], s[8:9], 0, v[144:145]
	s_add_i32 m0, s3, 0xc000
	ds_read_b128 v[180:183], v161
	ds_read_b128 v[184:187], v161 offset:1024
	ds_read_b128 v[188:191], v161 offset:2048
	ds_read_b128 v[204:207], v161 offset:3072
	ds_read_b128 v[208:211], v161 offset:4096
	ds_read_b128 v[212:215], v161 offset:5120
	ds_read_b128 v[216:219], v161 offset:6144
	ds_read_b128 v[220:223], v161 offset:7168
	global_load_lds_dwordx4 v[192:193], off
	v_lshl_add_u64 v[192:193], s[8:9], 0, v[146:147]
	s_add_i32 m0, s3, 0xe000
	s_nop 0
	global_load_lds_dwordx4 v[192:193], off
	s_waitcnt vmcnt(8)
	s_waitcnt lgkmcnt(0)
	s_barrier
	s_setprio 1
	s_waitcnt lgkmcnt(0)
	v_mfma_f32_16x16x32_bf16 v[126:129], v[130:133], v[180:183], v[126:129]
	v_mfma_f32_16x16x32_bf16 v[122:125], v[148:151], v[180:183], v[122:125]
	v_mfma_f32_16x16x32_bf16 v[110:113], v[130:133], v[188:191], v[110:113]
	v_mfma_f32_16x16x32_bf16 v[106:109], v[148:151], v[188:191], v[106:109]
	v_mfma_f32_16x16x32_bf16 v[94:97], v[130:133], v[208:211], v[94:97]
	v_mfma_f32_16x16x32_bf16 v[90:93], v[148:151], v[208:211], v[90:93]
	v_mfma_f32_16x16x32_bf16 v[78:81], v[130:133], v[216:219], v[78:81]
	v_mfma_f32_16x16x32_bf16 v[74:77], v[148:151], v[216:219], v[74:77]
	v_mfma_f32_16x16x32_bf16 v[126:129], v[134:137], v[184:187], v[126:129]
	v_mfma_f32_16x16x32_bf16 v[122:125], v[152:155], v[184:187], v[122:125]
	v_mfma_f32_16x16x32_bf16 v[110:113], v[134:137], v[204:207], v[110:113]
	v_mfma_f32_16x16x32_bf16 v[106:109], v[152:155], v[204:207], v[106:109]
	v_mfma_f32_16x16x32_bf16 v[94:97], v[134:137], v[212:215], v[94:97]
	v_mfma_f32_16x16x32_bf16 v[90:93], v[152:155], v[212:215], v[90:93]
	v_mfma_f32_16x16x32_bf16 v[78:81], v[134:137], v[220:223], v[78:81]
	v_mfma_f32_16x16x32_bf16 v[74:77], v[152:155], v[220:223], v[74:77]
	s_setprio 0
	s_setprio 1
	v_mfma_f32_16x16x32_bf16 v[118:121], v[164:167], v[180:183], v[118:121]
	v_mfma_f32_16x16x32_bf16 v[114:117], v[172:175], v[180:183], v[114:117]
	v_mfma_f32_16x16x32_bf16 v[102:105], v[164:167], v[188:191], v[102:105]
	v_mfma_f32_16x16x32_bf16 v[98:101], v[172:175], v[188:191], v[98:101]
	v_mfma_f32_16x16x32_bf16 v[86:89], v[164:167], v[208:211], v[86:89]
	v_mfma_f32_16x16x32_bf16 v[82:85], v[172:175], v[208:211], v[82:85]
	v_mfma_f32_16x16x32_bf16 v[70:73], v[164:167], v[216:219], v[70:73]
	v_mfma_f32_16x16x32_bf16 v[66:69], v[172:175], v[216:219], v[66:69]
	v_mfma_f32_16x16x32_bf16 v[118:121], v[168:171], v[184:187], v[118:121]
	v_mfma_f32_16x16x32_bf16 v[114:117], v[176:179], v[184:187], v[114:117]
	v_mfma_f32_16x16x32_bf16 v[102:105], v[168:171], v[204:207], v[102:105]
	v_mfma_f32_16x16x32_bf16 v[98:101], v[176:179], v[204:207], v[98:101]
	v_mfma_f32_16x16x32_bf16 v[86:89], v[168:171], v[212:215], v[86:89]
	v_mfma_f32_16x16x32_bf16 v[82:85], v[176:179], v[212:215], v[82:85]
	v_mfma_f32_16x16x32_bf16 v[70:73], v[168:171], v[220:223], v[70:73]
	v_mfma_f32_16x16x32_bf16 v[66:69], v[176:179], v[220:223], v[66:69]
	s_setprio 0
	s_barrier
	s_add_i32 s37, s37, s2
	v_lshl_add_u64 v[192:193], s[20:21], 0, v[0:1]
	s_mov_b32 m0, s37
	ds_read_b128 v[180:183], v161 offset:16384
	global_load_lds_dwordx4 v[192:193], off
	ds_read_b128 v[184:187], v161 offset:17408
	ds_read_b128 v[188:191], v161 offset:18432
	s_add_i32 m0, s37, 0x2000
	s_add_u32 s56, s20, 0x40000
	v_lshl_add_u64 v[194:195], s[20:21], 0, v[138:139]
	s_addc_u32 s57, s21, 0
	s_add_i32 s37, s58, s2
	global_load_lds_dwordx4 v[194:195], off
	ds_read_b128 v[204:207], v161 offset:19456
	ds_read_b128 v[208:211], v161 offset:20480
	v_lshl_add_u64 v[224:225], s[56:57], 0, v[0:1]
	s_mov_b32 m0, s37
	v_lshl_add_u64 v[226:227], s[50:51], 0, v[140:141]
	global_load_lds_dwordx4 v[224:225], off
	ds_read_b128 v[212:215], v161 offset:21504
	ds_read_b128 v[216:219], v161 offset:22528
	v_lshl_add_u64 v[224:225], s[56:57], 0, v[138:139]
	s_add_i32 m0, s37, 0x2000
	s_nop 0
	global_load_lds_dwordx4 v[224:225], off
	ds_read_b128 v[220:223], v161 offset:23552
	v_lshl_add_u64 v[224:225], s[50:51], 0, v[142:143]
	s_mov_b32 m0, s3
	s_nop 0
	global_load_lds_dwordx4 v[224:225], off
	s_mov_b32 m0, s16
	s_nop 0
	global_load_lds_dwordx4 v[226:227], off
	s_waitcnt vmcnt(8)
	s_waitcnt lgkmcnt(0)
	s_barrier
; #define PG8_STAGE(bufoff, gbase, voff) do { _Pragma("unroll") for (int _i = 0; _i < 2; ++_i) \
;         __builtin_amdgcn_global_load_lds((const unsigned*)((const char*)(gbase) + (voff)[_i]), (PG8_LAS unsigned*)(lds + (bufoff) + ldsw + _i * 8192), 16, 0, 0); } while (0)
; #define PG8_LDA(dst, b, h) do { _Pragma("unroll") for (int m = 0; m < 4; ++m) _Pragma("unroll") for (int k = 0; k < 2; ++k) dst[m][k] = *(const PG8_LAS bf16x8*)(lds + PG8_SA(b, h) + aoff + m * 2048 + k * 1024); } while (0)
; #define PG8_LDB(dst, b, h) do { _Pragma("unroll") for (int n = 0; n < 2; ++n) _Pragma("unroll") for (int k = 0; k < 2; ++k) dst[n][k] = *(const PG8_LAS bf16x8*)(lds + PG8_SB(b, h) + boff + n * 2048 + k * 1024); } while (0)
; #define PG8_MMA(ai, bj, At, Bt) do { __builtin_amdgcn_s_setprio(1); _Pragma("unroll") for (int m = 0; m < 4; ++m) _Pragma("unroll") for (int n = 0; n < 2; ++n) _Pragma("unroll") for (int k = 0; k < 2; ++k) \
;         acc[ai][bj][m][n] = __builtin_amdgcn_mfma_f32_16x16x32_bf16(Bt[n][k], At[m][k], acc[ai][bj][m][n], 0, 0, 0); __builtin_amdgcn_s_setprio(0); } while (0)
; #define PG8_WAIT_V(n) asm volatile("s_waitcnt vmcnt(" #n ")" ::: "memory")
; #define PG8_WAIT_L(n) asm volatile("s_waitcnt lgkmcnt(" #n ")" ::: "memory")
; #define PG8_BAR __builtin_amdgcn_s_barrier()
; #define PG8_SCHED __builtin_amdgcn_sched_barrier(0)
; template <class Epi, class Sched, bool ALIGN_EPI = false, bool SP2 = false>
; __device__ __forceinline__ void gemm_phase(PG8_LAS unsigned char* lds, const Gemm g, const Sched& S, const Epi& E) {
;     ...
;             PG8_WAIT_V(8); PG8_WAIT_L(0); PG8_BAR; PG8_MMA(1, 0, At, B0); PG8_MMA(1, 1, At, B1); PG8_BAR; PG8_SCHED;
;             PG8_LDB(B0, 1, 0); PG8_LDB(B1, 1, 1); PG8_SCHED; PG8_LDA(At, 1, 0); PG8_STAGE(PG8_SA(0, 1), a2 + hstep, voffA);
;             PG8_WAIT_V(8); PG8_WAIT_L(0); PG8_BAR; PG8_MMA(0, 0, At, B0); PG8_MMA(0, 1, At, B1); PG8_BAR; PG8_SCHED;
	s_setprio 1
	s_waitcnt lgkmcnt(0)
	v_mfma_f32_16x16x32_bf16 v[62:65], v[130:133], v[180:183], v[62:65]
	v_mfma_f32_16x16x32_bf16 v[58:61], v[148:151], v[180:183], v[58:61]
	v_mfma_f32_16x16x32_bf16 v[46:49], v[130:133], v[188:191], v[46:49]
	v_mfma_f32_16x16x32_bf16 v[42:45], v[148:151], v[188:191], v[42:45]
	v_mfma_f32_16x16x32_bf16 v[30:33], v[130:133], v[208:211], v[30:33]
	v_mfma_f32_16x16x32_bf16 v[26:29], v[148:151], v[208:211], v[26:29]
	v_mfma_f32_16x16x32_bf16 v[14:17], v[130:133], v[216:219], v[14:17]
	v_mfma_f32_16x16x32_bf16 v[10:13], v[148:151], v[216:219], v[10:13]
	v_mfma_f32_16x16x32_bf16 v[62:65], v[134:137], v[184:187], v[62:65]
	v_mfma_f32_16x16x32_bf16 v[58:61], v[152:155], v[184:187], v[58:61]
	v_mfma_f32_16x16x32_bf16 v[46:49], v[134:137], v[204:207], v[46:49]
	v_mfma_f32_16x16x32_bf16 v[42:45], v[152:155], v[204:207], v[42:45]
	v_mfma_f32_16x16x32_bf16 v[30:33], v[134:137], v[212:215], v[30:33]
	v_mfma_f32_16x16x32_bf16 v[26:29], v[152:155], v[212:215], v[26:29]
	v_mfma_f32_16x16x32_bf16 v[14:17], v[134:137], v[220:223], v[14:17]
	v_mfma_f32_16x16x32_bf16 v[10:13], v[152:155], v[220:223], v[10:13]
	s_setprio 0
	s_setprio 1
	v_mfma_f32_16x16x32_bf16 v[54:57], v[164:167], v[180:183], v[54:57]
	v_mfma_f32_16x16x32_bf16 v[50:53], v[172:175], v[180:183], v[50:53]
	v_mfma_f32_16x16x32_bf16 v[38:41], v[164:167], v[188:191], v[38:41]
	v_mfma_f32_16x16x32_bf16 v[34:37], v[172:175], v[188:191], v[34:37]
	v_mfma_f32_16x16x32_bf16 v[22:25], v[164:167], v[208:211], v[22:25]
	v_mfma_f32_16x16x32_bf16 v[18:21], v[172:175], v[208:211], v[18:21]
	v_mfma_f32_16x16x32_bf16 v[6:9], v[164:167], v[216:219], v[6:9]
	v_mfma_f32_16x16x32_bf16 v[2:5], v[172:175], v[216:219], v[2:5]
	v_mfma_f32_16x16x32_bf16 v[54:57], v[168:171], v[184:187], v[54:57]
	v_mfma_f32_16x16x32_bf16 v[50:53], v[176:179], v[184:187], v[50:53]
	v_mfma_f32_16x16x32_bf16 v[38:41], v[168:171], v[204:207], v[38:41]
	v_mfma_f32_16x16x32_bf16 v[34:37], v[176:179], v[204:207], v[34:37]
	v_mfma_f32_16x16x32_bf16 v[22:25], v[168:171], v[212:215], v[22:25]
	v_mfma_f32_16x16x32_bf16 v[18:21], v[176:179], v[212:215], v[18:21]
	v_mfma_f32_16x16x32_bf16 v[6:9], v[168:171], v[220:223], v[6:9]
	v_mfma_f32_16x16x32_bf16 v[2:5], v[176:179], v[220:223], v[2:5]
	s_setprio 0
	s_barrier
	s_add_i32 s37, 0, 0x18000
	s_add_i32 s56, 0, 0x1c000
	v_add_u32_e32 v152, s37, v157
	v_add_u32_e32 v163, s56, v157
	ds_read_b128 v[130:133], v152
	ds_read_b128 v[134:137], v152 offset:1024
	ds_read_b128 v[148:151], v152 offset:2048
	ds_read_b128 v[152:155], v152 offset:3072
	ds_read_b128 v[164:167], v163
	ds_read_b128 v[168:171], v163 offset:1024
	ds_read_b128 v[172:175], v163 offset:2048
	ds_read_b128 v[176:179], v163 offset:3072
	s_add_u32 s50, s50, 0x40000
	s_addc_u32 s51, s51, 0
	s_mov_b32 m0, s18
	v_lshl_add_u64 v[228:229], s[50:51], 0, v[142:143]
	ds_read_b128 v[180:183], v161 offset:32768
	ds_read_b128 v[184:187], v161 offset:33792
	ds_read_b128 v[188:191], v161 offset:34816
	ds_read_b128 v[204:207], v161 offset:35840
	ds_read_b128 v[208:211], v161 offset:36864
	ds_read_b128 v[212:215], v161 offset:37888
	ds_read_b128 v[216:219], v161 offset:38912
	ds_read_b128 v[220:223], v161 offset:39936
	global_load_lds_dwordx4 v[228:229], off
	v_lshl_add_u64 v[228:229], s[50:51], 0, v[140:141]
	s_mov_b32 m0, s19
	s_nop 0
	global_load_lds_dwordx4 v[228:229], off
	s_waitcnt vmcnt(8)
	s_waitcnt lgkmcnt(0)
	s_barrier
	s_setprio 1
	s_waitcnt lgkmcnt(0)
	v_mfma_f32_16x16x32_bf16 v[126:129], v[130:133], v[180:183], v[126:129]
	v_mfma_f32_16x16x32_bf16 v[122:125], v[148:151], v[180:183], v[122:125]
	v_mfma_f32_16x16x32_bf16 v[110:113], v[130:133], v[188:191], v[110:113]
	v_mfma_f32_16x16x32_bf16 v[106:109], v[148:151], v[188:191], v[106:109]
	v_mfma_f32_16x16x32_bf16 v[94:97], v[130:133], v[208:211], v[94:97]
	v_mfma_f32_16x16x32_bf16 v[90:93], v[148:151], v[208:211], v[90:93]
	v_mfma_f32_16x16x32_bf16 v[78:81], v[130:133], v[216:219], v[78:81]
	v_mfma_f32_16x16x32_bf16 v[74:77], v[148:151], v[216:219], v[74:77]
	v_mfma_f32_16x16x32_bf16 v[126:129], v[134:137], v[184:187], v[126:129]
	v_mfma_f32_16x16x32_bf16 v[122:125], v[152:155], v[184:187], v[122:125]
	v_mfma_f32_16x16x32_bf16 v[110:113], v[134:137], v[204:207], v[110:113]
	v_mfma_f32_16x16x32_bf16 v[106:109], v[152:155], v[204:207], v[106:109]
	v_mfma_f32_16x16x32_bf16 v[94:97], v[134:137], v[212:215], v[94:97]
	v_mfma_f32_16x16x32_bf16 v[90:93], v[152:155], v[212:215], v[90:93]
	v_mfma_f32_16x16x32_bf16 v[78:81], v[134:137], v[220:223], v[78:81]
	v_mfma_f32_16x16x32_bf16 v[74:77], v[152:155], v[220:223], v[74:77]
	s_setprio 0
	s_setprio 1
	v_mfma_f32_16x16x32_bf16 v[118:121], v[164:167], v[180:183], v[118:121]
	v_mfma_f32_16x16x32_bf16 v[114:117], v[172:175], v[180:183], v[114:117]
	v_mfma_f32_16x16x32_bf16 v[102:105], v[164:167], v[188:191], v[102:105]
	v_mfma_f32_16x16x32_bf16 v[98:101], v[172:175], v[188:191], v[98:101]
	v_mfma_f32_16x16x32_bf16 v[86:89], v[164:167], v[208:211], v[86:89]
	v_mfma_f32_16x16x32_bf16 v[82:85], v[172:175], v[208:211], v[82:85]
	v_mfma_f32_16x16x32_bf16 v[70:73], v[164:167], v[216:219], v[70:73]
	v_mfma_f32_16x16x32_bf16 v[66:69], v[172:175], v[216:219], v[66:69]
	v_mfma_f32_16x16x32_bf16 v[118:121], v[168:171], v[184:187], v[118:121]
	v_mfma_f32_16x16x32_bf16 v[114:117], v[176:179], v[184:187], v[114:117]
	v_mfma_f32_16x16x32_bf16 v[102:105], v[168:171], v[204:207], v[102:105]
	v_mfma_f32_16x16x32_bf16 v[98:101], v[176:179], v[204:207], v[98:101]
	v_mfma_f32_16x16x32_bf16 v[86:89], v[168:171], v[212:215], v[86:89]
	v_mfma_f32_16x16x32_bf16 v[82:85], v[176:179], v[212:215], v[82:85]
	v_mfma_f32_16x16x32_bf16 v[70:73], v[168:171], v[220:223], v[70:73]
	v_mfma_f32_16x16x32_bf16 v[66:69], v[176:179], v[220:223], v[66:69]
	s_setprio 0
	s_barrier
; #define PG8_STAGE(bufoff, gbase, voff) do { _Pragma("unroll") for (int _i = 0; _i < 2; ++_i) \
;         __builtin_amdgcn_global_load_lds((const unsigned*)((const char*)(gbase) + (voff)[_i]), (PG8_LAS unsigned*)(lds + (bufoff) + ldsw + _i * 8192), 16, 0, 0); } while (0)
; #define PG8_LDA(dst, b, h) do { _Pragma("unroll") for (int m = 0; m < 4; ++m) _Pragma("unroll") for (int k = 0; k < 2; ++k) dst[m][k] = *(const PG8_LAS bf16x8*)(lds + PG8_SA(b, h) + aoff + m * 2048 + k * 1024); } while (0)
; #define PG8_MMA(ai, bj, At, Bt) do { __builtin_amdgcn_s_setprio(1); _Pragma("unroll") for (int m = 0; m < 4; ++m) _Pragma("unroll") for (int n = 0; n < 2; ++n) _Pragma("unroll") for (int k = 0; k < 2; ++k) \
;         acc[ai][bj][m][n] = __builtin_amdgcn_mfma_f32_16x16x32_bf16(Bt[n][k], At[m][k], acc[ai][bj][m][n], 0, 0, 0); __builtin_amdgcn_s_setprio(0); } while (0)
; #define PG8_WAIT_V(n) asm volatile("s_waitcnt vmcnt(" #n ")" ::: "memory")
; #define PG8_WAIT_L(n) asm volatile("s_waitcnt lgkmcnt(" #n ")" ::: "memory")
; #define PG8_BAR __builtin_amdgcn_s_barrier()
; #define PG8_SCHED __builtin_amdgcn_sched_barrier(0)
; template <class Epi, class Sched, bool ALIGN_EPI = false, bool SP2 = false>
; __device__ __forceinline__ void gemm_phase(PG8_LAS unsigned char* lds, const Gemm g, const Sched& S, const Epi& E) {
;     ...
;         for (int t = 0; t < nt; t += 2) {
;     ...
;             PG8_LDA(At, 1, 1); PG8_STAGE(PG8_SB(1, 0), b3, voffB); PG8_STAGE(PG8_SB(1, 1), b3 + hstep, voffB); PG8_STAGE(PG8_SA(1, 0), a3, voffA);
;             PG8_WAIT_V(8); PG8_WAIT_L(0); PG8_BAR; PG8_MMA(1, 0, At, B0); PG8_MMA(1, 1, At, B1); PG8_BAR; PG8_SCHED;
	s_add_i32 s37, s37, s2
	v_lshl_add_u64 v[192:193], v[192:193], 0, s[28:29]
	s_mov_b32 m0, s37
	ds_read_b128 v[180:183], v161 offset:49152
	global_load_lds_dwordx4 v[192:193], off
	ds_read_b128 v[184:187], v161 offset:50176
	ds_read_b128 v[188:191], v161 offset:51200
	s_add_i32 m0, s37, 0x2000
	s_add_u32 s20, s20, 0x40080
	v_lshl_add_u64 v[192:193], v[194:195], 0, s[28:29]
	s_addc_u32 s21, s21, 0
	s_add_i32 s37, s56, s2
	global_load_lds_dwordx4 v[192:193], off
	ds_read_b128 v[204:207], v161 offset:52224
	ds_read_b128 v[208:211], v161 offset:53248
	v_lshl_add_u64 v[192:193], s[20:21], 0, v[0:1]
	s_mov_b32 m0, s37
	s_nop 0
	global_load_lds_dwordx4 v[192:193], off
	ds_read_b128 v[212:215], v161 offset:54272
	ds_read_b128 v[216:219], v161 offset:55296
	v_lshl_add_u64 v[192:193], s[20:21], 0, v[138:139]
	s_add_i32 m0, s37, 0x2000
	s_nop 0
	global_load_lds_dwordx4 v[192:193], off
	ds_read_b128 v[220:223], v161 offset:56320
	v_lshl_add_u64 v[192:193], v[224:225], 0, s[28:29]
	s_mov_b32 m0, s33
	s_nop 0
	global_load_lds_dwordx4 v[192:193], off
	v_lshl_add_u64 v[192:193], v[226:227], 0, s[28:29]
	s_mov_b32 m0, s34
	s_nop 0
	global_load_lds_dwordx4 v[192:193], off
	s_waitcnt vmcnt(8)
	s_waitcnt lgkmcnt(0)
	s_barrier
	s_setprio 1
	s_waitcnt lgkmcnt(0)
	v_mfma_f32_16x16x32_bf16 v[62:65], v[130:133], v[180:183], v[62:65]
	v_mfma_f32_16x16x32_bf16 v[58:61], v[148:151], v[180:183], v[58:61]
	v_mfma_f32_16x16x32_bf16 v[46:49], v[130:133], v[188:191], v[46:49]
	v_mfma_f32_16x16x32_bf16 v[42:45], v[148:151], v[188:191], v[42:45]
	v_mfma_f32_16x16x32_bf16 v[30:33], v[130:133], v[208:211], v[30:33]
	v_mfma_f32_16x16x32_bf16 v[26:29], v[148:151], v[208:211], v[26:29]
	v_mfma_f32_16x16x32_bf16 v[14:17], v[130:133], v[216:219], v[14:17]
	v_mfma_f32_16x16x32_bf16 v[10:13], v[148:151], v[216:219], v[10:13]
	v_mfma_f32_16x16x32_bf16 v[62:65], v[134:137], v[184:187], v[62:65]
	v_mfma_f32_16x16x32_bf16 v[58:61], v[152:155], v[184:187], v[58:61]
	v_mfma_f32_16x16x32_bf16 v[46:49], v[134:137], v[204:207], v[46:49]
	v_mfma_f32_16x16x32_bf16 v[42:45], v[152:155], v[204:207], v[42:45]
	v_mfma_f32_16x16x32_bf16 v[30:33], v[134:137], v[212:215], v[30:33]
	v_mfma_f32_16x16x32_bf16 v[26:29], v[152:155], v[212:215], v[26:29]
	v_mfma_f32_16x16x32_bf16 v[14:17], v[134:137], v[220:223], v[14:17]
	v_mfma_f32_16x16x32_bf16 v[10:13], v[152:155], v[220:223], v[10:13]
	s_setprio 0
	s_setprio 1
	v_mfma_f32_16x16x32_bf16 v[54:57], v[164:167], v[180:183], v[54:57]
	v_mfma_f32_16x16x32_bf16 v[50:53], v[172:175], v[180:183], v[50:53]
	v_mfma_f32_16x16x32_bf16 v[38:41], v[164:167], v[188:191], v[38:41]
	v_mfma_f32_16x16x32_bf16 v[34:37], v[172:175], v[188:191], v[34:37]
	v_mfma_f32_16x16x32_bf16 v[22:25], v[164:167], v[208:211], v[22:25]
	v_mfma_f32_16x16x32_bf16 v[18:21], v[172:175], v[208:211], v[18:21]
	v_mfma_f32_16x16x32_bf16 v[6:9], v[164:167], v[216:219], v[6:9]
	v_mfma_f32_16x16x32_bf16 v[2:5], v[172:175], v[216:219], v[2:5]
	v_mfma_f32_16x16x32_bf16 v[54:57], v[168:171], v[184:187], v[54:57]
	v_mfma_f32_16x16x32_bf16 v[50:53], v[176:179], v[184:187], v[50:53]
	v_mfma_f32_16x16x32_bf16 v[38:41], v[168:171], v[204:207], v[38:41]
	v_mfma_f32_16x16x32_bf16 v[34:37], v[176:179], v[204:207], v[34:37]
	v_mfma_f32_16x16x32_bf16 v[22:25], v[168:171], v[212:215], v[22:25]
	v_mfma_f32_16x16x32_bf16 v[18:21], v[176:179], v[212:215], v[18:21]
	v_mfma_f32_16x16x32_bf16 v[6:9], v[168:171], v[220:223], v[6:9]
	v_mfma_f32_16x16x32_bf16 v[2:5], v[176:179], v[220:223], v[2:5]
	s_setprio 0
	s_barrier
	s_add_i32 s55, s55, 2
	s_add_u32 s8, s8, 0x100
	s_addc_u32 s9, s9, 0
	s_add_u32 s53, s53, 0x100
	s_addc_u32 s54, s54, 0
	s_cmp_gt_u32 s55, 13
	s_cbranch_scc0 .LBB0_918
	s_and_b64 vcc, exec, s[4:5]
	s_cbranch_vccz .LBB0_921
	s_barrier
; __device__ __forceinline__ unsigned pk(float lo, float hi) { f32x2v v = {lo, hi}; bf16x2v b = __builtin_convertvector(v, bf16x2v); return __builtin_bit_cast(unsigned, b); }
;     __device__ __forceinline__ void operator()(const f32x4 (&acc)[2][2][4][2], const Unit& u, int wr, int wc, int fr, int fq) const {
;         const int row0 = u.pm * BM + wr * 64 + fr, col0 = u.pn * BM + wc * 32 + 8 * fq;
; #pragma unroll
;         for (int ai = 0; ai < 2; ++ai)
; #pragma unroll
;           for (int mp = 0; mp < 2; ++mp) { u32x4 xv[2][2];
; #pragma unroll
;             for (int mm = 0; mm < 2; ++mm)
; #pragma unroll
;                 for (int bj = 0; bj < 2; ++bj) xv[mm][bj] = *(const u32x4*)(xb + (size_t)(row0 + ai * HALF + (2 * mp + mm) * 16) * DMODEL + col0 + bj * HALF);
; #pragma unroll
;             for (int mm = 0; mm < 2; ++mm) { const int m = 2 * mp + mm, row = row0 + ai * HALF + m * 16; float ss = 0.f;
; #pragma unroll
;                 for (int bj = 0; bj < 2; ++bj) { const u32x4 xr = xv[mm][bj];
;                     const f32x4 x0 = {__uint_as_float(xr.x << 16), __uint_as_float(xr.x & 0xffff0000u), __uint_as_float(xr.y << 16), __uint_as_float(xr.y & 0xffff0000u)};
;                     const f32x4 x1 = {__uint_as_float(xr.z << 16), __uint_as_float(xr.z & 0xffff0000u), __uint_as_float(xr.w << 16), __uint_as_float(xr.w & 0xffff0000u)};
;                     const f32x4 y0 = x0 + acc[ai][bj][m][0] * alpha, y1 = x1 + acc[ai][bj][m][1] * alpha;
;                     u32x4 w; w.x = pk(y0[0], y0[1]); w.y = pk(y0[2], y0[3]); w.z = pk(y1[0], y1[1]); w.w = pk(y1[2], y1[3]);
;                     *(u32x4*)(xb + (size_t)row * DMODEL + col0 + bj * HALF) = w;
;                     ss += ((y0[0] * y0[0] + y0[1] * y0[1]) + (y0[2] * y0[2] + y0[3] * y0[3])) + ((y1[0] * y1[0] + y1[1] * y1[1]) + (y1[2] * y1[2] + y1[3] * y1[3])); }
;                 ss += __shfl_xor(ss, 16); ss += __shfl_xor(ss, 32);
;                 if (fq == 0) red[(ai * HALF + wr * 64 + m * 16 + fr) * 4 + wc] = ss; }
.LBB0_921:
	v_and_b32_e32 v131, 64, v243
	v_xor_b32_e32 v130, 16, v243
	v_add_u32_e32 v131, 64, v131
	v_cmp_lt_i32_e32 vcc, v130, v131
	s_lshl_b32 s7, s7, 8
	v_lshl_or_b32 v148, s6, 8, v158
	v_cndmask_b32_e32 v130, v243, v130, vcc
	v_add_u32_e32 v150, s7, v156
	v_ashrrev_i32_e32 v149, 31, v148
	v_lshlrev_b32_e32 v164, 2, v130
	v_xor_b32_e32 v130, 32, v243
	v_cmp_lt_i32_e32 vcc, v130, v131
	v_lshlrev_b64 v[174:175], 1, v[148:149]
	v_ashrrev_i32_e32 v151, 31, v150
	v_cndmask_b32_e32 v130, v243, v130, vcc
	v_lshl_add_u64 v[152:153], s[10:11], 0, v[174:175]
	v_lshlrev_b64 v[176:177], 11, v[150:151]
	v_lshlrev_b32_e32 v163, 2, v130
	v_lshl_add_u64 v[130:131], v[152:153], 0, v[176:177]
	v_mov_b32_e32 v224, v130
	v_mov_b32_e32 v225, v131
	global_load_dwordx4 v[166:169], v[130:131], off
	global_load_dwordx4 v[170:173], v[130:131], off offset:256
	v_or_b32_e32 v130, 16, v150
	v_ashrrev_i32_e32 v131, 31, v130
	v_lshlrev_b64 v[154:155], 11, v[130:131]
	v_lshl_add_u64 v[130:131], v[152:153], 0, v[154:155]
	global_load_dwordx4 v[134:137], v[130:131], off
	s_nop 0
	global_load_dwordx4 v[130:133], v[130:131], off offset:256
	s_mov_b64 s[8:9], 0x10000
	v_lshl_add_u64 v[226:227], v[224:225], 0, s[8:9]
	global_load_dwordx4 v[182:185], v[226:227], off
	global_load_dwordx4 v[186:189], v[226:227], off offset:256
	s_mov_b64 s[8:9], 0x18000
	v_lshl_add_u64 v[226:227], v[224:225], 0, s[8:9]
	global_load_dwordx4 v[190:193], v[226:227], off
	global_load_dwordx4 v[204:207], v[226:227], off offset:256
	s_mov_b64 s[8:9], 0x40000
	v_lshl_add_u64 v[226:227], v[224:225], 0, s[8:9]
	global_load_dwordx4 v[208:211], v[226:227], off
	global_load_dwordx4 v[212:215], v[226:227], off offset:256
	s_mov_b64 s[8:9], 0x48000
	v_lshl_add_u64 v[226:227], v[224:225], 0, s[8:9]
	global_load_dwordx4 v[216:219], v[226:227], off
	global_load_dwordx4 v[220:223], v[226:227], off offset:256
	v_lshl_add_u64 v[176:177], s[10:11], 0, v[176:177]
	v_lshl_add_u64 v[174:175], v[176:177], 0, v[174:175]
	s_waitcnt vmcnt(8)
	v_lshlrev_b32_e32 v178, 16, v166
	v_and_b32_e32 v179, 0xffff0000, v166
	v_lshlrev_b32_e32 v166, 16, v167
	v_and_b32_e32 v167, 0xffff0000, v167
	v_lshlrev_b32_e32 v180, 16, v168
	v_and_b32_e32 v181, 0xffff0000, v168
	v_lshlrev_b32_e32 v168, 16, v169
	v_and_b32_e32 v169, 0xffff0000, v169
	v_pk_add_f32 v[128:129], v[128:129], v[166:167]
	v_pk_add_f32 v[126:127], v[126:127], v[178:179]
	v_pk_add_f32 v[166:167], v[124:125], v[168:169]
	v_pk_add_f32 v[168:169], v[122:123], v[180:181]
	v_cvt_pk_bf16_f32 v122, v126, v127
	v_cvt_pk_bf16_f32 v123, v128, v129
	v_cvt_pk_bf16_f32 v124, v168, v169
	v_cvt_pk_bf16_f32 v125, v166, v167
	global_store_dwordx4 v[174:175], v[122:125], off
	s_nop 1
	v_mul_f32_e32 v122, v127, v127
	v_mul_f32_e32 v123, v129, v129
	v_fmac_f32_e32 v122, v126, v126
	v_fmac_f32_e32 v123, v128, v128
	v_add_f32_e32 v122, v122, v123
	v_mul_f32_e32 v123, v169, v169
	v_mul_f32_e32 v124, v167, v167
	v_fmac_f32_e32 v123, v168, v168
	v_fmac_f32_e32 v124, v166, v166
	v_add_f32_e32 v123, v123, v124
	v_add_f32_e32 v165, v122, v123
	v_lshlrev_b32_e32 v122, 16, v170
	v_and_b32_e32 v123, 0xffff0000, v170
	v_lshlrev_b32_e32 v124, 16, v171
	v_and_b32_e32 v125, 0xffff0000, v171
	v_lshlrev_b32_e32 v126, 16, v172
	v_and_b32_e32 v127, 0xffff0000, v172
	v_lshlrev_b32_e32 v128, 16, v173
	v_and_b32_e32 v129, 0xffff0000, v173
	v_pk_add_f32 v[120:121], v[120:121], v[124:125]
	v_pk_add_f32 v[118:119], v[118:119], v[122:123]
	v_pk_add_f32 v[122:123], v[116:117], v[128:129]
	v_pk_add_f32 v[124:125], v[114:115], v[126:127]
	v_cvt_pk_bf16_f32 v114, v118, v119
	v_cvt_pk_bf16_f32 v115, v120, v121
	v_cvt_pk_bf16_f32 v116, v124, v125
	v_cvt_pk_bf16_f32 v117, v122, v123
	global_store_dwordx4 v[174:175], v[114:117], off offset:256
	s_nop 1
	v_mul_f32_e32 v114, v119, v119
	v_mul_f32_e32 v115, v121, v121
	v_fmac_f32_e32 v114, v118, v118
	v_fmac_f32_e32 v115, v120, v120
	v_add_f32_e32 v114, v114, v115
	v_mul_f32_e32 v115, v125, v125
	v_mul_f32_e32 v116, v123, v123
	v_fmac_f32_e32 v115, v124, v124
	v_fmac_f32_e32 v116, v122, v122
	v_add_f32_e32 v115, v115, v116
	v_add_f32_e32 v114, v114, v115
	v_add_f32_e32 v114, v165, v114
	ds_bpermute_b32 v115, v164, v114
	s_waitcnt lgkmcnt(0)
	v_add_f32_e32 v114, v114, v115
	ds_bpermute_b32 v115, v163, v114
	s_and_saveexec_b64 s[8:9], s[38:39]
	s_cbranch_execz .LBB0_923
	s_waitcnt lgkmcnt(0)
	v_add_f32_e32 v114, v114, v115
	ds_write_b32 v160, v114

; __device__ __forceinline__ unsigned pk(float lo, float hi) { f32x2v v = {lo, hi}; bf16x2v b = __builtin_convertvector(v, bf16x2v); return __builtin_bit_cast(unsigned, b); }
;     __device__ __forceinline__ void operator()(const f32x4 (&acc)[2][2][4][2], const Unit& u, int wr, int wc, int fr, int fq) const {
;     ...
;           for (int mp = 0; mp < 2; ++mp) { u32x4 xv[2][2];
; #pragma unroll
;             for (int mm = 0; mm < 2; ++mm)
; #pragma unroll
;                 for (int bj = 0; bj < 2; ++bj) xv[mm][bj] = *(const u32x4*)(xb + (size_t)(row0 + ai * HALF + (2 * mp + mm) * 16) * DMODEL + col0 + bj * HALF);
; #pragma unroll
;             for (int mm = 0; mm < 2; ++mm) { const int m = 2 * mp + mm, row = row0 + ai * HALF + m * 16; float ss = 0.f;
; #pragma unroll
;                 for (int bj = 0; bj < 2; ++bj) { const u32x4 xr = xv[mm][bj];
;                     const f32x4 x0 = {__uint_as_float(xr.x << 16), __uint_as_float(xr.x & 0xffff0000u), __uint_as_float(xr.y << 16), __uint_as_float(xr.y & 0xffff0000u)};
;                     const f32x4 x1 = {__uint_as_float(xr.z << 16), __uint_as_float(xr.z & 0xffff0000u), __uint_as_float(xr.w << 16), __uint_as_float(xr.w & 0xffff0000u)};
;                     const f32x4 y0 = x0 + acc[ai][bj][m][0] * alpha, y1 = x1 + acc[ai][bj][m][1] * alpha;
;                     u32x4 w; w.x = pk(y0[0], y0[1]); w.y = pk(y0[2], y0[3]); w.z = pk(y1[0], y1[1]); w.w = pk(y1[2], y1[3]);
;                     *(u32x4*)(xb + (size_t)row * DMODEL + col0 + bj * HALF) = w;
;                     ss += ((y0[0] * y0[0] + y0[1] * y0[1]) + (y0[2] * y0[2] + y0[3] * y0[3])) + ((y1[0] * y1[0] + y1[1] * y1[1]) + (y1[2] * y1[2] + y1[3] * y1[3])); }
;                 ss += __shfl_xor(ss, 16); ss += __shfl_xor(ss, 32);
;                 if (fq == 0) red[(ai * HALF + wr * 64 + m * 16 + fr) * 4 + wc] = ss; }
.LBB0_925:
	s_or_b64 exec, exec, s[8:9]
	v_or_b32_e32 v98, 32, v150
	s_waitcnt lgkmcnt(0)
	v_ashrrev_i32_e32 v99, 31, v98
	v_lshlrev_b64 v[116:117], 11, v[98:99]
	v_lshl_add_u64 v[98:99], v[152:153], 0, v[116:117]
	s_mov_b64 s[8:9], 0x50000
	v_lshl_add_u64 v[226:227], v[224:225], 0, s[8:9]
	global_load_dwordx4 v[166:169], v[226:227], off
	global_load_dwordx4 v[170:173], v[226:227], off offset:256
	s_mov_b64 s[8:9], 0x58000
	v_lshl_add_u64 v[226:227], v[224:225], 0, s[8:9]
	global_load_dwordx4 v[178:181], v[226:227], off
	global_load_dwordx4 v[134:137], v[226:227], off offset:256
	v_or_b32_e32 v98, 48, v150
	v_ashrrev_i32_e32 v99, 31, v98
	v_lshlrev_b64 v[106:107], 11, v[98:99]
	v_lshl_add_u64 v[98:99], v[152:153], 0, v[106:107]
	s_nop 0
	v_lshl_add_u64 v[116:117], s[10:11], 0, v[116:117]
	v_lshl_add_u64 v[116:117], v[148:149], 1, v[116:117]
	s_waitcnt vmcnt(12)
	v_mov_b32_e32 v108, v182
	v_mov_b32_e32 v109, v183
	v_mov_b32_e32 v110, v184
	v_mov_b32_e32 v111, v185
	v_mov_b32_e32 v112, v186
	v_mov_b32_e32 v113, v187
	v_mov_b32_e32 v114, v188
	v_mov_b32_e32 v115, v189
	v_mov_b32_e32 v102, v190
	v_mov_b32_e32 v103, v191
	v_mov_b32_e32 v104, v192
	v_mov_b32_e32 v105, v193
	v_mov_b32_e32 v98, v204
	v_mov_b32_e32 v99, v205
	v_mov_b32_e32 v100, v206
	v_mov_b32_e32 v101, v207
	v_lshlrev_b32_e32 v118, 16, v108
	v_and_b32_e32 v119, 0xffff0000, v108
	v_lshlrev_b32_e32 v108, 16, v109
	v_and_b32_e32 v109, 0xffff0000, v109
	v_lshlrev_b32_e32 v120, 16, v110
	v_and_b32_e32 v121, 0xffff0000, v110
	v_lshlrev_b32_e32 v110, 16, v111
	v_and_b32_e32 v111, 0xffff0000, v111
	v_pk_add_f32 v[96:97], v[96:97], v[108:109]
	v_pk_add_f32 v[94:95], v[94:95], v[118:119]
	v_pk_add_f32 v[108:109], v[92:93], v[110:111]
	v_pk_add_f32 v[110:111], v[90:91], v[120:121]
	v_cvt_pk_bf16_f32 v90, v94, v95
	v_cvt_pk_bf16_f32 v91, v96, v97
	v_cvt_pk_bf16_f32 v92, v110, v111
	v_cvt_pk_bf16_f32 v93, v108, v109
	global_store_dwordx4 v[116:117], v[90:93], off
	s_nop 1
	v_mul_f32_e32 v90, v95, v95
	v_mul_f32_e32 v91, v97, v97
	v_fmac_f32_e32 v90, v94, v94
	v_fmac_f32_e32 v91, v96, v96
	v_add_f32_e32 v90, v90, v91
	v_mul_f32_e32 v91, v111, v111
	v_mul_f32_e32 v92, v109, v109
	v_fmac_f32_e32 v91, v110, v110
	v_fmac_f32_e32 v92, v108, v108
	v_add_f32_e32 v91, v91, v92
	v_add_f32_e32 v108, v90, v91
	v_lshlrev_b32_e32 v90, 16, v112
	v_and_b32_e32 v91, 0xffff0000, v112
	v_lshlrev_b32_e32 v92, 16, v113
	v_and_b32_e32 v93, 0xffff0000, v113
	v_lshlrev_b32_e32 v94, 16, v114
	v_and_b32_e32 v95, 0xffff0000, v114
	v_lshlrev_b32_e32 v96, 16, v115
	v_and_b32_e32 v97, 0xffff0000, v115
	v_pk_add_f32 v[88:89], v[88:89], v[92:93]
	v_pk_add_f32 v[86:87], v[86:87], v[90:91]
	v_pk_add_f32 v[90:91], v[84:85], v[96:97]
	v_pk_add_f32 v[92:93], v[82:83], v[94:95]
	v_cvt_pk_bf16_f32 v82, v86, v87
	v_cvt_pk_bf16_f32 v83, v88, v89
	v_cvt_pk_bf16_f32 v84, v92, v93
	v_cvt_pk_bf16_f32 v85, v90, v91
	global_store_dwordx4 v[116:117], v[82:85], off offset:256
	s_nop 1
	v_mul_f32_e32 v82, v87, v87
	v_mul_f32_e32 v83, v89, v89
	v_fmac_f32_e32 v82, v86, v86
	v_fmac_f32_e32 v83, v88, v88
	v_add_f32_e32 v82, v82, v83
	v_mul_f32_e32 v83, v93, v93
	v_mul_f32_e32 v84, v91, v91
	v_fmac_f32_e32 v83, v92, v92
	v_fmac_f32_e32 v84, v90, v90
	v_add_f32_e32 v83, v83, v84
	v_add_f32_e32 v82, v82, v83
	v_add_f32_e32 v82, v108, v82
	ds_bpermute_b32 v83, v164, v82
	s_waitcnt lgkmcnt(0)
	v_add_f32_e32 v82, v82, v83
	ds_bpermute_b32 v83, v163, v82
	s_and_saveexec_b64 s[8:9], s[38:39]
	s_cbranch_execz .LBB0_927
	s_waitcnt lgkmcnt(0)
	v_add_f32_e32 v82, v82, v83
	ds_write_b32 v160, v82 offset:512
.LBB0_927:
	s_or_b64 exec, exec, s[8:9]
	v_lshlrev_b32_e32 v82, 16, v102
	s_waitcnt lgkmcnt(0)
	v_and_b32_e32 v83, 0xffff0000, v102
	v_lshlrev_b32_e32 v84, 16, v103
	v_and_b32_e32 v85, 0xffff0000, v103
	v_lshlrev_b32_e32 v86, 16, v104
	v_and_b32_e32 v87, 0xffff0000, v104
	v_pk_add_f32 v[78:79], v[78:79], v[82:83]
	v_pk_add_f32 v[80:81], v[80:81], v[84:85]
	v_pk_add_f32 v[84:85], v[74:75], v[86:87]
	v_cvt_pk_bf16_f32 v74, v78, v79
	v_mul_f32_e32 v79, v79, v79
	v_lshlrev_b32_e32 v88, 16, v105
	v_and_b32_e32 v89, 0xffff0000, v105
	v_fmac_f32_e32 v79, v78, v78
	v_mul_f32_e32 v78, v81, v81
	v_pk_add_f32 v[82:83], v[76:77], v[88:89]
	v_fmac_f32_e32 v78, v80, v80
	v_cvt_pk_bf16_f32 v75, v80, v81
	v_add_f32_e32 v78, v79, v78
	v_mul_f32_e32 v79, v85, v85
	v_mul_f32_e32 v80, v83, v83
	v_fmac_f32_e32 v79, v84, v84
	v_fmac_f32_e32 v80, v82, v82
	v_add_f32_e32 v79, v79, v80
	v_add_f32_e32 v86, v78, v79
	v_lshlrev_b32_e32 v78, 16, v98
	v_and_b32_e32 v79, 0xffff0000, v98
	v_lshlrev_b32_e32 v80, 16, v99
	v_and_b32_e32 v81, 0xffff0000, v99
	v_cvt_pk_bf16_f32 v77, v82, v83
	v_lshlrev_b32_e32 v82, 16, v100
	v_and_b32_e32 v83, 0xffff0000, v100
	v_pk_add_f32 v[72:73], v[72:73], v[80:81]
	v_pk_add_f32 v[70:71], v[70:71], v[78:79]
	v_cvt_pk_bf16_f32 v76, v84, v85
	v_lshlrev_b32_e32 v84, 16, v101
	v_and_b32_e32 v85, 0xffff0000, v101
	v_pk_add_f32 v[80:81], v[66:67], v[82:83]
	v_mul_f32_e32 v66, v71, v71
	v_mul_f32_e32 v67, v73, v73
	v_pk_add_f32 v[78:79], v[68:69], v[84:85]
	v_fmac_f32_e32 v66, v70, v70
	v_fmac_f32_e32 v67, v72, v72
	v_add_f32_e32 v66, v66, v67
	v_mul_f32_e32 v67, v81, v81
	v_mul_f32_e32 v68, v79, v79
	v_fmac_f32_e32 v67, v80, v80
	v_fmac_f32_e32 v68, v78, v78
	v_add_f32_e32 v67, v67, v68
	v_add_f32_e32 v66, v66, v67
	v_add_f32_e32 v69, v86, v66
	ds_bpermute_b32 v84, v164, v69
	v_lshl_add_u64 v[66:67], s[10:11], 0, v[106:107]
	v_lshl_add_u64 v[82:83], v[148:149], 1, v[66:67]
	v_cvt_pk_bf16_f32 v68, v70, v71
	v_cvt_pk_bf16_f32 v70, v80, v81
	s_waitcnt lgkmcnt(0)
	v_add_f32_e32 v66, v69, v84
	ds_bpermute_b32 v67, v163, v66
	v_cvt_pk_bf16_f32 v69, v72, v73
	v_cvt_pk_bf16_f32 v71, v78, v79
	global_store_dwordx4 v[82:83], v[74:77], off
	global_store_dwordx4 v[82:83], v[68:71], off offset:256
	s_and_saveexec_b64 s[8:9], s[38:39]
	s_cbranch_execz .LBB0_929
	s_waitcnt lgkmcnt(0)
	v_add_f32_e32 v66, v66, v67
	ds_write_b32 v160, v66 offset:768
; __device__ __forceinline__ unsigned pk(float lo, float hi) { f32x2v v = {lo, hi}; bf16x2v b = __builtin_convertvector(v, bf16x2v); return __builtin_bit_cast(unsigned, b); }
;     __device__ __forceinline__ void operator()(const f32x4 (&acc)[2][2][4][2], const Unit& u, int wr, int wc, int fr, int fq) const {
;     ...
;           for (int mp = 0; mp < 2; ++mp) { u32x4 xv[2][2];
; #pragma unroll
;             for (int mm = 0; mm < 2; ++mm)
; #pragma unroll
;                 for (int bj = 0; bj < 2; ++bj) xv[mm][bj] = *(const u32x4*)(xb + (size_t)(row0 + ai * HALF + (2 * mp + mm) * 16) * DMODEL + col0 + bj * HALF);
; #pragma unroll
;             for (int mm = 0; mm < 2; ++mm) { const int m = 2 * mp + mm, row = row0 + ai * HALF + m * 16; float ss = 0.f;
; #pragma unroll
;                 for (int bj = 0; bj < 2; ++bj) { const u32x4 xr = xv[mm][bj];
;                     const f32x4 x0 = {__uint_as_float(xr.x << 16), __uint_as_float(xr.x & 0xffff0000u), __uint_as_float(xr.y << 16), __uint_as_float(xr.y & 0xffff0000u)};
;                     const f32x4 x1 = {__uint_as_float(xr.z << 16), __uint_as_float(xr.z & 0xffff0000u), __uint_as_float(xr.w << 16), __uint_as_float(xr.w & 0xffff0000u)};
;                     const f32x4 y0 = x0 + acc[ai][bj][m][0] * alpha, y1 = x1 + acc[ai][bj][m][1] * alpha;
;                     u32x4 w; w.x = pk(y0[0], y0[1]); w.y = pk(y0[2], y0[3]); w.z = pk(y1[0], y1[1]); w.w = pk(y1[2], y1[3]);
;                     *(u32x4*)(xb + (size_t)row * DMODEL + col0 + bj * HALF) = w;
;                     ss += ((y0[0] * y0[0] + y0[1] * y0[1]) + (y0[2] * y0[2] + y0[3] * y0[3])) + ((y1[0] * y1[0] + y1[1] * y1[1]) + (y1[2] * y1[2] + y1[3] * y1[3])); }
;                 ss += __shfl_xor(ss, 16); ss += __shfl_xor(ss, 32);
;                 if (fq == 0) red[(ai * HALF + wr * 64 + m * 16 + fr) * 4 + wc] = ss; }
.LBB0_929:
	s_or_b64 exec, exec, s[8:9]
	s_waitcnt lgkmcnt(0)
	v_lshlrev_b64 v[66:67], 11, v[150:151]
	s_mov_b64 s[8:9], 0x40000
	v_lshl_add_u64 v[84:85], v[66:67], 0, s[8:9]
	v_lshl_add_u64 v[68:69], v[152:153], 0, v[84:85]
	s_mov_b64 s[8:9], 0x48000
	v_lshl_add_u64 v[74:75], v[66:67], 0, s[8:9]
	v_lshl_add_u64 v[66:67], v[152:153], 0, v[74:75]
	s_nop 0
	v_lshl_add_u64 v[84:85], s[10:11], 0, v[84:85]
	v_lshl_add_u64 v[84:85], v[148:149], 1, v[84:85]
	s_waitcnt vmcnt(12)
	v_mov_b32_e32 v76, v208
	v_mov_b32_e32 v77, v209
	v_mov_b32_e32 v78, v210
	v_mov_b32_e32 v79, v211
	v_mov_b32_e32 v80, v212
	v_mov_b32_e32 v81, v213
	v_mov_b32_e32 v82, v214
	v_mov_b32_e32 v83, v215
	v_mov_b32_e32 v70, v216
	v_mov_b32_e32 v71, v217
	v_mov_b32_e32 v72, v218
	v_mov_b32_e32 v73, v219
	v_mov_b32_e32 v66, v220
	v_mov_b32_e32 v67, v221
	v_mov_b32_e32 v68, v222
	v_mov_b32_e32 v69, v223
	v_lshlrev_b32_e32 v86, 16, v76
	v_and_b32_e32 v87, 0xffff0000, v76
	v_lshlrev_b32_e32 v76, 16, v77
	v_and_b32_e32 v77, 0xffff0000, v77
	v_lshlrev_b32_e32 v88, 16, v78
	v_and_b32_e32 v89, 0xffff0000, v78
	v_lshlrev_b32_e32 v78, 16, v79
	v_and_b32_e32 v79, 0xffff0000, v79
	v_pk_add_f32 v[64:65], v[64:65], v[76:77]
	v_pk_add_f32 v[62:63], v[62:63], v[86:87]
	v_pk_add_f32 v[76:77], v[60:61], v[78:79]
	v_pk_add_f32 v[78:79], v[58:59], v[88:89]
	v_cvt_pk_bf16_f32 v58, v62, v63
	v_cvt_pk_bf16_f32 v59, v64, v65
	v_cvt_pk_bf16_f32 v60, v78, v79
	v_cvt_pk_bf16_f32 v61, v76, v77
	global_store_dwordx4 v[84:85], v[58:61], off
	s_nop 1
	v_mul_f32_e32 v58, v63, v63
	v_mul_f32_e32 v59, v65, v65
	v_fmac_f32_e32 v58, v62, v62
	v_fmac_f32_e32 v59, v64, v64
	v_add_f32_e32 v58, v58, v59
	v_mul_f32_e32 v59, v79, v79
	v_mul_f32_e32 v60, v77, v77
	v_fmac_f32_e32 v59, v78, v78
	v_fmac_f32_e32 v60, v76, v76
	v_add_f32_e32 v59, v59, v60
	v_add_f32_e32 v76, v58, v59
	v_lshlrev_b32_e32 v58, 16, v80
	v_and_b32_e32 v59, 0xffff0000, v80
	v_lshlrev_b32_e32 v60, 16, v81
	v_and_b32_e32 v61, 0xffff0000, v81
	v_lshlrev_b32_e32 v62, 16, v82
	v_and_b32_e32 v63, 0xffff0000, v82
	v_lshlrev_b32_e32 v64, 16, v83
	v_and_b32_e32 v65, 0xffff0000, v83
	v_pk_add_f32 v[56:57], v[56:57], v[60:61]
	v_pk_add_f32 v[54:55], v[54:55], v[58:59]
	v_pk_add_f32 v[58:59], v[52:53], v[64:65]
	v_pk_add_f32 v[60:61], v[50:51], v[62:63]
	v_cvt_pk_bf16_f32 v50, v54, v55
	v_cvt_pk_bf16_f32 v51, v56, v57
	v_cvt_pk_bf16_f32 v52, v60, v61
	v_cvt_pk_bf16_f32 v53, v58, v59
	global_store_dwordx4 v[84:85], v[50:53], off offset:256
	s_nop 1
	v_mul_f32_e32 v50, v55, v55
	v_mul_f32_e32 v51, v57, v57
	v_fmac_f32_e32 v50, v54, v54
	v_fmac_f32_e32 v51, v56, v56
	v_add_f32_e32 v50, v50, v51
	v_mul_f32_e32 v51, v61, v61
	v_mul_f32_e32 v52, v59, v59
	v_fmac_f32_e32 v51, v60, v60
	v_fmac_f32_e32 v52, v58, v58
	v_add_f32_e32 v51, v51, v52
	v_add_f32_e32 v50, v50, v51
	v_add_f32_e32 v50, v76, v50
	ds_bpermute_b32 v51, v164, v50
	s_waitcnt lgkmcnt(0)
	v_add_f32_e32 v50, v50, v51
	ds_bpermute_b32 v51, v163, v50
	s_and_saveexec_b64 s[8:9], s[38:39]
	s_cbranch_execz .LBB0_931
	s_waitcnt lgkmcnt(0)
	v_add_f32_e32 v50, v50, v51
	ds_write_b32 v160, v50 offset:2048
.LBB0_931:
	s_or_b64 exec, exec, s[8:9]
	v_lshlrev_b32_e32 v50, 16, v70
	s_waitcnt lgkmcnt(0)
	v_and_b32_e32 v51, 0xffff0000, v70
	v_lshlrev_b32_e32 v52, 16, v71
	v_and_b32_e32 v53, 0xffff0000, v71
	v_lshlrev_b32_e32 v54, 16, v72
	v_and_b32_e32 v55, 0xffff0000, v72
	v_pk_add_f32 v[46:47], v[46:47], v[50:51]
	v_pk_add_f32 v[48:49], v[48:49], v[52:53]
	v_pk_add_f32 v[52:53], v[42:43], v[54:55]
	v_cvt_pk_bf16_f32 v42, v46, v47
	v_mul_f32_e32 v47, v47, v47
	v_lshlrev_b32_e32 v56, 16, v73
	v_and_b32_e32 v57, 0xffff0000, v73
	v_fmac_f32_e32 v47, v46, v46
	v_mul_f32_e32 v46, v49, v49
	v_pk_add_f32 v[50:51], v[44:45], v[56:57]
	v_fmac_f32_e32 v46, v48, v48
	v_cvt_pk_bf16_f32 v43, v48, v49
	v_add_f32_e32 v46, v47, v46
	v_mul_f32_e32 v47, v53, v53
	v_mul_f32_e32 v48, v51, v51
	v_fmac_f32_e32 v47, v52, v52
	v_fmac_f32_e32 v48, v50, v50
	v_add_f32_e32 v47, v47, v48
	v_add_f32_e32 v54, v46, v47
	v_lshlrev_b32_e32 v46, 16, v66
	v_and_b32_e32 v47, 0xffff0000, v66
	v_lshlrev_b32_e32 v48, 16, v67
	v_and_b32_e32 v49, 0xffff0000, v67
	v_cvt_pk_bf16_f32 v45, v50, v51
	v_lshlrev_b32_e32 v50, 16, v68
	v_and_b32_e32 v51, 0xffff0000, v68
	v_pk_add_f32 v[40:41], v[40:41], v[48:49]
	v_pk_add_f32 v[38:39], v[38:39], v[46:47]
	v_cvt_pk_bf16_f32 v44, v52, v53
	v_lshlrev_b32_e32 v52, 16, v69
	v_and_b32_e32 v53, 0xffff0000, v69
	v_pk_add_f32 v[48:49], v[34:35], v[50:51]
	v_mul_f32_e32 v34, v39, v39
	v_mul_f32_e32 v35, v41, v41
	v_pk_add_f32 v[46:47], v[36:37], v[52:53]
	v_fmac_f32_e32 v34, v38, v38
	v_fmac_f32_e32 v35, v40, v40
	v_add_f32_e32 v34, v34, v35
	v_mul_f32_e32 v35, v49, v49
	v_mul_f32_e32 v36, v47, v47
	v_fmac_f32_e32 v35, v48, v48
	v_fmac_f32_e32 v36, v46, v46
	v_add_f32_e32 v35, v35, v36
	v_add_f32_e32 v34, v34, v35
	v_add_f32_e32 v37, v54, v34
	ds_bpermute_b32 v52, v164, v37
	v_lshl_add_u64 v[34:35], s[10:11], 0, v[74:75]
	v_lshl_add_u64 v[50:51], v[148:149], 1, v[34:35]
	v_cvt_pk_bf16_f32 v36, v38, v39
	v_cvt_pk_bf16_f32 v38, v48, v49
	s_waitcnt lgkmcnt(0)
	v_add_f32_e32 v34, v37, v52
	ds_bpermute_b32 v35, v163, v34
	v_cvt_pk_bf16_f32 v37, v40, v41
	v_cvt_pk_bf16_f32 v39, v46, v47
	global_store_dwordx4 v[50:51], v[42:45], off
	global_store_dwordx4 v[50:51], v[36:39], off offset:256
	s_and_saveexec_b64 s[8:9], s[38:39]
	s_cbranch_execz .LBB0_933
	s_waitcnt lgkmcnt(0)
	v_add_f32_e32 v34, v34, v35
	ds_write_b32 v160, v34 offset:2304
; __device__ __forceinline__ unsigned pk(float lo, float hi) { f32x2v v = {lo, hi}; bf16x2v b = __builtin_convertvector(v, bf16x2v); return __builtin_bit_cast(unsigned, b); }
;     __device__ __forceinline__ void operator()(const f32x4 (&acc)[2][2][4][2], const Unit& u, int wr, int wc, int fr, int fq) const {
;     ...
;           for (int mp = 0; mp < 2; ++mp) { u32x4 xv[2][2];
; #pragma unroll
;             for (int mm = 0; mm < 2; ++mm)
; #pragma unroll
;                 for (int bj = 0; bj < 2; ++bj) xv[mm][bj] = *(const u32x4*)(xb + (size_t)(row0 + ai * HALF + (2 * mp + mm) * 16) * DMODEL + col0 + bj * HALF);
; #pragma unroll
;             for (int mm = 0; mm < 2; ++mm) { const int m = 2 * mp + mm, row = row0 + ai * HALF + m * 16; float ss = 0.f;
; #pragma unroll
;                 for (int bj = 0; bj < 2; ++bj) { const u32x4 xr = xv[mm][bj];
;                     const f32x4 x0 = {__uint_as_float(xr.x << 16), __uint_as_float(xr.x & 0xffff0000u), __uint_as_float(xr.y << 16), __uint_as_float(xr.y & 0xffff0000u)};
;                     const f32x4 x1 = {__uint_as_float(xr.z << 16), __uint_as_float(xr.z & 0xffff0000u), __uint_as_float(xr.w << 16), __uint_as_float(xr.w & 0xffff0000u)};
;                     const f32x4 y0 = x0 + acc[ai][bj][m][0] * alpha, y1 = x1 + acc[ai][bj][m][1] * alpha;
;                     u32x4 w; w.x = pk(y0[0], y0[1]); w.y = pk(y0[2], y0[3]); w.z = pk(y1[0], y1[1]); w.w = pk(y1[2], y1[3]);
;                     *(u32x4*)(xb + (size_t)row * DMODEL + col0 + bj * HALF) = w;
;                     ss += ((y0[0] * y0[0] + y0[1] * y0[1]) + (y0[2] * y0[2] + y0[3] * y0[3])) + ((y1[0] * y1[0] + y1[1] * y1[1]) + (y1[2] * y1[2] + y1[3] * y1[3])); }
;                 ss += __shfl_xor(ss, 16); ss += __shfl_xor(ss, 32);
;                 if (fq == 0) red[(ai * HALF + wr * 64 + m * 16 + fr) * 4 + wc] = ss; }
.LBB0_933:
	s_or_b64 exec, exec, s[8:9]
	s_waitcnt lgkmcnt(0)
	v_lshlrev_b64 v[34:35], 11, v[150:151]
	s_mov_b64 s[8:9], 0x50000
	v_lshl_add_u64 v[52:53], v[34:35], 0, s[8:9]
	v_lshl_add_u64 v[36:37], v[152:153], 0, v[52:53]
	s_mov_b64 s[8:9], 0x58000
	v_lshl_add_u64 v[42:43], v[34:35], 0, s[8:9]
	v_lshl_add_u64 v[34:35], v[152:153], 0, v[42:43]
	s_nop 0
	v_lshl_add_u64 v[52:53], s[10:11], 0, v[52:53]
	v_lshl_add_u64 v[52:53], v[148:149], 1, v[52:53]
	s_waitcnt vmcnt(8)
	v_mov_b32_e32 v44, v166
	v_mov_b32_e32 v45, v167
	v_mov_b32_e32 v46, v168
	v_mov_b32_e32 v47, v169
	v_mov_b32_e32 v48, v170
	v_mov_b32_e32 v49, v171
	v_mov_b32_e32 v50, v172
	v_mov_b32_e32 v51, v173
	v_mov_b32_e32 v38, v178
	v_mov_b32_e32 v39, v179
	v_mov_b32_e32 v40, v180
	v_mov_b32_e32 v41, v181
	v_mov_b32_e32 v34, v134
	v_mov_b32_e32 v35, v135
	v_mov_b32_e32 v36, v136
	v_mov_b32_e32 v37, v137
	v_lshlrev_b32_e32 v54, 16, v44
	v_and_b32_e32 v55, 0xffff0000, v44
	v_lshlrev_b32_e32 v44, 16, v45
	v_and_b32_e32 v45, 0xffff0000, v45
	v_lshlrev_b32_e32 v56, 16, v46
	v_and_b32_e32 v57, 0xffff0000, v46
	v_lshlrev_b32_e32 v46, 16, v47
	v_and_b32_e32 v47, 0xffff0000, v47
	v_pk_add_f32 v[32:33], v[32:33], v[44:45]
	v_pk_add_f32 v[30:31], v[30:31], v[54:55]
	v_pk_add_f32 v[44:45], v[28:29], v[46:47]
	v_pk_add_f32 v[46:47], v[26:27], v[56:57]
	v_cvt_pk_bf16_f32 v26, v30, v31
	v_cvt_pk_bf16_f32 v27, v32, v33
	v_cvt_pk_bf16_f32 v28, v46, v47
	v_cvt_pk_bf16_f32 v29, v44, v45
	global_store_dwordx4 v[52:53], v[26:29], off
	s_nop 1
	v_mul_f32_e32 v26, v31, v31
	v_mul_f32_e32 v27, v33, v33
	v_fmac_f32_e32 v26, v30, v30
	v_fmac_f32_e32 v27, v32, v32
	v_add_f32_e32 v26, v26, v27
	v_mul_f32_e32 v27, v47, v47
	v_mul_f32_e32 v28, v45, v45
	v_fmac_f32_e32 v27, v46, v46
	v_fmac_f32_e32 v28, v44, v44
	v_add_f32_e32 v27, v27, v28
	v_add_f32_e32 v44, v26, v27
	v_lshlrev_b32_e32 v26, 16, v48
	v_and_b32_e32 v27, 0xffff0000, v48
	v_lshlrev_b32_e32 v28, 16, v49
	v_and_b32_e32 v29, 0xffff0000, v49
	v_lshlrev_b32_e32 v30, 16, v50
	v_and_b32_e32 v31, 0xffff0000, v50
	v_lshlrev_b32_e32 v32, 16, v51
	v_and_b32_e32 v33, 0xffff0000, v51
	v_pk_add_f32 v[24:25], v[24:25], v[28:29]
	v_pk_add_f32 v[22:23], v[22:23], v[26:27]
	v_pk_add_f32 v[26:27], v[20:21], v[32:33]
	v_pk_add_f32 v[28:29], v[18:19], v[30:31]
	v_cvt_pk_bf16_f32 v18, v22, v23
	v_cvt_pk_bf16_f32 v19, v24, v25
	v_cvt_pk_bf16_f32 v20, v28, v29
	v_cvt_pk_bf16_f32 v21, v26, v27
	global_store_dwordx4 v[52:53], v[18:21], off offset:256
	s_nop 1
	v_mul_f32_e32 v18, v23, v23
	v_mul_f32_e32 v19, v25, v25
	v_fmac_f32_e32 v18, v22, v22
	v_fmac_f32_e32 v19, v24, v24
	v_add_f32_e32 v18, v18, v19
	v_mul_f32_e32 v19, v29, v29
	v_mul_f32_e32 v20, v27, v27
	v_fmac_f32_e32 v19, v28, v28
	v_fmac_f32_e32 v20, v26, v26
	v_add_f32_e32 v19, v19, v20
	v_add_f32_e32 v18, v18, v19
	v_add_f32_e32 v18, v44, v18
	ds_bpermute_b32 v19, v164, v18
	s_waitcnt lgkmcnt(0)
	v_add_f32_e32 v18, v18, v19
	ds_bpermute_b32 v19, v163, v18
	s_and_saveexec_b64 s[8:9], s[38:39]
	s_cbranch_execz .LBB0_935
	s_waitcnt lgkmcnt(0)
	v_add_f32_e32 v18, v18, v19
	ds_write_b32 v160, v18 offset:2560
.LBB0_935:
	s_or_b64 exec, exec, s[8:9]
	v_lshlrev_b32_e32 v18, 16, v38
	s_waitcnt lgkmcnt(0)
	v_and_b32_e32 v19, 0xffff0000, v38
	v_lshlrev_b32_e32 v20, 16, v39
	v_and_b32_e32 v21, 0xffff0000, v39
	v_lshlrev_b32_e32 v22, 16, v40
	v_and_b32_e32 v23, 0xffff0000, v40
	v_pk_add_f32 v[14:15], v[14:15], v[18:19]
	v_pk_add_f32 v[16:17], v[16:17], v[20:21]
	v_pk_add_f32 v[20:21], v[10:11], v[22:23]
	v_cvt_pk_bf16_f32 v10, v14, v15
	v_mul_f32_e32 v15, v15, v15
	v_lshlrev_b32_e32 v24, 16, v41
	v_and_b32_e32 v25, 0xffff0000, v41
	v_fmac_f32_e32 v15, v14, v14
	v_mul_f32_e32 v14, v17, v17
	v_pk_add_f32 v[18:19], v[12:13], v[24:25]
	v_fmac_f32_e32 v14, v16, v16
	v_cvt_pk_bf16_f32 v11, v16, v17
	v_add_f32_e32 v14, v15, v14
	v_mul_f32_e32 v15, v21, v21
	v_mul_f32_e32 v16, v19, v19
	v_fmac_f32_e32 v15, v20, v20
	v_fmac_f32_e32 v16, v18, v18
	v_add_f32_e32 v15, v15, v16
	v_add_f32_e32 v22, v14, v15
	v_lshlrev_b32_e32 v14, 16, v34
	v_and_b32_e32 v15, 0xffff0000, v34
	v_lshlrev_b32_e32 v16, 16, v35
	v_and_b32_e32 v17, 0xffff0000, v35
	v_cvt_pk_bf16_f32 v13, v18, v19
	v_lshlrev_b32_e32 v18, 16, v36
	v_and_b32_e32 v19, 0xffff0000, v36
	v_pk_add_f32 v[8:9], v[8:9], v[16:17]
	v_pk_add_f32 v[6:7], v[6:7], v[14:15]
	v_cvt_pk_bf16_f32 v12, v20, v21
	v_lshlrev_b32_e32 v20, 16, v37
	v_and_b32_e32 v21, 0xffff0000, v37
	v_pk_add_f32 v[16:17], v[2:3], v[18:19]
	v_mul_f32_e32 v2, v7, v7
	v_mul_f32_e32 v3, v9, v9
	v_pk_add_f32 v[14:15], v[4:5], v[20:21]
	v_fmac_f32_e32 v2, v6, v6
	v_fmac_f32_e32 v3, v8, v8
	v_add_f32_e32 v2, v2, v3
	v_mul_f32_e32 v3, v17, v17
	v_mul_f32_e32 v4, v15, v15
	v_fmac_f32_e32 v3, v16, v16
	v_fmac_f32_e32 v4, v14, v14
	v_add_f32_e32 v3, v3, v4
	v_add_f32_e32 v2, v2, v3
	v_add_f32_e32 v5, v22, v2
	ds_bpermute_b32 v20, v164, v5
	v_lshl_add_u64 v[2:3], s[10:11], 0, v[42:43]
	v_lshl_add_u64 v[18:19], v[148:149], 1, v[2:3]
	v_cvt_pk_bf16_f32 v4, v6, v7
	v_cvt_pk_bf16_f32 v6, v16, v17
	s_waitcnt lgkmcnt(0)
	v_add_f32_e32 v2, v5, v20
	ds_bpermute_b32 v3, v163, v2
	v_cvt_pk_bf16_f32 v5, v8, v9
	v_cvt_pk_bf16_f32 v7, v14, v15
	global_store_dwordx4 v[18:19], v[10:13], off
	global_store_dwordx4 v[18:19], v[4:7], off offset:256
	s_and_saveexec_b64 s[8:9], s[38:39]
	s_cbranch_execz .LBB0_937
	s_waitcnt lgkmcnt(0)
	v_add_f32_e32 v2, v2, v3
	ds_write_b32 v160, v2 offset:2816
